# v7 + tail_gemm K loops rewritten (all 8 instances): software-pipelined global loads with counted vmcnt instead of serialized vmcnt(0) round trips
# speedup vs baseline: 1.0056x; 1.0006x over previous
.LBB0_122:
	v_add_co_u32_e32 v82, vcc, s84, v66
	s_nop 1
	v_addc_co_u32_e32 v83, vcc, 0, v67, vcc
	v_add_co_u32_e32 v130, vcc, s85, v66
	s_nop 1
	v_addc_co_u32_e32 v131, vcc, 0, v67, vcc
	v_add_co_u32_e32 v172, vcc, s88, v66
	s_nop 1
	v_addc_co_u32_e32 v173, vcc, 0, v67, vcc
	v_add_co_u32_e32 v174, vcc, s89, v66
	s_nop 1
	v_addc_co_u32_e32 v175, vcc, 0, v67, vcc
	v_add_co_u32_e32 v176, vcc, 0x5808000, v64
	s_nop 1
	v_addc_co_u32_e32 v177, vcc, 0, v65, vcc
	v_add_co_u32_e32 v178, vcc, 0x5818000, v64
	s_nop 1
	v_addc_co_u32_e32 v179, vcc, 0, v65, vcc
	v_add_co_u32_e32 v180, vcc, 0x5888000, v64
	s_nop 1
	v_addc_co_u32_e32 v181, vcc, 0, v65, vcc
	v_add_co_u32_e32 v182, vcc, 0x5898000, v64
	s_nop 1
	v_addc_co_u32_e32 v183, vcc, 0, v65, vcc
	global_load_dwordx4 v[68:71], v[82:83], off
	global_load_dwordx4 v[72:75], v[130:131], off
	global_load_dwordx4 v[76:79], v[172:173], off
	global_load_dwordx4 v[84:87], v[174:175], off
	global_load_dwordx4 v[88:91], v[176:177], off
	global_load_dwordx4 v[92:95], v[178:179], off
	global_load_dwordx4 v[96:99], v[180:181], off
	global_load_dwordx4 v[100:103], v[182:183], off
	global_load_dwordx4 v[104:107], v[82:83], off offset:64
	global_load_dwordx4 v[108:111], v[130:131], off offset:64
	global_load_dwordx4 v[112:115], v[172:173], off offset:64
	global_load_dwordx4 v[116:119], v[174:175], off offset:64
	global_load_dwordx4 v[120:123], v[176:177], off offset:64
	global_load_dwordx4 v[124:127], v[178:179], off offset:64
	global_load_dwordx4 v[132:135], v[180:181], off offset:64
	global_load_dwordx4 v[136:139], v[182:183], off offset:64
	global_load_dwordx4 v[140:143], v[82:83], off offset:128
	global_load_dwordx4 v[144:147], v[130:131], off offset:128
	global_load_dwordx4 v[148:151], v[172:173], off offset:128
	global_load_dwordx4 v[152:155], v[174:175], off offset:128
	global_load_dwordx4 v[156:159], v[176:177], off offset:128
	global_load_dwordx4 v[160:163], v[178:179], off offset:128
	global_load_dwordx4 v[164:167], v[180:181], off offset:128
	global_load_dwordx4 v[168:171], v[182:183], off offset:128
	s_waitcnt vmcnt(16)
	v_mfma_f32_16x16x32_bf16 v[56:59], v[88:91], v[68:71], 0
	v_mfma_f32_16x16x32_bf16 v[52:55], v[88:91], v[72:75], 0
	v_mfma_f32_16x16x32_bf16 v[48:51], v[88:91], v[76:79], 0
	v_mfma_f32_16x16x32_bf16 v[44:47], v[88:91], v[84:87], 0
	v_mfma_f32_16x16x32_bf16 v[12:15], v[92:95], v[68:71], 0
	v_mfma_f32_16x16x32_bf16 v[8:11], v[92:95], v[72:75], 0
	v_mfma_f32_16x16x32_bf16 v[4:7], v[92:95], v[76:79], 0
	v_mfma_f32_16x16x32_bf16 v[0:3], v[92:95], v[84:87], 0
	v_mfma_f32_16x16x32_bf16 v[16:19], v[96:99], v[68:71], 0
	v_mfma_f32_16x16x32_bf16 v[24:27], v[96:99], v[72:75], 0
	v_mfma_f32_16x16x32_bf16 v[28:31], v[96:99], v[76:79], 0
	v_mfma_f32_16x16x32_bf16 v[36:39], v[96:99], v[84:87], 0
	v_mfma_f32_16x16x32_bf16 v[20:23], v[100:103], v[68:71], 0
	v_mfma_f32_16x16x32_bf16 v[32:35], v[100:103], v[72:75], 0
	v_mfma_f32_16x16x32_bf16 v[40:43], v[100:103], v[76:79], 0
	v_mfma_f32_16x16x32_bf16 v[60:63], v[100:103], v[84:87], 0
	global_load_dwordx4 v[68:71], v[82:83], off offset:192
	global_load_dwordx4 v[72:75], v[130:131], off offset:192
	global_load_dwordx4 v[76:79], v[172:173], off offset:192
	global_load_dwordx4 v[84:87], v[174:175], off offset:192
	global_load_dwordx4 v[88:91], v[176:177], off offset:192
	global_load_dwordx4 v[92:95], v[178:179], off offset:192
	global_load_dwordx4 v[96:99], v[180:181], off offset:192
	global_load_dwordx4 v[100:103], v[182:183], off offset:192
	s_waitcnt vmcnt(16)
	v_mfma_f32_16x16x32_bf16 v[56:59], v[120:123], v[104:107], v[56:59]
	v_mfma_f32_16x16x32_bf16 v[52:55], v[120:123], v[108:111], v[52:55]
	v_mfma_f32_16x16x32_bf16 v[48:51], v[120:123], v[112:115], v[48:51]
	v_mfma_f32_16x16x32_bf16 v[44:47], v[120:123], v[116:119], v[44:47]
	v_mfma_f32_16x16x32_bf16 v[12:15], v[124:127], v[104:107], v[12:15]
	v_mfma_f32_16x16x32_bf16 v[8:11], v[124:127], v[108:111], v[8:11]
	v_mfma_f32_16x16x32_bf16 v[4:7], v[124:127], v[112:115], v[4:7]
	v_mfma_f32_16x16x32_bf16 v[0:3], v[124:127], v[116:119], v[0:3]
	v_mfma_f32_16x16x32_bf16 v[16:19], v[132:135], v[104:107], v[16:19]
	v_mfma_f32_16x16x32_bf16 v[24:27], v[132:135], v[108:111], v[24:27]
	v_mfma_f32_16x16x32_bf16 v[28:31], v[132:135], v[112:115], v[28:31]
	v_mfma_f32_16x16x32_bf16 v[36:39], v[132:135], v[116:119], v[36:39]
	v_mfma_f32_16x16x32_bf16 v[20:23], v[136:139], v[104:107], v[20:23]
	v_mfma_f32_16x16x32_bf16 v[32:35], v[136:139], v[108:111], v[32:35]
	v_mfma_f32_16x16x32_bf16 v[40:43], v[136:139], v[112:115], v[40:43]
	v_mfma_f32_16x16x32_bf16 v[60:63], v[136:139], v[116:119], v[60:63]
	global_load_dwordx4 v[104:107], v[82:83], off offset:256
	global_load_dwordx4 v[108:111], v[130:131], off offset:256
	global_load_dwordx4 v[112:115], v[172:173], off offset:256
	global_load_dwordx4 v[116:119], v[174:175], off offset:256
	global_load_dwordx4 v[120:123], v[176:177], off offset:256
	global_load_dwordx4 v[124:127], v[178:179], off offset:256
	global_load_dwordx4 v[132:135], v[180:181], off offset:256
	global_load_dwordx4 v[136:139], v[182:183], off offset:256
	s_waitcnt vmcnt(16)
	v_mfma_f32_16x16x32_bf16 v[56:59], v[156:159], v[140:143], v[56:59]
	v_mfma_f32_16x16x32_bf16 v[52:55], v[156:159], v[144:147], v[52:55]
	v_mfma_f32_16x16x32_bf16 v[48:51], v[156:159], v[148:151], v[48:51]
	v_mfma_f32_16x16x32_bf16 v[44:47], v[156:159], v[152:155], v[44:47]
	v_mfma_f32_16x16x32_bf16 v[12:15], v[160:163], v[140:143], v[12:15]
	v_mfma_f32_16x16x32_bf16 v[8:11], v[160:163], v[144:147], v[8:11]
	v_mfma_f32_16x16x32_bf16 v[4:7], v[160:163], v[148:151], v[4:7]
	v_mfma_f32_16x16x32_bf16 v[0:3], v[160:163], v[152:155], v[0:3]
	v_mfma_f32_16x16x32_bf16 v[16:19], v[164:167], v[140:143], v[16:19]
	v_mfma_f32_16x16x32_bf16 v[24:27], v[164:167], v[144:147], v[24:27]
	v_mfma_f32_16x16x32_bf16 v[28:31], v[164:167], v[148:151], v[28:31]
	v_mfma_f32_16x16x32_bf16 v[36:39], v[164:167], v[152:155], v[36:39]
	v_mfma_f32_16x16x32_bf16 v[20:23], v[168:171], v[140:143], v[20:23]
	v_mfma_f32_16x16x32_bf16 v[32:35], v[168:171], v[144:147], v[32:35]
	v_mfma_f32_16x16x32_bf16 v[40:43], v[168:171], v[148:151], v[40:43]
	v_mfma_f32_16x16x32_bf16 v[60:63], v[168:171], v[152:155], v[60:63]
	global_load_dwordx4 v[140:143], v[82:83], off offset:320
	global_load_dwordx4 v[144:147], v[130:131], off offset:320
	global_load_dwordx4 v[148:151], v[172:173], off offset:320
	global_load_dwordx4 v[152:155], v[174:175], off offset:320
	global_load_dwordx4 v[156:159], v[176:177], off offset:320
	global_load_dwordx4 v[160:163], v[178:179], off offset:320
	global_load_dwordx4 v[164:167], v[180:181], off offset:320
	global_load_dwordx4 v[168:171], v[182:183], off offset:320
	s_waitcnt vmcnt(16)
	v_mfma_f32_16x16x32_bf16 v[56:59], v[88:91], v[68:71], v[56:59]
	v_mfma_f32_16x16x32_bf16 v[52:55], v[88:91], v[72:75], v[52:55]
	v_mfma_f32_16x16x32_bf16 v[48:51], v[88:91], v[76:79], v[48:51]
	v_mfma_f32_16x16x32_bf16 v[44:47], v[88:91], v[84:87], v[44:47]
	v_mfma_f32_16x16x32_bf16 v[12:15], v[92:95], v[68:71], v[12:15]
	v_mfma_f32_16x16x32_bf16 v[8:11], v[92:95], v[72:75], v[8:11]
	v_mfma_f32_16x16x32_bf16 v[4:7], v[92:95], v[76:79], v[4:7]
	v_mfma_f32_16x16x32_bf16 v[0:3], v[92:95], v[84:87], v[0:3]
	v_mfma_f32_16x16x32_bf16 v[16:19], v[96:99], v[68:71], v[16:19]
	v_mfma_f32_16x16x32_bf16 v[24:27], v[96:99], v[72:75], v[24:27]
	v_mfma_f32_16x16x32_bf16 v[28:31], v[96:99], v[76:79], v[28:31]
	v_mfma_f32_16x16x32_bf16 v[36:39], v[96:99], v[84:87], v[36:39]
	v_mfma_f32_16x16x32_bf16 v[20:23], v[100:103], v[68:71], v[20:23]
	v_mfma_f32_16x16x32_bf16 v[32:35], v[100:103], v[72:75], v[32:35]
	v_mfma_f32_16x16x32_bf16 v[40:43], v[100:103], v[76:79], v[40:43]
	v_mfma_f32_16x16x32_bf16 v[60:63], v[100:103], v[84:87], v[60:63]
	global_load_dwordx4 v[68:71], v[82:83], off offset:384
	global_load_dwordx4 v[72:75], v[130:131], off offset:384
	global_load_dwordx4 v[76:79], v[172:173], off offset:384
	global_load_dwordx4 v[84:87], v[174:175], off offset:384
	global_load_dwordx4 v[88:91], v[176:177], off offset:384
	global_load_dwordx4 v[92:95], v[178:179], off offset:384
	global_load_dwordx4 v[96:99], v[180:181], off offset:384
	global_load_dwordx4 v[100:103], v[182:183], off offset:384
	s_waitcnt vmcnt(16)
	v_mfma_f32_16x16x32_bf16 v[56:59], v[120:123], v[104:107], v[56:59]
	v_mfma_f32_16x16x32_bf16 v[52:55], v[120:123], v[108:111], v[52:55]
	v_mfma_f32_16x16x32_bf16 v[48:51], v[120:123], v[112:115], v[48:51]
	v_mfma_f32_16x16x32_bf16 v[44:47], v[120:123], v[116:119], v[44:47]
	v_mfma_f32_16x16x32_bf16 v[12:15], v[124:127], v[104:107], v[12:15]
	v_mfma_f32_16x16x32_bf16 v[8:11], v[124:127], v[108:111], v[8:11]
	v_mfma_f32_16x16x32_bf16 v[4:7], v[124:127], v[112:115], v[4:7]
	v_mfma_f32_16x16x32_bf16 v[0:3], v[124:127], v[116:119], v[0:3]
	v_mfma_f32_16x16x32_bf16 v[16:19], v[132:135], v[104:107], v[16:19]
	v_mfma_f32_16x16x32_bf16 v[24:27], v[132:135], v[108:111], v[24:27]
	v_mfma_f32_16x16x32_bf16 v[28:31], v[132:135], v[112:115], v[28:31]
	v_mfma_f32_16x16x32_bf16 v[36:39], v[132:135], v[116:119], v[36:39]
	v_mfma_f32_16x16x32_bf16 v[20:23], v[136:139], v[104:107], v[20:23]
	v_mfma_f32_16x16x32_bf16 v[32:35], v[136:139], v[108:111], v[32:35]
	v_mfma_f32_16x16x32_bf16 v[40:43], v[136:139], v[112:115], v[40:43]
	v_mfma_f32_16x16x32_bf16 v[60:63], v[136:139], v[116:119], v[60:63]
	global_load_dwordx4 v[104:107], v[82:83], off offset:448
	global_load_dwordx4 v[108:111], v[130:131], off offset:448
	global_load_dwordx4 v[112:115], v[172:173], off offset:448
	global_load_dwordx4 v[116:119], v[174:175], off offset:448
	global_load_dwordx4 v[120:123], v[176:177], off offset:448
	global_load_dwordx4 v[124:127], v[178:179], off offset:448
	global_load_dwordx4 v[132:135], v[180:181], off offset:448
	global_load_dwordx4 v[136:139], v[182:183], off offset:448
	s_waitcnt vmcnt(16)
	v_mfma_f32_16x16x32_bf16 v[56:59], v[156:159], v[140:143], v[56:59]
	v_mfma_f32_16x16x32_bf16 v[52:55], v[156:159], v[144:147], v[52:55]
	v_mfma_f32_16x16x32_bf16 v[48:51], v[156:159], v[148:151], v[48:51]
	v_mfma_f32_16x16x32_bf16 v[44:47], v[156:159], v[152:155], v[44:47]
	v_mfma_f32_16x16x32_bf16 v[12:15], v[160:163], v[140:143], v[12:15]
	v_mfma_f32_16x16x32_bf16 v[8:11], v[160:163], v[144:147], v[8:11]
	v_mfma_f32_16x16x32_bf16 v[4:7], v[160:163], v[148:151], v[4:7]
	v_mfma_f32_16x16x32_bf16 v[0:3], v[160:163], v[152:155], v[0:3]
	v_mfma_f32_16x16x32_bf16 v[16:19], v[164:167], v[140:143], v[16:19]
	v_mfma_f32_16x16x32_bf16 v[24:27], v[164:167], v[144:147], v[24:27]
	v_mfma_f32_16x16x32_bf16 v[28:31], v[164:167], v[148:151], v[28:31]
	v_mfma_f32_16x16x32_bf16 v[36:39], v[164:167], v[152:155], v[36:39]
	v_mfma_f32_16x16x32_bf16 v[20:23], v[168:171], v[140:143], v[20:23]
	v_mfma_f32_16x16x32_bf16 v[32:35], v[168:171], v[144:147], v[32:35]
	v_mfma_f32_16x16x32_bf16 v[40:43], v[168:171], v[148:151], v[40:43]
	v_mfma_f32_16x16x32_bf16 v[60:63], v[168:171], v[152:155], v[60:63]
	s_waitcnt vmcnt(8)
	v_mfma_f32_16x16x32_bf16 v[56:59], v[88:91], v[68:71], v[56:59]
	v_mfma_f32_16x16x32_bf16 v[52:55], v[88:91], v[72:75], v[52:55]
	v_mfma_f32_16x16x32_bf16 v[48:51], v[88:91], v[76:79], v[48:51]
	v_mfma_f32_16x16x32_bf16 v[44:47], v[88:91], v[84:87], v[44:47]
	v_mfma_f32_16x16x32_bf16 v[12:15], v[92:95], v[68:71], v[12:15]
	v_mfma_f32_16x16x32_bf16 v[8:11], v[92:95], v[72:75], v[8:11]
	v_mfma_f32_16x16x32_bf16 v[4:7], v[92:95], v[76:79], v[4:7]
	v_mfma_f32_16x16x32_bf16 v[0:3], v[92:95], v[84:87], v[0:3]
	v_mfma_f32_16x16x32_bf16 v[16:19], v[96:99], v[68:71], v[16:19]
	v_mfma_f32_16x16x32_bf16 v[24:27], v[96:99], v[72:75], v[24:27]
	v_mfma_f32_16x16x32_bf16 v[28:31], v[96:99], v[76:79], v[28:31]
	v_mfma_f32_16x16x32_bf16 v[36:39], v[96:99], v[84:87], v[36:39]
	v_mfma_f32_16x16x32_bf16 v[20:23], v[100:103], v[68:71], v[20:23]
	v_mfma_f32_16x16x32_bf16 v[32:35], v[100:103], v[72:75], v[32:35]
	v_mfma_f32_16x16x32_bf16 v[40:43], v[100:103], v[76:79], v[40:43]
	v_mfma_f32_16x16x32_bf16 v[60:63], v[100:103], v[84:87], v[60:63]
	s_waitcnt vmcnt(0)
	v_mfma_f32_16x16x32_bf16 v[56:59], v[120:123], v[104:107], v[56:59]
	v_mfma_f32_16x16x32_bf16 v[52:55], v[120:123], v[108:111], v[52:55]
	v_mfma_f32_16x16x32_bf16 v[48:51], v[120:123], v[112:115], v[48:51]
	v_mfma_f32_16x16x32_bf16 v[44:47], v[120:123], v[116:119], v[44:47]
	v_mfma_f32_16x16x32_bf16 v[12:15], v[124:127], v[104:107], v[12:15]
	v_mfma_f32_16x16x32_bf16 v[8:11], v[124:127], v[108:111], v[8:11]
	v_mfma_f32_16x16x32_bf16 v[4:7], v[124:127], v[112:115], v[4:7]
	v_mfma_f32_16x16x32_bf16 v[0:3], v[124:127], v[116:119], v[0:3]
	v_mfma_f32_16x16x32_bf16 v[16:19], v[132:135], v[104:107], v[16:19]
	v_mfma_f32_16x16x32_bf16 v[24:27], v[132:135], v[108:111], v[24:27]
	v_mfma_f32_16x16x32_bf16 v[28:31], v[132:135], v[112:115], v[28:31]
	v_mfma_f32_16x16x32_bf16 v[36:39], v[132:135], v[116:119], v[36:39]
	v_mfma_f32_16x16x32_bf16 v[20:23], v[136:139], v[104:107], v[20:23]
	v_mfma_f32_16x16x32_bf16 v[32:35], v[136:139], v[108:111], v[32:35]
	v_mfma_f32_16x16x32_bf16 v[40:43], v[136:139], v[112:115], v[40:43]
	v_mfma_f32_16x16x32_bf16 v[60:63], v[136:139], v[116:119], v[60:63]
	s_nop 7
	s_nop 3
	v_and_b32_e32 v65, 63, v81
	s_ashr_i32 s2, s4, 7
	v_lshl_add_u32 v65, v65, 4, 0
	s_lshl_b32 s3, s2, 4
	v_lshl_add_u32 v66, s5, 14, v65
	s_addk_i32 s3, 0x4000
	ds_write_b128 v66, v[56:59]
	ds_write_b128 v66, v[52:55] offset:1024
	ds_write_b128 v66, v[48:51] offset:2048
	ds_write_b128 v66, v[44:47] offset:3072
	ds_write_b128 v66, v[12:15] offset:4096
	ds_write_b128 v66, v[8:11] offset:5120
	ds_write_b128 v66, v[4:7] offset:6144
	ds_write_b128 v66, v[0:3] offset:7168
	ds_write_b128 v66, v[16:19] offset:8192
	ds_write_b128 v66, v[24:27] offset:9216
	ds_write_b128 v66, v[28:31] offset:10240
	ds_write_b128 v66, v[36:39] offset:11264
	ds_write_b128 v66, v[20:23] offset:12288
	ds_write_b128 v66, v[32:35] offset:13312
	ds_write_b128 v66, v[40:43] offset:14336
	ds_write_b128 v66, v[60:63] offset:15360
	v_or_b32_e32 v0, s3, v80
	v_ashrrev_i32_e32 v1, 31, v0
	v_bfe_u32 v64, v81, 4, 2
	v_lshlrev_b64 v[2:3], 7, v[0:1]
	v_lshl_add_u64 v[2:3], s[8:9], 0, v[2:3]
	v_lshlrev_b32_e32 v128, 5, v64
	v_lshl_add_u64 v[6:7], v[2:3], 0, v[128:129]
	s_waitcnt lgkmcnt(0)
	s_barrier
	global_load_dwordx4 v[2:5], v[6:7], off
	s_nop 0
	global_load_dwordx4 v[6:9], v[6:7], off offset:16
	s_bfe_u32 s3, s4, 0x10006
	s_lshl_b32 s4, s3, 2
	s_add_i32 s4, s4, s2
	v_lshl_add_u32 v62, s4, 10, v65
	ds_read_b128 v[10:13], v62
	ds_read_b128 v[14:17], v62 offset:8192
	ds_read_b128 v[18:21], v62 offset:16384
	ds_read_b128 v[22:25], v62 offset:24576
	ds_read_b128 v[26:29], v62 offset:32768
	ds_read_b128 v[30:33], v62 offset:40960
	ds_read_b128 v[34:37], v62 offset:49152
	ds_read_b128 v[38:41], v62 offset:57344
	s_waitcnt lgkmcnt(0)
	v_pk_add_f32 v[10:11], v[10:11], 0 op_sel_hi:[1,0]
	v_pk_add_f32 v[12:13], v[12:13], 0 op_sel_hi:[1,0]
	v_pk_add_f32 v[10:11], v[10:11], v[18:19]
	v_pk_add_f32 v[12:13], v[12:13], v[20:21]
	v_add_u32_e32 v42, 0x10000, v62
	v_add_u32_e32 v46, 0x12000, v62
	v_add_u32_e32 v50, 0x14000, v62
	v_add_u32_e32 v54, 0x16000, v62
	v_add_u32_e32 v58, 0x18000, v62
	v_add_u32_e32 v63, 0x1a000, v62
	ds_read_b128 v[42:45], v42
	ds_read_b128 v[46:49], v46
	ds_read_b128 v[50:53], v50
	ds_read_b128 v[54:57], v54
	ds_read_b128 v[58:61], v58
	ds_read_b128 v[66:69], v63
	v_pk_add_f32 v[10:11], v[10:11], v[26:27]
	v_pk_add_f32 v[14:15], v[14:15], 0 op_sel_hi:[1,0]
	v_pk_add_f32 v[10:11], v[10:11], v[34:35]
	v_pk_add_f32 v[12:13], v[12:13], v[28:29]
	s_waitcnt lgkmcnt(0)
	v_pk_add_f32 v[10:11], v[10:11], v[42:43]
	v_pk_add_f32 v[16:17], v[16:17], 0 op_sel_hi:[1,0]
	v_pk_add_f32 v[10:11], v[10:11], v[50:51]
	v_pk_add_f32 v[14:15], v[14:15], v[22:23]
	v_pk_add_f32 v[10:11], v[10:11], v[58:59]
	v_pk_add_f32 v[12:13], v[12:13], v[36:37]
	v_pk_add_f32 v[16:17], v[16:17], v[24:25]
	v_pk_add_f32 v[14:15], v[14:15], v[30:31]
	v_pk_add_f32 v[12:13], v[12:13], v[44:45]
	v_pk_add_f32 v[16:17], v[16:17], v[32:33]
	v_pk_add_f32 v[14:15], v[14:15], v[38:39]
	v_pk_add_f32 v[12:13], v[12:13], v[52:53]
	v_pk_add_f32 v[16:17], v[16:17], v[40:41]
	v_pk_add_f32 v[14:15], v[14:15], v[46:47]
	v_pk_add_f32 v[12:13], v[12:13], v[60:61]
	v_pk_add_f32 v[16:17], v[16:17], v[48:49]
	v_pk_add_f32 v[14:15], v[14:15], v[54:55]
	v_lshlrev_b64 v[0:1], 12, v[0:1]
	s_and_b32 s0, s0, 0x700
	v_pk_add_f32 v[16:17], v[16:17], v[56:57]
	v_pk_add_f32 v[14:15], v[14:15], v[66:67]
	v_lshl_add_u64 v[0:1], s[6:7], 0, v[0:1]
	s_lshl_b32 s94, s0, 1
	v_pk_add_f32 v[16:17], v[16:17], v[68:69]
	v_lshl_add_u64 v[0:1], v[0:1], 0, s[94:95]
	s_waitcnt vmcnt(0)
	v_mov_b32_e32 v18, v2
	v_mov_b32_e32 v19, v6
	v_mov_b32_e32 v6, v3
	v_pk_add_f32 v[2:3], v[18:19], v[6:7]
	v_mov_b32_e32 v6, v4
	v_mov_b32_e32 v7, v8
	v_mov_b32_e32 v8, v5
	v_pk_add_f32 v[4:5], v[6:7], v[8:9]
	v_add_u32_e32 v6, 0x1e000, v62
	v_pk_add_f32 v[2:3], v[2:3], v[4:5]
	s_nop 0
	v_add_f32_e32 v18, v2, v3
	v_and_b32_e32 v3, 64, v214
	v_xor_b32_e32 v2, 16, v214
	v_add_u32_e32 v19, 64, v3
	v_cmp_lt_i32_e32 vcc, v2, v19
	s_nop 1
	v_cndmask_b32_e32 v2, v214, v2, vcc
	v_lshlrev_b32_e32 v2, 2, v2
	ds_bpermute_b32 v20, v2, v18
	v_add_u32_e32 v2, 0x1c000, v62
	ds_read_b128 v[2:5], v2
	ds_read_b128 v[6:9], v6
	s_waitcnt lgkmcnt(2)
	v_add_f32_e32 v18, v18, v20
	v_xor_b32_e32 v20, 32, v214
	v_cmp_lt_i32_e32 vcc, v20, v19
	s_waitcnt lgkmcnt(1)
	v_pk_add_f32 v[2:3], v[10:11], v[2:3]
	v_pk_add_f32 v[4:5], v[12:13], v[4:5]
	v_cndmask_b32_e32 v19, v214, v20, vcc
	v_lshlrev_b32_e32 v19, 2, v19
	ds_bpermute_b32 v19, v19, v18
	s_waitcnt lgkmcnt(1)
	v_pk_add_f32 v[6:7], v[14:15], v[6:7]
	v_pk_add_f32 v[8:9], v[16:17], v[8:9]
	s_waitcnt lgkmcnt(0)
	v_add_f32_e32 v10, v18, v19
	v_fmamk_f32 v10, v10, 0x3a000000, v190
	v_mul_f32_e32 v11, 0x4b800000, v10
	v_cmp_gt_f32_e32 vcc, s70, v10
	s_nop 1
	v_cndmask_b32_e32 v10, v10, v11, vcc
	v_rsq_f32_e32 v10, v10
	v_lshlrev_b32_e32 v11, 2, v64
	v_lshl_or_b32 v11, s3, 4, v11
	v_or_b32_e32 v11, s1, v11
	v_mul_f32_e32 v12, 0x45800000, v10
	v_cndmask_b32_e32 v10, v10, v12, vcc
	v_lshlrev_b32_e32 v128, 1, v11
	v_pk_mul_f32 v[4:5], v[4:5], v[10:11] op_sel_hi:[1,0]
	v_pk_mul_f32 v[2:3], v[2:3], v[10:11] op_sel_hi:[1,0]
	v_lshl_add_u64 v[0:1], v[0:1], 0, v[128:129]
	v_cvt_pk_bf16_f32 v2, v2, v3
	v_cvt_pk_bf16_f32 v3, v4, v5
	v_pk_mul_f32 v[4:5], v[6:7], v[10:11] op_sel_hi:[1,0]
	global_store_dwordx2 v[0:1], v[2:3], off
	v_pk_mul_f32 v[2:3], v[8:9], v[10:11] op_sel_hi:[1,0]
	v_cvt_pk_bf16_f32 v4, v4, v5
	s_nop 0
	v_cvt_pk_bf16_f32 v5, v2, v3
	global_store_dwordx2 v[0:1], v[4:5], off offset:256
	s_waitcnt lgkmcnt(0)
	s_barrier

.LBB0_199:
	v_add_co_u32_e32 v82, vcc, s84, v66
	s_nop 1
	v_addc_co_u32_e32 v83, vcc, 0, v67, vcc
	v_add_co_u32_e32 v130, vcc, s85, v66
	s_nop 1
	v_addc_co_u32_e32 v131, vcc, 0, v67, vcc
	v_add_co_u32_e32 v172, vcc, s88, v66
	s_nop 1
	v_addc_co_u32_e32 v173, vcc, 0, v67, vcc
	v_add_co_u32_e32 v174, vcc, s89, v66
	s_nop 1
	v_addc_co_u32_e32 v175, vcc, 0, v67, vcc
	v_add_co_u32_e32 v176, vcc, 0x4008000, v64
	s_nop 1
	v_addc_co_u32_e32 v177, vcc, 0, v65, vcc
	v_add_co_u32_e32 v178, vcc, 0x4018000, v64
	s_nop 1
	v_addc_co_u32_e32 v179, vcc, 0, v65, vcc
	v_add_co_u32_e32 v180, vcc, 0x4088000, v64
	s_nop 1
	v_addc_co_u32_e32 v181, vcc, 0, v65, vcc
	v_add_co_u32_e32 v182, vcc, 0x4098000, v64
	s_nop 1
	v_addc_co_u32_e32 v183, vcc, 0, v65, vcc
	global_load_dwordx4 v[68:71], v[82:83], off
	global_load_dwordx4 v[72:75], v[130:131], off
	global_load_dwordx4 v[76:79], v[172:173], off
	global_load_dwordx4 v[84:87], v[174:175], off
	global_load_dwordx4 v[88:91], v[176:177], off
	global_load_dwordx4 v[92:95], v[178:179], off
	global_load_dwordx4 v[96:99], v[180:181], off
	global_load_dwordx4 v[100:103], v[182:183], off
	global_load_dwordx4 v[104:107], v[82:83], off offset:64
	global_load_dwordx4 v[108:111], v[130:131], off offset:64
	global_load_dwordx4 v[112:115], v[172:173], off offset:64
	global_load_dwordx4 v[116:119], v[174:175], off offset:64
	global_load_dwordx4 v[120:123], v[176:177], off offset:64
	global_load_dwordx4 v[124:127], v[178:179], off offset:64
	global_load_dwordx4 v[132:135], v[180:181], off offset:64
	global_load_dwordx4 v[136:139], v[182:183], off offset:64
	global_load_dwordx4 v[140:143], v[82:83], off offset:128
	global_load_dwordx4 v[144:147], v[130:131], off offset:128
	global_load_dwordx4 v[148:151], v[172:173], off offset:128
	global_load_dwordx4 v[152:155], v[174:175], off offset:128
	global_load_dwordx4 v[156:159], v[176:177], off offset:128
	global_load_dwordx4 v[160:163], v[178:179], off offset:128
	global_load_dwordx4 v[164:167], v[180:181], off offset:128
	global_load_dwordx4 v[168:171], v[182:183], off offset:128
	s_waitcnt vmcnt(16)
	v_mfma_f32_16x16x32_bf16 v[56:59], v[88:91], v[68:71], 0
	v_mfma_f32_16x16x32_bf16 v[52:55], v[88:91], v[72:75], 0
	v_mfma_f32_16x16x32_bf16 v[48:51], v[88:91], v[76:79], 0
	v_mfma_f32_16x16x32_bf16 v[44:47], v[88:91], v[84:87], 0
	v_mfma_f32_16x16x32_bf16 v[12:15], v[92:95], v[68:71], 0
	v_mfma_f32_16x16x32_bf16 v[8:11], v[92:95], v[72:75], 0
	v_mfma_f32_16x16x32_bf16 v[4:7], v[92:95], v[76:79], 0
	v_mfma_f32_16x16x32_bf16 v[0:3], v[92:95], v[84:87], 0
	v_mfma_f32_16x16x32_bf16 v[16:19], v[96:99], v[68:71], 0
	v_mfma_f32_16x16x32_bf16 v[24:27], v[96:99], v[72:75], 0
	v_mfma_f32_16x16x32_bf16 v[28:31], v[96:99], v[76:79], 0
	v_mfma_f32_16x16x32_bf16 v[36:39], v[96:99], v[84:87], 0
	v_mfma_f32_16x16x32_bf16 v[20:23], v[100:103], v[68:71], 0
	v_mfma_f32_16x16x32_bf16 v[32:35], v[100:103], v[72:75], 0
	v_mfma_f32_16x16x32_bf16 v[40:43], v[100:103], v[76:79], 0
	v_mfma_f32_16x16x32_bf16 v[60:63], v[100:103], v[84:87], 0
	global_load_dwordx4 v[68:71], v[82:83], off offset:192
	global_load_dwordx4 v[72:75], v[130:131], off offset:192
	global_load_dwordx4 v[76:79], v[172:173], off offset:192
	global_load_dwordx4 v[84:87], v[174:175], off offset:192
	global_load_dwordx4 v[88:91], v[176:177], off offset:192
	global_load_dwordx4 v[92:95], v[178:179], off offset:192
	global_load_dwordx4 v[96:99], v[180:181], off offset:192
	global_load_dwordx4 v[100:103], v[182:183], off offset:192
	s_waitcnt vmcnt(16)
	v_mfma_f32_16x16x32_bf16 v[56:59], v[120:123], v[104:107], v[56:59]
	v_mfma_f32_16x16x32_bf16 v[52:55], v[120:123], v[108:111], v[52:55]
	v_mfma_f32_16x16x32_bf16 v[48:51], v[120:123], v[112:115], v[48:51]
	v_mfma_f32_16x16x32_bf16 v[44:47], v[120:123], v[116:119], v[44:47]
	v_mfma_f32_16x16x32_bf16 v[12:15], v[124:127], v[104:107], v[12:15]
	v_mfma_f32_16x16x32_bf16 v[8:11], v[124:127], v[108:111], v[8:11]
	v_mfma_f32_16x16x32_bf16 v[4:7], v[124:127], v[112:115], v[4:7]
	v_mfma_f32_16x16x32_bf16 v[0:3], v[124:127], v[116:119], v[0:3]
	v_mfma_f32_16x16x32_bf16 v[16:19], v[132:135], v[104:107], v[16:19]
	v_mfma_f32_16x16x32_bf16 v[24:27], v[132:135], v[108:111], v[24:27]
	v_mfma_f32_16x16x32_bf16 v[28:31], v[132:135], v[112:115], v[28:31]
	v_mfma_f32_16x16x32_bf16 v[36:39], v[132:135], v[116:119], v[36:39]
	v_mfma_f32_16x16x32_bf16 v[20:23], v[136:139], v[104:107], v[20:23]
	v_mfma_f32_16x16x32_bf16 v[32:35], v[136:139], v[108:111], v[32:35]
	v_mfma_f32_16x16x32_bf16 v[40:43], v[136:139], v[112:115], v[40:43]
	v_mfma_f32_16x16x32_bf16 v[60:63], v[136:139], v[116:119], v[60:63]
	global_load_dwordx4 v[104:107], v[82:83], off offset:256
	global_load_dwordx4 v[108:111], v[130:131], off offset:256
	global_load_dwordx4 v[112:115], v[172:173], off offset:256
	global_load_dwordx4 v[116:119], v[174:175], off offset:256
	global_load_dwordx4 v[120:123], v[176:177], off offset:256
	global_load_dwordx4 v[124:127], v[178:179], off offset:256
	global_load_dwordx4 v[132:135], v[180:181], off offset:256
	global_load_dwordx4 v[136:139], v[182:183], off offset:256
	s_waitcnt vmcnt(16)
	v_mfma_f32_16x16x32_bf16 v[56:59], v[156:159], v[140:143], v[56:59]
	v_mfma_f32_16x16x32_bf16 v[52:55], v[156:159], v[144:147], v[52:55]
	v_mfma_f32_16x16x32_bf16 v[48:51], v[156:159], v[148:151], v[48:51]
	v_mfma_f32_16x16x32_bf16 v[44:47], v[156:159], v[152:155], v[44:47]
	v_mfma_f32_16x16x32_bf16 v[12:15], v[160:163], v[140:143], v[12:15]
	v_mfma_f32_16x16x32_bf16 v[8:11], v[160:163], v[144:147], v[8:11]
	v_mfma_f32_16x16x32_bf16 v[4:7], v[160:163], v[148:151], v[4:7]
	v_mfma_f32_16x16x32_bf16 v[0:3], v[160:163], v[152:155], v[0:3]
	v_mfma_f32_16x16x32_bf16 v[16:19], v[164:167], v[140:143], v[16:19]
	v_mfma_f32_16x16x32_bf16 v[24:27], v[164:167], v[144:147], v[24:27]
	v_mfma_f32_16x16x32_bf16 v[28:31], v[164:167], v[148:151], v[28:31]
	v_mfma_f32_16x16x32_bf16 v[36:39], v[164:167], v[152:155], v[36:39]
	v_mfma_f32_16x16x32_bf16 v[20:23], v[168:171], v[140:143], v[20:23]
	v_mfma_f32_16x16x32_bf16 v[32:35], v[168:171], v[144:147], v[32:35]
	v_mfma_f32_16x16x32_bf16 v[40:43], v[168:171], v[148:151], v[40:43]
	v_mfma_f32_16x16x32_bf16 v[60:63], v[168:171], v[152:155], v[60:63]
	global_load_dwordx4 v[140:143], v[82:83], off offset:320
	global_load_dwordx4 v[144:147], v[130:131], off offset:320
	global_load_dwordx4 v[148:151], v[172:173], off offset:320
	global_load_dwordx4 v[152:155], v[174:175], off offset:320
	global_load_dwordx4 v[156:159], v[176:177], off offset:320
	global_load_dwordx4 v[160:163], v[178:179], off offset:320
	global_load_dwordx4 v[164:167], v[180:181], off offset:320
	global_load_dwordx4 v[168:171], v[182:183], off offset:320
	s_waitcnt vmcnt(16)
	v_mfma_f32_16x16x32_bf16 v[56:59], v[88:91], v[68:71], v[56:59]
	v_mfma_f32_16x16x32_bf16 v[52:55], v[88:91], v[72:75], v[52:55]
	v_mfma_f32_16x16x32_bf16 v[48:51], v[88:91], v[76:79], v[48:51]
	v_mfma_f32_16x16x32_bf16 v[44:47], v[88:91], v[84:87], v[44:47]
	v_mfma_f32_16x16x32_bf16 v[12:15], v[92:95], v[68:71], v[12:15]
	v_mfma_f32_16x16x32_bf16 v[8:11], v[92:95], v[72:75], v[8:11]
	v_mfma_f32_16x16x32_bf16 v[4:7], v[92:95], v[76:79], v[4:7]
	v_mfma_f32_16x16x32_bf16 v[0:3], v[92:95], v[84:87], v[0:3]
	v_mfma_f32_16x16x32_bf16 v[16:19], v[96:99], v[68:71], v[16:19]
	v_mfma_f32_16x16x32_bf16 v[24:27], v[96:99], v[72:75], v[24:27]
	v_mfma_f32_16x16x32_bf16 v[28:31], v[96:99], v[76:79], v[28:31]
	v_mfma_f32_16x16x32_bf16 v[36:39], v[96:99], v[84:87], v[36:39]
	v_mfma_f32_16x16x32_bf16 v[20:23], v[100:103], v[68:71], v[20:23]
	v_mfma_f32_16x16x32_bf16 v[32:35], v[100:103], v[72:75], v[32:35]
	v_mfma_f32_16x16x32_bf16 v[40:43], v[100:103], v[76:79], v[40:43]
	v_mfma_f32_16x16x32_bf16 v[60:63], v[100:103], v[84:87], v[60:63]
	global_load_dwordx4 v[68:71], v[82:83], off offset:384
	global_load_dwordx4 v[72:75], v[130:131], off offset:384
	global_load_dwordx4 v[76:79], v[172:173], off offset:384
	global_load_dwordx4 v[84:87], v[174:175], off offset:384
	global_load_dwordx4 v[88:91], v[176:177], off offset:384
	global_load_dwordx4 v[92:95], v[178:179], off offset:384
	global_load_dwordx4 v[96:99], v[180:181], off offset:384
	global_load_dwordx4 v[100:103], v[182:183], off offset:384
	s_waitcnt vmcnt(16)
	v_mfma_f32_16x16x32_bf16 v[56:59], v[120:123], v[104:107], v[56:59]
	v_mfma_f32_16x16x32_bf16 v[52:55], v[120:123], v[108:111], v[52:55]
	v_mfma_f32_16x16x32_bf16 v[48:51], v[120:123], v[112:115], v[48:51]
	v_mfma_f32_16x16x32_bf16 v[44:47], v[120:123], v[116:119], v[44:47]
	v_mfma_f32_16x16x32_bf16 v[12:15], v[124:127], v[104:107], v[12:15]
	v_mfma_f32_16x16x32_bf16 v[8:11], v[124:127], v[108:111], v[8:11]
	v_mfma_f32_16x16x32_bf16 v[4:7], v[124:127], v[112:115], v[4:7]
	v_mfma_f32_16x16x32_bf16 v[0:3], v[124:127], v[116:119], v[0:3]
	v_mfma_f32_16x16x32_bf16 v[16:19], v[132:135], v[104:107], v[16:19]
	v_mfma_f32_16x16x32_bf16 v[24:27], v[132:135], v[108:111], v[24:27]
	v_mfma_f32_16x16x32_bf16 v[28:31], v[132:135], v[112:115], v[28:31]
	v_mfma_f32_16x16x32_bf16 v[36:39], v[132:135], v[116:119], v[36:39]
	v_mfma_f32_16x16x32_bf16 v[20:23], v[136:139], v[104:107], v[20:23]
	v_mfma_f32_16x16x32_bf16 v[32:35], v[136:139], v[108:111], v[32:35]
	v_mfma_f32_16x16x32_bf16 v[40:43], v[136:139], v[112:115], v[40:43]
	v_mfma_f32_16x16x32_bf16 v[60:63], v[136:139], v[116:119], v[60:63]
	global_load_dwordx4 v[104:107], v[82:83], off offset:448
	global_load_dwordx4 v[108:111], v[130:131], off offset:448
	global_load_dwordx4 v[112:115], v[172:173], off offset:448
	global_load_dwordx4 v[116:119], v[174:175], off offset:448
	global_load_dwordx4 v[120:123], v[176:177], off offset:448
	global_load_dwordx4 v[124:127], v[178:179], off offset:448
	global_load_dwordx4 v[132:135], v[180:181], off offset:448
	global_load_dwordx4 v[136:139], v[182:183], off offset:448
	s_waitcnt vmcnt(16)
	v_mfma_f32_16x16x32_bf16 v[56:59], v[156:159], v[140:143], v[56:59]
	v_mfma_f32_16x16x32_bf16 v[52:55], v[156:159], v[144:147], v[52:55]
	v_mfma_f32_16x16x32_bf16 v[48:51], v[156:159], v[148:151], v[48:51]
	v_mfma_f32_16x16x32_bf16 v[44:47], v[156:159], v[152:155], v[44:47]
	v_mfma_f32_16x16x32_bf16 v[12:15], v[160:163], v[140:143], v[12:15]
	v_mfma_f32_16x16x32_bf16 v[8:11], v[160:163], v[144:147], v[8:11]
	v_mfma_f32_16x16x32_bf16 v[4:7], v[160:163], v[148:151], v[4:7]
	v_mfma_f32_16x16x32_bf16 v[0:3], v[160:163], v[152:155], v[0:3]
	v_mfma_f32_16x16x32_bf16 v[16:19], v[164:167], v[140:143], v[16:19]
	v_mfma_f32_16x16x32_bf16 v[24:27], v[164:167], v[144:147], v[24:27]
	v_mfma_f32_16x16x32_bf16 v[28:31], v[164:167], v[148:151], v[28:31]
	v_mfma_f32_16x16x32_bf16 v[36:39], v[164:167], v[152:155], v[36:39]
	v_mfma_f32_16x16x32_bf16 v[20:23], v[168:171], v[140:143], v[20:23]
	v_mfma_f32_16x16x32_bf16 v[32:35], v[168:171], v[144:147], v[32:35]
	v_mfma_f32_16x16x32_bf16 v[40:43], v[168:171], v[148:151], v[40:43]
	v_mfma_f32_16x16x32_bf16 v[60:63], v[168:171], v[152:155], v[60:63]
	s_waitcnt vmcnt(8)
	v_mfma_f32_16x16x32_bf16 v[56:59], v[88:91], v[68:71], v[56:59]
	v_mfma_f32_16x16x32_bf16 v[52:55], v[88:91], v[72:75], v[52:55]
	v_mfma_f32_16x16x32_bf16 v[48:51], v[88:91], v[76:79], v[48:51]
	v_mfma_f32_16x16x32_bf16 v[44:47], v[88:91], v[84:87], v[44:47]
	v_mfma_f32_16x16x32_bf16 v[12:15], v[92:95], v[68:71], v[12:15]
	v_mfma_f32_16x16x32_bf16 v[8:11], v[92:95], v[72:75], v[8:11]
	v_mfma_f32_16x16x32_bf16 v[4:7], v[92:95], v[76:79], v[4:7]
	v_mfma_f32_16x16x32_bf16 v[0:3], v[92:95], v[84:87], v[0:3]
	v_mfma_f32_16x16x32_bf16 v[16:19], v[96:99], v[68:71], v[16:19]
	v_mfma_f32_16x16x32_bf16 v[24:27], v[96:99], v[72:75], v[24:27]
	v_mfma_f32_16x16x32_bf16 v[28:31], v[96:99], v[76:79], v[28:31]
	v_mfma_f32_16x16x32_bf16 v[36:39], v[96:99], v[84:87], v[36:39]
	v_mfma_f32_16x16x32_bf16 v[20:23], v[100:103], v[68:71], v[20:23]
	v_mfma_f32_16x16x32_bf16 v[32:35], v[100:103], v[72:75], v[32:35]
	v_mfma_f32_16x16x32_bf16 v[40:43], v[100:103], v[76:79], v[40:43]
	v_mfma_f32_16x16x32_bf16 v[60:63], v[100:103], v[84:87], v[60:63]
	s_waitcnt vmcnt(0)
	v_mfma_f32_16x16x32_bf16 v[56:59], v[120:123], v[104:107], v[56:59]
	v_mfma_f32_16x16x32_bf16 v[52:55], v[120:123], v[108:111], v[52:55]
	v_mfma_f32_16x16x32_bf16 v[48:51], v[120:123], v[112:115], v[48:51]
	v_mfma_f32_16x16x32_bf16 v[44:47], v[120:123], v[116:119], v[44:47]
	v_mfma_f32_16x16x32_bf16 v[12:15], v[124:127], v[104:107], v[12:15]
	v_mfma_f32_16x16x32_bf16 v[8:11], v[124:127], v[108:111], v[8:11]
	v_mfma_f32_16x16x32_bf16 v[4:7], v[124:127], v[112:115], v[4:7]
	v_mfma_f32_16x16x32_bf16 v[0:3], v[124:127], v[116:119], v[0:3]
	v_mfma_f32_16x16x32_bf16 v[16:19], v[132:135], v[104:107], v[16:19]
	v_mfma_f32_16x16x32_bf16 v[24:27], v[132:135], v[108:111], v[24:27]
	v_mfma_f32_16x16x32_bf16 v[28:31], v[132:135], v[112:115], v[28:31]
	v_mfma_f32_16x16x32_bf16 v[36:39], v[132:135], v[116:119], v[36:39]
	v_mfma_f32_16x16x32_bf16 v[20:23], v[136:139], v[104:107], v[20:23]
	v_mfma_f32_16x16x32_bf16 v[32:35], v[136:139], v[108:111], v[32:35]
	v_mfma_f32_16x16x32_bf16 v[40:43], v[136:139], v[112:115], v[40:43]
	v_mfma_f32_16x16x32_bf16 v[60:63], v[136:139], v[116:119], v[60:63]
	s_nop 7
	s_nop 3
	v_and_b32_e32 v65, 63, v81
	s_ashr_i32 s2, s11, 7
	v_lshl_add_u32 v65, v65, 4, 0
	s_lshl_b32 s3, s2, 4
	v_lshl_add_u32 v66, s12, 14, v65
	s_addk_i32 s3, 0x4000
	ds_write_b128 v66, v[56:59]
	ds_write_b128 v66, v[52:55] offset:1024
	ds_write_b128 v66, v[48:51] offset:2048
	ds_write_b128 v66, v[44:47] offset:3072
	ds_write_b128 v66, v[12:15] offset:4096
	ds_write_b128 v66, v[8:11] offset:5120
	ds_write_b128 v66, v[4:7] offset:6144
	ds_write_b128 v66, v[0:3] offset:7168
	ds_write_b128 v66, v[16:19] offset:8192
	ds_write_b128 v66, v[24:27] offset:9216
	ds_write_b128 v66, v[28:31] offset:10240
	ds_write_b128 v66, v[36:39] offset:11264
	ds_write_b128 v66, v[20:23] offset:12288
	ds_write_b128 v66, v[32:35] offset:13312
	ds_write_b128 v66, v[40:43] offset:14336
	ds_write_b128 v66, v[60:63] offset:15360
	v_or_b32_e32 v0, s3, v80
	v_ashrrev_i32_e32 v1, 31, v0
	v_bfe_u32 v64, v81, 4, 2
	v_lshlrev_b64 v[2:3], 7, v[0:1]
	v_lshl_add_u64 v[2:3], s[6:7], 0, v[2:3]
	v_lshlrev_b32_e32 v128, 5, v64
	v_lshl_add_u64 v[6:7], v[2:3], 0, v[128:129]
	s_waitcnt lgkmcnt(0)
	s_barrier
	global_load_dwordx4 v[2:5], v[6:7], off
	s_nop 0
	global_load_dwordx4 v[6:9], v[6:7], off offset:16
	s_bfe_u32 s3, s11, 0x10006
	s_lshl_b32 s6, s3, 2
	s_add_i32 s6, s6, s2
	v_lshl_add_u32 v62, s6, 10, v65
	ds_read_b128 v[10:13], v62
	ds_read_b128 v[14:17], v62 offset:8192
	ds_read_b128 v[18:21], v62 offset:16384
	ds_read_b128 v[22:25], v62 offset:24576
	ds_read_b128 v[26:29], v62 offset:32768
	ds_read_b128 v[30:33], v62 offset:40960
	ds_read_b128 v[34:37], v62 offset:49152
	ds_read_b128 v[38:41], v62 offset:57344
	s_waitcnt lgkmcnt(0)
	v_pk_add_f32 v[10:11], v[10:11], 0 op_sel_hi:[1,0]
	v_pk_add_f32 v[12:13], v[12:13], 0 op_sel_hi:[1,0]
	v_pk_add_f32 v[10:11], v[10:11], v[18:19]
	v_pk_add_f32 v[12:13], v[12:13], v[20:21]
	v_add_u32_e32 v42, 0x10000, v62
	v_add_u32_e32 v46, 0x12000, v62
	v_add_u32_e32 v50, 0x14000, v62
	v_add_u32_e32 v54, 0x16000, v62
	v_add_u32_e32 v58, 0x18000, v62
	v_add_u32_e32 v63, 0x1a000, v62
	ds_read_b128 v[42:45], v42
	ds_read_b128 v[46:49], v46
	ds_read_b128 v[50:53], v50
	ds_read_b128 v[54:57], v54
	ds_read_b128 v[58:61], v58
	ds_read_b128 v[66:69], v63
	v_pk_add_f32 v[10:11], v[10:11], v[26:27]
	v_pk_add_f32 v[14:15], v[14:15], 0 op_sel_hi:[1,0]
	v_pk_add_f32 v[10:11], v[10:11], v[34:35]
	v_pk_add_f32 v[12:13], v[12:13], v[28:29]
	s_waitcnt lgkmcnt(0)
	v_pk_add_f32 v[10:11], v[10:11], v[42:43]
	v_pk_add_f32 v[16:17], v[16:17], 0 op_sel_hi:[1,0]
	v_pk_add_f32 v[10:11], v[10:11], v[50:51]
	v_pk_add_f32 v[14:15], v[14:15], v[22:23]
	v_pk_add_f32 v[10:11], v[10:11], v[58:59]
	v_pk_add_f32 v[12:13], v[12:13], v[36:37]
	s_ashr_i32 s2, s5, 5
	v_pk_add_f32 v[16:17], v[16:17], v[24:25]
	v_pk_add_f32 v[14:15], v[14:15], v[30:31]
	v_pk_add_f32 v[12:13], v[12:13], v[44:45]
	v_pk_add_f32 v[16:17], v[16:17], v[32:33]
	v_pk_add_f32 v[14:15], v[14:15], v[38:39]
	v_pk_add_f32 v[12:13], v[12:13], v[52:53]
	v_pk_add_f32 v[16:17], v[16:17], v[40:41]
	v_pk_add_f32 v[14:15], v[14:15], v[46:47]
	v_pk_add_f32 v[12:13], v[12:13], v[60:61]
	v_lshlrev_b64 v[0:1], 12, v[0:1]
	v_pk_add_f32 v[16:17], v[16:17], v[48:49]
	v_pk_add_f32 v[14:15], v[14:15], v[54:55]
	v_pk_add_f32 v[16:17], v[16:17], v[56:57]
	v_pk_add_f32 v[14:15], v[14:15], v[66:67]
	v_pk_add_f32 v[16:17], v[16:17], v[68:69]
	s_waitcnt vmcnt(0)
	v_mov_b32_e32 v18, v2
	v_mov_b32_e32 v19, v6
	v_mov_b32_e32 v6, v3
	v_pk_add_f32 v[2:3], v[18:19], v[6:7]
	v_mov_b32_e32 v6, v4
	v_mov_b32_e32 v7, v8
	v_mov_b32_e32 v8, v5
	v_pk_add_f32 v[4:5], v[6:7], v[8:9]
	v_add_u32_e32 v6, 0x1e000, v62
	v_pk_add_f32 v[2:3], v[2:3], v[4:5]
	s_nop 0
	v_add_f32_e32 v18, v2, v3
	v_and_b32_e32 v3, 64, v214
	v_xor_b32_e32 v2, 16, v214
	v_add_u32_e32 v19, 64, v3
	v_cmp_lt_i32_e32 vcc, v2, v19
	s_nop 1
	v_cndmask_b32_e32 v2, v214, v2, vcc
	v_lshlrev_b32_e32 v2, 2, v2
	ds_bpermute_b32 v20, v2, v18
	v_add_u32_e32 v2, 0x1c000, v62
	ds_read_b128 v[2:5], v2
	ds_read_b128 v[6:9], v6
	s_waitcnt lgkmcnt(2)
	v_add_f32_e32 v18, v18, v20
	v_xor_b32_e32 v20, 32, v214
	v_cmp_lt_i32_e32 vcc, v20, v19
	s_waitcnt lgkmcnt(1)
	v_pk_add_f32 v[2:3], v[10:11], v[2:3]
	v_pk_add_f32 v[4:5], v[12:13], v[4:5]
	v_cndmask_b32_e32 v19, v214, v20, vcc
	v_lshlrev_b32_e32 v19, 2, v19
	ds_bpermute_b32 v19, v19, v18
	s_waitcnt lgkmcnt(1)
	v_pk_add_f32 v[6:7], v[14:15], v[6:7]
	v_pk_add_f32 v[8:9], v[16:17], v[8:9]
	s_waitcnt lgkmcnt(0)
	v_add_f32_e32 v10, v18, v19
	v_fmamk_f32 v10, v10, 0x3a000000, v190
	v_mul_f32_e32 v11, 0x4b800000, v10
	v_cmp_gt_f32_e32 vcc, s70, v10
	s_nop 1
	v_cndmask_b32_e32 v10, v10, v11, vcc
	v_rsq_f32_e32 v10, v10
	v_lshlrev_b32_e32 v11, 2, v64
	v_lshl_or_b32 v11, s3, 4, v11
	s_mul_hi_i32 s3, s2, 0x4200000
	s_mul_i32 s2, s2, 0x4200000
	s_add_u32 s0, s0, s2
	s_addc_u32 s1, s1, s3
	v_mul_f32_e32 v12, 0x45800000, v10
	v_lshl_add_u64 v[0:1], s[0:1], 0, v[0:1]
	s_and_b32 s0, s4, 0x700
	v_or_b32_e32 v11, s10, v11
	v_cndmask_b32_e32 v10, v10, v12, vcc
	s_lshl_b32 s94, s0, 1
	v_lshl_add_u64 v[0:1], v[0:1], 0, s[94:95]
	v_lshlrev_b32_e32 v128, 1, v11
	v_pk_mul_f32 v[4:5], v[4:5], v[10:11] op_sel_hi:[1,0]
	v_pk_mul_f32 v[2:3], v[2:3], v[10:11] op_sel_hi:[1,0]
	v_lshl_add_u64 v[0:1], v[0:1], 0, v[128:129]
	v_cvt_pk_bf16_f32 v2, v2, v3
	v_cvt_pk_bf16_f32 v3, v4, v5
	v_pk_mul_f32 v[4:5], v[6:7], v[10:11] op_sel_hi:[1,0]
	global_store_dwordx2 v[0:1], v[2:3], off
	v_pk_mul_f32 v[2:3], v[8:9], v[10:11] op_sel_hi:[1,0]
	v_cvt_pk_bf16_f32 v4, v4, v5
	s_nop 0
	v_cvt_pk_bf16_f32 v5, v2, v3
	global_store_dwordx2 v[0:1], v[4:5], off offset:256
	s_waitcnt lgkmcnt(0)
	s_barrier

.LBB0_797:
	v_add_co_u32_e32 v82, vcc, 0x3f5d0000, v66
	s_nop 1
	v_addc_co_u32_e32 v83, vcc, 0, v67, vcc
	v_add_co_u32_e32 v130, vcc, 0x3f5e0000, v66
	s_nop 1
	v_addc_co_u32_e32 v131, vcc, 0, v67, vcc
	v_add_co_u32_e32 v172, vcc, 0x3f5f0000, v66
	s_nop 1
	v_addc_co_u32_e32 v173, vcc, 0, v67, vcc
	v_add_co_u32_e32 v174, vcc, 0x3f600000, v66
	s_nop 1
	v_addc_co_u32_e32 v175, vcc, 0, v67, vcc
	v_add_co_u32_e32 v176, vcc, 0x6008000, v64
	s_nop 1
	v_addc_co_u32_e32 v177, vcc, 0, v65, vcc
	v_add_co_u32_e32 v178, vcc, 0x6018000, v64
	s_nop 1
	v_addc_co_u32_e32 v179, vcc, 0, v65, vcc
	v_add_co_u32_e32 v180, vcc, 0x6088000, v64
	s_nop 1
	v_addc_co_u32_e32 v181, vcc, 0, v65, vcc
	v_add_co_u32_e32 v182, vcc, 0x6098000, v64
	s_nop 1
	v_addc_co_u32_e32 v183, vcc, 0, v65, vcc
	global_load_dwordx4 v[68:71], v[82:83], off
	global_load_dwordx4 v[72:75], v[130:131], off
	global_load_dwordx4 v[76:79], v[172:173], off
	global_load_dwordx4 v[84:87], v[174:175], off
	global_load_dwordx4 v[88:91], v[176:177], off
	global_load_dwordx4 v[92:95], v[178:179], off
	global_load_dwordx4 v[96:99], v[180:181], off
	global_load_dwordx4 v[100:103], v[182:183], off
	global_load_dwordx4 v[104:107], v[82:83], off offset:64
	global_load_dwordx4 v[108:111], v[130:131], off offset:64
	global_load_dwordx4 v[112:115], v[172:173], off offset:64
	global_load_dwordx4 v[116:119], v[174:175], off offset:64
	global_load_dwordx4 v[120:123], v[176:177], off offset:64
	global_load_dwordx4 v[124:127], v[178:179], off offset:64
	global_load_dwordx4 v[132:135], v[180:181], off offset:64
	global_load_dwordx4 v[136:139], v[182:183], off offset:64
	global_load_dwordx4 v[140:143], v[82:83], off offset:128
	global_load_dwordx4 v[144:147], v[130:131], off offset:128
	global_load_dwordx4 v[148:151], v[172:173], off offset:128
	global_load_dwordx4 v[152:155], v[174:175], off offset:128
	global_load_dwordx4 v[156:159], v[176:177], off offset:128
	global_load_dwordx4 v[160:163], v[178:179], off offset:128
	global_load_dwordx4 v[164:167], v[180:181], off offset:128
	global_load_dwordx4 v[168:171], v[182:183], off offset:128
	s_waitcnt vmcnt(16)
	v_mfma_f32_16x16x32_bf16 v[56:59], v[88:91], v[68:71], 0
	v_mfma_f32_16x16x32_bf16 v[52:55], v[88:91], v[72:75], 0
	v_mfma_f32_16x16x32_bf16 v[48:51], v[88:91], v[76:79], 0
	v_mfma_f32_16x16x32_bf16 v[44:47], v[88:91], v[84:87], 0
	v_mfma_f32_16x16x32_bf16 v[12:15], v[92:95], v[68:71], 0
	v_mfma_f32_16x16x32_bf16 v[8:11], v[92:95], v[72:75], 0
	v_mfma_f32_16x16x32_bf16 v[4:7], v[92:95], v[76:79], 0
	v_mfma_f32_16x16x32_bf16 v[0:3], v[92:95], v[84:87], 0
	v_mfma_f32_16x16x32_bf16 v[16:19], v[96:99], v[68:71], 0
	v_mfma_f32_16x16x32_bf16 v[24:27], v[96:99], v[72:75], 0
	v_mfma_f32_16x16x32_bf16 v[28:31], v[96:99], v[76:79], 0
	v_mfma_f32_16x16x32_bf16 v[36:39], v[96:99], v[84:87], 0
	v_mfma_f32_16x16x32_bf16 v[20:23], v[100:103], v[68:71], 0
	v_mfma_f32_16x16x32_bf16 v[32:35], v[100:103], v[72:75], 0
	v_mfma_f32_16x16x32_bf16 v[40:43], v[100:103], v[76:79], 0
	v_mfma_f32_16x16x32_bf16 v[60:63], v[100:103], v[84:87], 0
	global_load_dwordx4 v[68:71], v[82:83], off offset:192
	global_load_dwordx4 v[72:75], v[130:131], off offset:192
	global_load_dwordx4 v[76:79], v[172:173], off offset:192
	global_load_dwordx4 v[84:87], v[174:175], off offset:192
	global_load_dwordx4 v[88:91], v[176:177], off offset:192
	global_load_dwordx4 v[92:95], v[178:179], off offset:192
	global_load_dwordx4 v[96:99], v[180:181], off offset:192
	global_load_dwordx4 v[100:103], v[182:183], off offset:192
	s_waitcnt vmcnt(16)
	v_mfma_f32_16x16x32_bf16 v[56:59], v[120:123], v[104:107], v[56:59]
	v_mfma_f32_16x16x32_bf16 v[52:55], v[120:123], v[108:111], v[52:55]
	v_mfma_f32_16x16x32_bf16 v[48:51], v[120:123], v[112:115], v[48:51]
	v_mfma_f32_16x16x32_bf16 v[44:47], v[120:123], v[116:119], v[44:47]
	v_mfma_f32_16x16x32_bf16 v[12:15], v[124:127], v[104:107], v[12:15]
	v_mfma_f32_16x16x32_bf16 v[8:11], v[124:127], v[108:111], v[8:11]
	v_mfma_f32_16x16x32_bf16 v[4:7], v[124:127], v[112:115], v[4:7]
	v_mfma_f32_16x16x32_bf16 v[0:3], v[124:127], v[116:119], v[0:3]
	v_mfma_f32_16x16x32_bf16 v[16:19], v[132:135], v[104:107], v[16:19]
	v_mfma_f32_16x16x32_bf16 v[24:27], v[132:135], v[108:111], v[24:27]
	v_mfma_f32_16x16x32_bf16 v[28:31], v[132:135], v[112:115], v[28:31]
	v_mfma_f32_16x16x32_bf16 v[36:39], v[132:135], v[116:119], v[36:39]
	v_mfma_f32_16x16x32_bf16 v[20:23], v[136:139], v[104:107], v[20:23]
	v_mfma_f32_16x16x32_bf16 v[32:35], v[136:139], v[108:111], v[32:35]
	v_mfma_f32_16x16x32_bf16 v[40:43], v[136:139], v[112:115], v[40:43]
	v_mfma_f32_16x16x32_bf16 v[60:63], v[136:139], v[116:119], v[60:63]
	global_load_dwordx4 v[104:107], v[82:83], off offset:256
	global_load_dwordx4 v[108:111], v[130:131], off offset:256
	global_load_dwordx4 v[112:115], v[172:173], off offset:256
	global_load_dwordx4 v[116:119], v[174:175], off offset:256
	global_load_dwordx4 v[120:123], v[176:177], off offset:256
	global_load_dwordx4 v[124:127], v[178:179], off offset:256
	global_load_dwordx4 v[132:135], v[180:181], off offset:256
	global_load_dwordx4 v[136:139], v[182:183], off offset:256
	s_waitcnt vmcnt(16)
	v_mfma_f32_16x16x32_bf16 v[56:59], v[156:159], v[140:143], v[56:59]
	v_mfma_f32_16x16x32_bf16 v[52:55], v[156:159], v[144:147], v[52:55]
	v_mfma_f32_16x16x32_bf16 v[48:51], v[156:159], v[148:151], v[48:51]
	v_mfma_f32_16x16x32_bf16 v[44:47], v[156:159], v[152:155], v[44:47]
	v_mfma_f32_16x16x32_bf16 v[12:15], v[160:163], v[140:143], v[12:15]
	v_mfma_f32_16x16x32_bf16 v[8:11], v[160:163], v[144:147], v[8:11]
	v_mfma_f32_16x16x32_bf16 v[4:7], v[160:163], v[148:151], v[4:7]
	v_mfma_f32_16x16x32_bf16 v[0:3], v[160:163], v[152:155], v[0:3]
	v_mfma_f32_16x16x32_bf16 v[16:19], v[164:167], v[140:143], v[16:19]
	v_mfma_f32_16x16x32_bf16 v[24:27], v[164:167], v[144:147], v[24:27]
	v_mfma_f32_16x16x32_bf16 v[28:31], v[164:167], v[148:151], v[28:31]
	v_mfma_f32_16x16x32_bf16 v[36:39], v[164:167], v[152:155], v[36:39]
	v_mfma_f32_16x16x32_bf16 v[20:23], v[168:171], v[140:143], v[20:23]
	v_mfma_f32_16x16x32_bf16 v[32:35], v[168:171], v[144:147], v[32:35]
	v_mfma_f32_16x16x32_bf16 v[40:43], v[168:171], v[148:151], v[40:43]
	v_mfma_f32_16x16x32_bf16 v[60:63], v[168:171], v[152:155], v[60:63]
	global_load_dwordx4 v[140:143], v[82:83], off offset:320
	global_load_dwordx4 v[144:147], v[130:131], off offset:320
	global_load_dwordx4 v[148:151], v[172:173], off offset:320
	global_load_dwordx4 v[152:155], v[174:175], off offset:320
	global_load_dwordx4 v[156:159], v[176:177], off offset:320
	global_load_dwordx4 v[160:163], v[178:179], off offset:320
	global_load_dwordx4 v[164:167], v[180:181], off offset:320
	global_load_dwordx4 v[168:171], v[182:183], off offset:320
	s_waitcnt vmcnt(16)
	v_mfma_f32_16x16x32_bf16 v[56:59], v[88:91], v[68:71], v[56:59]
	v_mfma_f32_16x16x32_bf16 v[52:55], v[88:91], v[72:75], v[52:55]
	v_mfma_f32_16x16x32_bf16 v[48:51], v[88:91], v[76:79], v[48:51]
	v_mfma_f32_16x16x32_bf16 v[44:47], v[88:91], v[84:87], v[44:47]
	v_mfma_f32_16x16x32_bf16 v[12:15], v[92:95], v[68:71], v[12:15]
	v_mfma_f32_16x16x32_bf16 v[8:11], v[92:95], v[72:75], v[8:11]
	v_mfma_f32_16x16x32_bf16 v[4:7], v[92:95], v[76:79], v[4:7]
	v_mfma_f32_16x16x32_bf16 v[0:3], v[92:95], v[84:87], v[0:3]
	v_mfma_f32_16x16x32_bf16 v[16:19], v[96:99], v[68:71], v[16:19]
	v_mfma_f32_16x16x32_bf16 v[24:27], v[96:99], v[72:75], v[24:27]
	v_mfma_f32_16x16x32_bf16 v[28:31], v[96:99], v[76:79], v[28:31]
	v_mfma_f32_16x16x32_bf16 v[36:39], v[96:99], v[84:87], v[36:39]
	v_mfma_f32_16x16x32_bf16 v[20:23], v[100:103], v[68:71], v[20:23]
	v_mfma_f32_16x16x32_bf16 v[32:35], v[100:103], v[72:75], v[32:35]
	v_mfma_f32_16x16x32_bf16 v[40:43], v[100:103], v[76:79], v[40:43]
	v_mfma_f32_16x16x32_bf16 v[60:63], v[100:103], v[84:87], v[60:63]
	global_load_dwordx4 v[68:71], v[82:83], off offset:384
	global_load_dwordx4 v[72:75], v[130:131], off offset:384
	global_load_dwordx4 v[76:79], v[172:173], off offset:384
	global_load_dwordx4 v[84:87], v[174:175], off offset:384
	global_load_dwordx4 v[88:91], v[176:177], off offset:384
	global_load_dwordx4 v[92:95], v[178:179], off offset:384
	global_load_dwordx4 v[96:99], v[180:181], off offset:384
	global_load_dwordx4 v[100:103], v[182:183], off offset:384
	s_waitcnt vmcnt(16)
	v_mfma_f32_16x16x32_bf16 v[56:59], v[120:123], v[104:107], v[56:59]
	v_mfma_f32_16x16x32_bf16 v[52:55], v[120:123], v[108:111], v[52:55]
	v_mfma_f32_16x16x32_bf16 v[48:51], v[120:123], v[112:115], v[48:51]
	v_mfma_f32_16x16x32_bf16 v[44:47], v[120:123], v[116:119], v[44:47]
	v_mfma_f32_16x16x32_bf16 v[12:15], v[124:127], v[104:107], v[12:15]
	v_mfma_f32_16x16x32_bf16 v[8:11], v[124:127], v[108:111], v[8:11]
	v_mfma_f32_16x16x32_bf16 v[4:7], v[124:127], v[112:115], v[4:7]
	v_mfma_f32_16x16x32_bf16 v[0:3], v[124:127], v[116:119], v[0:3]
	v_mfma_f32_16x16x32_bf16 v[16:19], v[132:135], v[104:107], v[16:19]
	v_mfma_f32_16x16x32_bf16 v[24:27], v[132:135], v[108:111], v[24:27]
	v_mfma_f32_16x16x32_bf16 v[28:31], v[132:135], v[112:115], v[28:31]
	v_mfma_f32_16x16x32_bf16 v[36:39], v[132:135], v[116:119], v[36:39]
	v_mfma_f32_16x16x32_bf16 v[20:23], v[136:139], v[104:107], v[20:23]
	v_mfma_f32_16x16x32_bf16 v[32:35], v[136:139], v[108:111], v[32:35]
	v_mfma_f32_16x16x32_bf16 v[40:43], v[136:139], v[112:115], v[40:43]
	v_mfma_f32_16x16x32_bf16 v[60:63], v[136:139], v[116:119], v[60:63]
	global_load_dwordx4 v[104:107], v[82:83], off offset:448
	global_load_dwordx4 v[108:111], v[130:131], off offset:448
	global_load_dwordx4 v[112:115], v[172:173], off offset:448
	global_load_dwordx4 v[116:119], v[174:175], off offset:448
	global_load_dwordx4 v[120:123], v[176:177], off offset:448
	global_load_dwordx4 v[124:127], v[178:179], off offset:448
	global_load_dwordx4 v[132:135], v[180:181], off offset:448
	global_load_dwordx4 v[136:139], v[182:183], off offset:448
	s_waitcnt vmcnt(16)
	v_mfma_f32_16x16x32_bf16 v[56:59], v[156:159], v[140:143], v[56:59]
	v_mfma_f32_16x16x32_bf16 v[52:55], v[156:159], v[144:147], v[52:55]
	v_mfma_f32_16x16x32_bf16 v[48:51], v[156:159], v[148:151], v[48:51]
	v_mfma_f32_16x16x32_bf16 v[44:47], v[156:159], v[152:155], v[44:47]
	v_mfma_f32_16x16x32_bf16 v[12:15], v[160:163], v[140:143], v[12:15]
	v_mfma_f32_16x16x32_bf16 v[8:11], v[160:163], v[144:147], v[8:11]
	v_mfma_f32_16x16x32_bf16 v[4:7], v[160:163], v[148:151], v[4:7]
	v_mfma_f32_16x16x32_bf16 v[0:3], v[160:163], v[152:155], v[0:3]
	v_mfma_f32_16x16x32_bf16 v[16:19], v[164:167], v[140:143], v[16:19]
	v_mfma_f32_16x16x32_bf16 v[24:27], v[164:167], v[144:147], v[24:27]
	v_mfma_f32_16x16x32_bf16 v[28:31], v[164:167], v[148:151], v[28:31]
	v_mfma_f32_16x16x32_bf16 v[36:39], v[164:167], v[152:155], v[36:39]
	v_mfma_f32_16x16x32_bf16 v[20:23], v[168:171], v[140:143], v[20:23]
	v_mfma_f32_16x16x32_bf16 v[32:35], v[168:171], v[144:147], v[32:35]
	v_mfma_f32_16x16x32_bf16 v[40:43], v[168:171], v[148:151], v[40:43]
	v_mfma_f32_16x16x32_bf16 v[60:63], v[168:171], v[152:155], v[60:63]
	s_waitcnt vmcnt(8)
	v_mfma_f32_16x16x32_bf16 v[56:59], v[88:91], v[68:71], v[56:59]
	v_mfma_f32_16x16x32_bf16 v[52:55], v[88:91], v[72:75], v[52:55]
	v_mfma_f32_16x16x32_bf16 v[48:51], v[88:91], v[76:79], v[48:51]
	v_mfma_f32_16x16x32_bf16 v[44:47], v[88:91], v[84:87], v[44:47]
	v_mfma_f32_16x16x32_bf16 v[12:15], v[92:95], v[68:71], v[12:15]
	v_mfma_f32_16x16x32_bf16 v[8:11], v[92:95], v[72:75], v[8:11]
	v_mfma_f32_16x16x32_bf16 v[4:7], v[92:95], v[76:79], v[4:7]
	v_mfma_f32_16x16x32_bf16 v[0:3], v[92:95], v[84:87], v[0:3]
	v_mfma_f32_16x16x32_bf16 v[16:19], v[96:99], v[68:71], v[16:19]
	v_mfma_f32_16x16x32_bf16 v[24:27], v[96:99], v[72:75], v[24:27]
	v_mfma_f32_16x16x32_bf16 v[28:31], v[96:99], v[76:79], v[28:31]
	v_mfma_f32_16x16x32_bf16 v[36:39], v[96:99], v[84:87], v[36:39]
	v_mfma_f32_16x16x32_bf16 v[20:23], v[100:103], v[68:71], v[20:23]
	v_mfma_f32_16x16x32_bf16 v[32:35], v[100:103], v[72:75], v[32:35]
	v_mfma_f32_16x16x32_bf16 v[40:43], v[100:103], v[76:79], v[40:43]
	v_mfma_f32_16x16x32_bf16 v[60:63], v[100:103], v[84:87], v[60:63]
	s_waitcnt vmcnt(0)
	v_mfma_f32_16x16x32_bf16 v[56:59], v[120:123], v[104:107], v[56:59]
	v_mfma_f32_16x16x32_bf16 v[52:55], v[120:123], v[108:111], v[52:55]
	v_mfma_f32_16x16x32_bf16 v[48:51], v[120:123], v[112:115], v[48:51]
	v_mfma_f32_16x16x32_bf16 v[44:47], v[120:123], v[116:119], v[44:47]
	v_mfma_f32_16x16x32_bf16 v[12:15], v[124:127], v[104:107], v[12:15]
	v_mfma_f32_16x16x32_bf16 v[8:11], v[124:127], v[108:111], v[8:11]
	v_mfma_f32_16x16x32_bf16 v[4:7], v[124:127], v[112:115], v[4:7]
	v_mfma_f32_16x16x32_bf16 v[0:3], v[124:127], v[116:119], v[0:3]
	v_mfma_f32_16x16x32_bf16 v[16:19], v[132:135], v[104:107], v[16:19]
	v_mfma_f32_16x16x32_bf16 v[24:27], v[132:135], v[108:111], v[24:27]
	v_mfma_f32_16x16x32_bf16 v[28:31], v[132:135], v[112:115], v[28:31]
	v_mfma_f32_16x16x32_bf16 v[36:39], v[132:135], v[116:119], v[36:39]
	v_mfma_f32_16x16x32_bf16 v[20:23], v[136:139], v[104:107], v[20:23]
	v_mfma_f32_16x16x32_bf16 v[32:35], v[136:139], v[108:111], v[32:35]
	v_mfma_f32_16x16x32_bf16 v[40:43], v[136:139], v[112:115], v[40:43]
	v_mfma_f32_16x16x32_bf16 v[60:63], v[136:139], v[116:119], v[60:63]
	s_nop 7
	s_nop 3
	v_and_b32_e32 v65, 63, v81
	v_lshl_add_u32 v66, v65, 4, 0
	s_ashr_i32 s10, s0, 7
	v_bfe_u32 v64, v81, 4, 2
	v_lshl_add_u32 v67, s3, 14, v66
	s_lshl_b32 s5, s10, 4
	ds_write_b128 v67, v[56:59]
	ds_write_b128 v67, v[52:55] offset:1024
	ds_write_b128 v67, v[48:51] offset:2048
	ds_write_b128 v67, v[44:47] offset:3072
	ds_write_b128 v67, v[12:15] offset:4096
	ds_write_b128 v67, v[8:11] offset:5120
	ds_write_b128 v67, v[4:7] offset:6144
	ds_write_b128 v67, v[0:3] offset:7168
	ds_write_b128 v67, v[16:19] offset:8192
	ds_write_b128 v67, v[24:27] offset:9216
	ds_write_b128 v67, v[28:31] offset:10240
	ds_write_b128 v67, v[36:39] offset:11264
	ds_write_b128 v67, v[20:23] offset:12288
	ds_write_b128 v67, v[32:35] offset:13312
	ds_write_b128 v67, v[40:43] offset:14336
	ds_write_b128 v67, v[60:63] offset:15360
	s_bfe_u32 s3, s0, 0x10006
	s_addk_i32 s5, 0x4000
	v_lshlrev_b32_e32 v1, 2, v64
	v_or_b32_e32 v0, s5, v80
	v_lshl_or_b32 v1, s3, 4, v1
	v_or_b32_e32 v4, s1, v1
	v_ashrrev_i32_e32 v1, 31, v0
	v_lshlrev_b64 v[2:3], 12, v[0:1]
	s_ashr_i32 s5, s4, 31
	v_lshl_add_u64 v[2:3], s[8:9], 0, v[2:3]
	v_lshl_add_u64 v[2:3], s[4:5], 1, v[2:3]
	v_lshlrev_b32_e32 v128, 1, v4
	v_lshl_add_u64 v[14:15], v[2:3], 0, v[128:129]
	s_waitcnt lgkmcnt(0)
	s_barrier
	global_load_dwordx2 v[16:17], v[14:15], off
	global_load_dwordx2 v[18:19], v[14:15], off offset:256
	s_lshl_b32 s1, s3, 2
	s_add_i32 s1, s1, s10
	v_lshl_add_u32 v28, s1, 10, v66
	ds_read_b128 v[2:5], v28
	ds_read_b128 v[6:9], v28 offset:8192
	ds_read_b128 v[10:13], v28 offset:16384
	v_cmp_gt_u32_e32 vcc, 16, v65
	s_waitcnt lgkmcnt(0)
	v_pk_add_f32 v[20:21], v[4:5], 0 op_sel_hi:[1,0]
	v_pk_add_f32 v[22:23], v[2:3], 0 op_sel_hi:[1,0]
	ds_read_b128 v[2:5], v28 offset:24576
	v_pk_add_f32 v[24:25], v[8:9], 0 op_sel_hi:[1,0]
	v_pk_add_f32 v[26:27], v[6:7], 0 op_sel_hi:[1,0]
	ds_read_b128 v[6:9], v28 offset:32768
	v_pk_add_f32 v[22:23], v[22:23], v[10:11]
	s_waitcnt lgkmcnt(0)
	v_pk_add_f32 v[24:25], v[24:25], v[4:5]
	v_pk_add_f32 v[26:27], v[26:27], v[2:3]
	ds_read_b128 v[2:5], v28 offset:49152
	v_pk_add_f32 v[20:21], v[20:21], v[12:13]
	ds_read_b128 v[10:13], v28 offset:40960
	v_pk_add_f32 v[22:23], v[22:23], v[6:7]
	v_pk_add_f32 v[20:21], v[20:21], v[8:9]
	ds_read_b128 v[6:9], v28 offset:57344
	s_waitcnt lgkmcnt(0)
	v_pk_add_f32 v[22:23], v[22:23], v[2:3]
	v_add_u32_e32 v2, 0x10000, v28
	v_pk_add_f32 v[20:21], v[20:21], v[4:5]
	ds_read_b128 v[2:5], v2
	v_pk_add_f32 v[10:11], v[26:27], v[10:11]
	v_pk_add_f32 v[12:13], v[24:25], v[12:13]
	v_pk_add_f32 v[10:11], v[10:11], v[6:7]
	v_add_u32_e32 v6, 0x12000, v28
	v_pk_add_f32 v[12:13], v[12:13], v[8:9]
	ds_read_b128 v[6:9], v6
	s_waitcnt lgkmcnt(0)
	v_pk_add_f32 v[22:23], v[22:23], v[2:3]
	v_add_u32_e32 v2, 0x14000, v28
	v_pk_add_f32 v[20:21], v[20:21], v[4:5]
	ds_read_b128 v[2:5], v2
	v_pk_add_f32 v[10:11], v[10:11], v[6:7]
	v_add_u32_e32 v6, 0x16000, v28
	v_pk_add_f32 v[12:13], v[12:13], v[8:9]
	ds_read_b128 v[6:9], v6
	s_waitcnt lgkmcnt(0)
	v_pk_add_f32 v[22:23], v[22:23], v[2:3]
	v_add_u32_e32 v2, 0x18000, v28
	v_pk_add_f32 v[20:21], v[20:21], v[4:5]
	ds_read_b128 v[2:5], v2
	v_pk_add_f32 v[26:27], v[10:11], v[6:7]
	v_add_u32_e32 v6, 0x1a000, v28
	v_pk_add_f32 v[24:25], v[12:13], v[8:9]
	ds_read_b128 v[6:9], v6
	s_waitcnt lgkmcnt(0)
	v_pk_add_f32 v[22:23], v[22:23], v[2:3]
	v_add_u32_e32 v2, 0x1c000, v28
	v_add_u32_e32 v10, 0x1e000, v28
	v_pk_add_f32 v[20:21], v[20:21], v[4:5]
	ds_read_b128 v[2:5], v2
	ds_read_b128 v[10:13], v10
	v_pk_add_f32 v[6:7], v[26:27], v[6:7]
	v_pk_add_f32 v[8:9], v[24:25], v[8:9]
	s_waitcnt lgkmcnt(0)
	v_pk_add_f32 v[2:3], v[22:23], v[2:3]
	v_pk_add_f32 v[6:7], v[6:7], v[10:11]
	v_pk_add_f32 v[4:5], v[20:21], v[4:5]
	v_pk_add_f32 v[8:9], v[8:9], v[12:13]
	s_waitcnt vmcnt(0)
	v_lshlrev_b32_e32 v10, 16, v16
	v_and_b32_e32 v11, 0xffff0000, v16
	v_pk_add_f32 v[2:3], v[2:3], v[10:11]
	v_lshlrev_b32_e32 v10, 16, v18
	v_and_b32_e32 v11, 0xffff0000, v18
	v_lshlrev_b32_e32 v12, 16, v17
	v_and_b32_e32 v13, 0xffff0000, v17
	v_pk_add_f32 v[6:7], v[6:7], v[10:11]
	v_pk_add_f32 v[4:5], v[4:5], v[12:13]
	v_lshlrev_b32_e32 v12, 16, v19
	v_and_b32_e32 v13, 0xffff0000, v19
	v_mul_f32_e32 v10, v6, v6
	v_mul_f32_e32 v11, v7, v7
	v_pk_add_f32 v[8:9], v[8:9], v[12:13]
	v_fmac_f32_e32 v10, v2, v2
	v_fmac_f32_e32 v11, v3, v3
	v_add_f32_e32 v10, v10, v11
	v_mul_f32_e32 v11, v8, v8
	v_fmac_f32_e32 v11, v4, v4
	v_add_f32_e32 v10, v11, v10
	v_mul_f32_e32 v11, v9, v9
	v_fmac_f32_e32 v11, v5, v5
	v_add_f32_e32 v10, v11, v10
	ds_bpermute_b32 v11, v216, v10
	v_cvt_pk_bf16_f32 v2, v2, v3
	v_cvt_pk_bf16_f32 v3, v4, v5
	global_store_dwordx2 v[14:15], v[2:3], off
	v_cvt_pk_bf16_f32 v2, v6, v7
	s_waitcnt lgkmcnt(0)
	v_add_f32_e32 v4, v10, v11
	ds_bpermute_b32 v5, v217, v4
	v_cvt_pk_bf16_f32 v3, v8, v9
	global_store_dwordx2 v[14:15], v[2:3], off offset:256
	s_waitcnt lgkmcnt(0)
	v_add_f32_e32 v2, v4, v5
	s_and_saveexec_b64 s[4:5], vcc
	s_and_b32 s1, s0, 0xffffffc0
	s_add_i32 s1, s1, 0
	v_lshl_add_u32 v3, v80, 2, s1
	v_add_u32_e32 v3, 0x20100, v3
	ds_write_b32 v3, v2
	s_or_b64 exec, exec, s[4:5]
	v_or_b32_e32 v3, s3, v64
	v_cmp_eq_u32_e32 vcc, 0, v3
	s_waitcnt lgkmcnt(0)
	s_barrier
	s_and_saveexec_b64 s[4:5], vcc
	s_cbranch_execz .LBB0_802
	s_andn2_b32 s0, s0, 63
	s_add_i32 s0, s0, 0
	s_add_i32 s0, s0, 0x20100
	v_lshl_add_u32 v3, v80, 2, s0
	ds_read_b32 v3, v3 offset:64
	v_lshlrev_b64 v[0:1], 7, v[0:1]
	v_lshl_add_u64 v[0:1], s[6:7], 0, v[0:1]
	s_ashr_i32 s3, s2, 31
	v_lshl_add_u64 v[0:1], s[2:3], 2, v[0:1]
	s_waitcnt lgkmcnt(0)
	v_add_f32_e32 v2, v2, v3
	global_store_dword v[0:1], v2, off

.LBB0_884:
	v_add_co_u32_e32 v82, vcc, s84, v66
	s_nop 1
	v_addc_co_u32_e32 v83, vcc, 0, v67, vcc
	v_add_co_u32_e32 v130, vcc, s85, v66
	s_nop 1
	v_addc_co_u32_e32 v131, vcc, 0, v67, vcc
	v_add_co_u32_e32 v172, vcc, s88, v66
	s_nop 1
	v_addc_co_u32_e32 v173, vcc, 0, v67, vcc
	v_add_co_u32_e32 v174, vcc, s89, v66
	s_nop 1
	v_addc_co_u32_e32 v175, vcc, 0, v67, vcc
	v_add_co_u32_e32 v176, vcc, 0x8000, v64
	s_nop 1
	v_addc_co_u32_e32 v177, vcc, 0, v65, vcc
	v_add_co_u32_e32 v178, vcc, 0x18000, v64
	s_nop 1
	v_addc_co_u32_e32 v179, vcc, 0, v65, vcc
	v_add_co_u32_e32 v180, vcc, 0x88000, v64
	s_nop 1
	v_addc_co_u32_e32 v181, vcc, 0, v65, vcc
	v_add_co_u32_e32 v182, vcc, 0x98000, v64
	s_nop 1
	v_addc_co_u32_e32 v183, vcc, 0, v65, vcc
	global_load_dwordx4 v[68:71], v[82:83], off
	global_load_dwordx4 v[72:75], v[130:131], off
	global_load_dwordx4 v[76:79], v[172:173], off
	global_load_dwordx4 v[84:87], v[174:175], off
	global_load_dwordx4 v[88:91], v[176:177], off
	global_load_dwordx4 v[92:95], v[178:179], off
	global_load_dwordx4 v[96:99], v[180:181], off
	global_load_dwordx4 v[100:103], v[182:183], off
	global_load_dwordx4 v[104:107], v[82:83], off offset:64
	global_load_dwordx4 v[108:111], v[130:131], off offset:64
	global_load_dwordx4 v[112:115], v[172:173], off offset:64
	global_load_dwordx4 v[116:119], v[174:175], off offset:64
	global_load_dwordx4 v[120:123], v[176:177], off offset:64
	global_load_dwordx4 v[124:127], v[178:179], off offset:64
	global_load_dwordx4 v[132:135], v[180:181], off offset:64
	global_load_dwordx4 v[136:139], v[182:183], off offset:64
	global_load_dwordx4 v[140:143], v[82:83], off offset:128
	global_load_dwordx4 v[144:147], v[130:131], off offset:128
	global_load_dwordx4 v[148:151], v[172:173], off offset:128
	global_load_dwordx4 v[152:155], v[174:175], off offset:128
	global_load_dwordx4 v[156:159], v[176:177], off offset:128
	global_load_dwordx4 v[160:163], v[178:179], off offset:128
	global_load_dwordx4 v[164:167], v[180:181], off offset:128
	global_load_dwordx4 v[168:171], v[182:183], off offset:128
	s_waitcnt vmcnt(16)
	v_mfma_f32_16x16x32_bf16 v[56:59], v[88:91], v[68:71], 0
	v_mfma_f32_16x16x32_bf16 v[52:55], v[88:91], v[72:75], 0
	v_mfma_f32_16x16x32_bf16 v[48:51], v[88:91], v[76:79], 0
	v_mfma_f32_16x16x32_bf16 v[44:47], v[88:91], v[84:87], 0
	v_mfma_f32_16x16x32_bf16 v[12:15], v[92:95], v[68:71], 0
	v_mfma_f32_16x16x32_bf16 v[8:11], v[92:95], v[72:75], 0
	v_mfma_f32_16x16x32_bf16 v[4:7], v[92:95], v[76:79], 0
	v_mfma_f32_16x16x32_bf16 v[0:3], v[92:95], v[84:87], 0
	v_mfma_f32_16x16x32_bf16 v[16:19], v[96:99], v[68:71], 0
	v_mfma_f32_16x16x32_bf16 v[24:27], v[96:99], v[72:75], 0
	v_mfma_f32_16x16x32_bf16 v[28:31], v[96:99], v[76:79], 0
	v_mfma_f32_16x16x32_bf16 v[36:39], v[96:99], v[84:87], 0
	v_mfma_f32_16x16x32_bf16 v[20:23], v[100:103], v[68:71], 0
	v_mfma_f32_16x16x32_bf16 v[32:35], v[100:103], v[72:75], 0
	v_mfma_f32_16x16x32_bf16 v[40:43], v[100:103], v[76:79], 0
	v_mfma_f32_16x16x32_bf16 v[60:63], v[100:103], v[84:87], 0
	global_load_dwordx4 v[68:71], v[82:83], off offset:192
	global_load_dwordx4 v[72:75], v[130:131], off offset:192
	global_load_dwordx4 v[76:79], v[172:173], off offset:192
	global_load_dwordx4 v[84:87], v[174:175], off offset:192
	global_load_dwordx4 v[88:91], v[176:177], off offset:192
	global_load_dwordx4 v[92:95], v[178:179], off offset:192
	global_load_dwordx4 v[96:99], v[180:181], off offset:192
	global_load_dwordx4 v[100:103], v[182:183], off offset:192
	s_waitcnt vmcnt(16)
	v_mfma_f32_16x16x32_bf16 v[56:59], v[120:123], v[104:107], v[56:59]
	v_mfma_f32_16x16x32_bf16 v[52:55], v[120:123], v[108:111], v[52:55]
	v_mfma_f32_16x16x32_bf16 v[48:51], v[120:123], v[112:115], v[48:51]
	v_mfma_f32_16x16x32_bf16 v[44:47], v[120:123], v[116:119], v[44:47]
	v_mfma_f32_16x16x32_bf16 v[12:15], v[124:127], v[104:107], v[12:15]
	v_mfma_f32_16x16x32_bf16 v[8:11], v[124:127], v[108:111], v[8:11]
	v_mfma_f32_16x16x32_bf16 v[4:7], v[124:127], v[112:115], v[4:7]
	v_mfma_f32_16x16x32_bf16 v[0:3], v[124:127], v[116:119], v[0:3]
	v_mfma_f32_16x16x32_bf16 v[16:19], v[132:135], v[104:107], v[16:19]
	v_mfma_f32_16x16x32_bf16 v[24:27], v[132:135], v[108:111], v[24:27]
	v_mfma_f32_16x16x32_bf16 v[28:31], v[132:135], v[112:115], v[28:31]
	v_mfma_f32_16x16x32_bf16 v[36:39], v[132:135], v[116:119], v[36:39]
	v_mfma_f32_16x16x32_bf16 v[20:23], v[136:139], v[104:107], v[20:23]
	v_mfma_f32_16x16x32_bf16 v[32:35], v[136:139], v[108:111], v[32:35]
	v_mfma_f32_16x16x32_bf16 v[40:43], v[136:139], v[112:115], v[40:43]
	v_mfma_f32_16x16x32_bf16 v[60:63], v[136:139], v[116:119], v[60:63]
	global_load_dwordx4 v[104:107], v[82:83], off offset:256
	global_load_dwordx4 v[108:111], v[130:131], off offset:256
	global_load_dwordx4 v[112:115], v[172:173], off offset:256
	global_load_dwordx4 v[116:119], v[174:175], off offset:256
	global_load_dwordx4 v[120:123], v[176:177], off offset:256
	global_load_dwordx4 v[124:127], v[178:179], off offset:256
	global_load_dwordx4 v[132:135], v[180:181], off offset:256
	global_load_dwordx4 v[136:139], v[182:183], off offset:256
	s_waitcnt vmcnt(16)
	v_mfma_f32_16x16x32_bf16 v[56:59], v[156:159], v[140:143], v[56:59]
	v_mfma_f32_16x16x32_bf16 v[52:55], v[156:159], v[144:147], v[52:55]
	v_mfma_f32_16x16x32_bf16 v[48:51], v[156:159], v[148:151], v[48:51]
	v_mfma_f32_16x16x32_bf16 v[44:47], v[156:159], v[152:155], v[44:47]
	v_mfma_f32_16x16x32_bf16 v[12:15], v[160:163], v[140:143], v[12:15]
	v_mfma_f32_16x16x32_bf16 v[8:11], v[160:163], v[144:147], v[8:11]
	v_mfma_f32_16x16x32_bf16 v[4:7], v[160:163], v[148:151], v[4:7]
	v_mfma_f32_16x16x32_bf16 v[0:3], v[160:163], v[152:155], v[0:3]
	v_mfma_f32_16x16x32_bf16 v[16:19], v[164:167], v[140:143], v[16:19]
	v_mfma_f32_16x16x32_bf16 v[24:27], v[164:167], v[144:147], v[24:27]
	v_mfma_f32_16x16x32_bf16 v[28:31], v[164:167], v[148:151], v[28:31]
	v_mfma_f32_16x16x32_bf16 v[36:39], v[164:167], v[152:155], v[36:39]
	v_mfma_f32_16x16x32_bf16 v[20:23], v[168:171], v[140:143], v[20:23]
	v_mfma_f32_16x16x32_bf16 v[32:35], v[168:171], v[144:147], v[32:35]
	v_mfma_f32_16x16x32_bf16 v[40:43], v[168:171], v[148:151], v[40:43]
	v_mfma_f32_16x16x32_bf16 v[60:63], v[168:171], v[152:155], v[60:63]
	global_load_dwordx4 v[140:143], v[82:83], off offset:320
	global_load_dwordx4 v[144:147], v[130:131], off offset:320
	global_load_dwordx4 v[148:151], v[172:173], off offset:320
	global_load_dwordx4 v[152:155], v[174:175], off offset:320
	global_load_dwordx4 v[156:159], v[176:177], off offset:320
	global_load_dwordx4 v[160:163], v[178:179], off offset:320
	global_load_dwordx4 v[164:167], v[180:181], off offset:320
	global_load_dwordx4 v[168:171], v[182:183], off offset:320
	s_waitcnt vmcnt(16)
	v_mfma_f32_16x16x32_bf16 v[56:59], v[88:91], v[68:71], v[56:59]
	v_mfma_f32_16x16x32_bf16 v[52:55], v[88:91], v[72:75], v[52:55]
	v_mfma_f32_16x16x32_bf16 v[48:51], v[88:91], v[76:79], v[48:51]
	v_mfma_f32_16x16x32_bf16 v[44:47], v[88:91], v[84:87], v[44:47]
	v_mfma_f32_16x16x32_bf16 v[12:15], v[92:95], v[68:71], v[12:15]
	v_mfma_f32_16x16x32_bf16 v[8:11], v[92:95], v[72:75], v[8:11]
	v_mfma_f32_16x16x32_bf16 v[4:7], v[92:95], v[76:79], v[4:7]
	v_mfma_f32_16x16x32_bf16 v[0:3], v[92:95], v[84:87], v[0:3]
	v_mfma_f32_16x16x32_bf16 v[16:19], v[96:99], v[68:71], v[16:19]
	v_mfma_f32_16x16x32_bf16 v[24:27], v[96:99], v[72:75], v[24:27]
	v_mfma_f32_16x16x32_bf16 v[28:31], v[96:99], v[76:79], v[28:31]
	v_mfma_f32_16x16x32_bf16 v[36:39], v[96:99], v[84:87], v[36:39]
	v_mfma_f32_16x16x32_bf16 v[20:23], v[100:103], v[68:71], v[20:23]
	v_mfma_f32_16x16x32_bf16 v[32:35], v[100:103], v[72:75], v[32:35]
	v_mfma_f32_16x16x32_bf16 v[40:43], v[100:103], v[76:79], v[40:43]
	v_mfma_f32_16x16x32_bf16 v[60:63], v[100:103], v[84:87], v[60:63]
	global_load_dwordx4 v[68:71], v[82:83], off offset:384
	global_load_dwordx4 v[72:75], v[130:131], off offset:384
	global_load_dwordx4 v[76:79], v[172:173], off offset:384
	global_load_dwordx4 v[84:87], v[174:175], off offset:384
	global_load_dwordx4 v[88:91], v[176:177], off offset:384
	global_load_dwordx4 v[92:95], v[178:179], off offset:384
	global_load_dwordx4 v[96:99], v[180:181], off offset:384
	global_load_dwordx4 v[100:103], v[182:183], off offset:384
	s_waitcnt vmcnt(16)
	v_mfma_f32_16x16x32_bf16 v[56:59], v[120:123], v[104:107], v[56:59]
	v_mfma_f32_16x16x32_bf16 v[52:55], v[120:123], v[108:111], v[52:55]
	v_mfma_f32_16x16x32_bf16 v[48:51], v[120:123], v[112:115], v[48:51]
	v_mfma_f32_16x16x32_bf16 v[44:47], v[120:123], v[116:119], v[44:47]
	v_mfma_f32_16x16x32_bf16 v[12:15], v[124:127], v[104:107], v[12:15]
	v_mfma_f32_16x16x32_bf16 v[8:11], v[124:127], v[108:111], v[8:11]
	v_mfma_f32_16x16x32_bf16 v[4:7], v[124:127], v[112:115], v[4:7]
	v_mfma_f32_16x16x32_bf16 v[0:3], v[124:127], v[116:119], v[0:3]
	v_mfma_f32_16x16x32_bf16 v[16:19], v[132:135], v[104:107], v[16:19]
	v_mfma_f32_16x16x32_bf16 v[24:27], v[132:135], v[108:111], v[24:27]
	v_mfma_f32_16x16x32_bf16 v[28:31], v[132:135], v[112:115], v[28:31]
	v_mfma_f32_16x16x32_bf16 v[36:39], v[132:135], v[116:119], v[36:39]
	v_mfma_f32_16x16x32_bf16 v[20:23], v[136:139], v[104:107], v[20:23]
	v_mfma_f32_16x16x32_bf16 v[32:35], v[136:139], v[108:111], v[32:35]
	v_mfma_f32_16x16x32_bf16 v[40:43], v[136:139], v[112:115], v[40:43]
	v_mfma_f32_16x16x32_bf16 v[60:63], v[136:139], v[116:119], v[60:63]
	global_load_dwordx4 v[104:107], v[82:83], off offset:448
	global_load_dwordx4 v[108:111], v[130:131], off offset:448
	global_load_dwordx4 v[112:115], v[172:173], off offset:448
	global_load_dwordx4 v[116:119], v[174:175], off offset:448
	global_load_dwordx4 v[120:123], v[176:177], off offset:448
	global_load_dwordx4 v[124:127], v[178:179], off offset:448
	global_load_dwordx4 v[132:135], v[180:181], off offset:448
	global_load_dwordx4 v[136:139], v[182:183], off offset:448
	s_waitcnt vmcnt(16)
	v_mfma_f32_16x16x32_bf16 v[56:59], v[156:159], v[140:143], v[56:59]
	v_mfma_f32_16x16x32_bf16 v[52:55], v[156:159], v[144:147], v[52:55]
	v_mfma_f32_16x16x32_bf16 v[48:51], v[156:159], v[148:151], v[48:51]
	v_mfma_f32_16x16x32_bf16 v[44:47], v[156:159], v[152:155], v[44:47]
	v_mfma_f32_16x16x32_bf16 v[12:15], v[160:163], v[140:143], v[12:15]
	v_mfma_f32_16x16x32_bf16 v[8:11], v[160:163], v[144:147], v[8:11]
	v_mfma_f32_16x16x32_bf16 v[4:7], v[160:163], v[148:151], v[4:7]
	v_mfma_f32_16x16x32_bf16 v[0:3], v[160:163], v[152:155], v[0:3]
	v_mfma_f32_16x16x32_bf16 v[16:19], v[164:167], v[140:143], v[16:19]
	v_mfma_f32_16x16x32_bf16 v[24:27], v[164:167], v[144:147], v[24:27]
	v_mfma_f32_16x16x32_bf16 v[28:31], v[164:167], v[148:151], v[28:31]
	v_mfma_f32_16x16x32_bf16 v[36:39], v[164:167], v[152:155], v[36:39]
	v_mfma_f32_16x16x32_bf16 v[20:23], v[168:171], v[140:143], v[20:23]
	v_mfma_f32_16x16x32_bf16 v[32:35], v[168:171], v[144:147], v[32:35]
	v_mfma_f32_16x16x32_bf16 v[40:43], v[168:171], v[148:151], v[40:43]
	v_mfma_f32_16x16x32_bf16 v[60:63], v[168:171], v[152:155], v[60:63]
	s_waitcnt vmcnt(8)
	v_mfma_f32_16x16x32_bf16 v[56:59], v[88:91], v[68:71], v[56:59]
	v_mfma_f32_16x16x32_bf16 v[52:55], v[88:91], v[72:75], v[52:55]
	v_mfma_f32_16x16x32_bf16 v[48:51], v[88:91], v[76:79], v[48:51]
	v_mfma_f32_16x16x32_bf16 v[44:47], v[88:91], v[84:87], v[44:47]
	v_mfma_f32_16x16x32_bf16 v[12:15], v[92:95], v[68:71], v[12:15]
	v_mfma_f32_16x16x32_bf16 v[8:11], v[92:95], v[72:75], v[8:11]
	v_mfma_f32_16x16x32_bf16 v[4:7], v[92:95], v[76:79], v[4:7]
	v_mfma_f32_16x16x32_bf16 v[0:3], v[92:95], v[84:87], v[0:3]
	v_mfma_f32_16x16x32_bf16 v[16:19], v[96:99], v[68:71], v[16:19]
	v_mfma_f32_16x16x32_bf16 v[24:27], v[96:99], v[72:75], v[24:27]
	v_mfma_f32_16x16x32_bf16 v[28:31], v[96:99], v[76:79], v[28:31]
	v_mfma_f32_16x16x32_bf16 v[36:39], v[96:99], v[84:87], v[36:39]
	v_mfma_f32_16x16x32_bf16 v[20:23], v[100:103], v[68:71], v[20:23]
	v_mfma_f32_16x16x32_bf16 v[32:35], v[100:103], v[72:75], v[32:35]
	v_mfma_f32_16x16x32_bf16 v[40:43], v[100:103], v[76:79], v[40:43]
	v_mfma_f32_16x16x32_bf16 v[60:63], v[100:103], v[84:87], v[60:63]
	s_waitcnt vmcnt(0)
	v_mfma_f32_16x16x32_bf16 v[56:59], v[120:123], v[104:107], v[56:59]
	v_mfma_f32_16x16x32_bf16 v[52:55], v[120:123], v[108:111], v[52:55]
	v_mfma_f32_16x16x32_bf16 v[48:51], v[120:123], v[112:115], v[48:51]
	v_mfma_f32_16x16x32_bf16 v[44:47], v[120:123], v[116:119], v[44:47]
	v_mfma_f32_16x16x32_bf16 v[12:15], v[124:127], v[104:107], v[12:15]
	v_mfma_f32_16x16x32_bf16 v[8:11], v[124:127], v[108:111], v[8:11]
	v_mfma_f32_16x16x32_bf16 v[4:7], v[124:127], v[112:115], v[4:7]
	v_mfma_f32_16x16x32_bf16 v[0:3], v[124:127], v[116:119], v[0:3]
	v_mfma_f32_16x16x32_bf16 v[16:19], v[132:135], v[104:107], v[16:19]
	v_mfma_f32_16x16x32_bf16 v[24:27], v[132:135], v[108:111], v[24:27]
	v_mfma_f32_16x16x32_bf16 v[28:31], v[132:135], v[112:115], v[28:31]
	v_mfma_f32_16x16x32_bf16 v[36:39], v[132:135], v[116:119], v[36:39]
	v_mfma_f32_16x16x32_bf16 v[20:23], v[136:139], v[104:107], v[20:23]
	v_mfma_f32_16x16x32_bf16 v[32:35], v[136:139], v[108:111], v[32:35]
	v_mfma_f32_16x16x32_bf16 v[40:43], v[136:139], v[112:115], v[40:43]
	v_mfma_f32_16x16x32_bf16 v[60:63], v[136:139], v[116:119], v[60:63]
	s_nop 7
	s_nop 3
	v_and_b32_e32 v65, 63, v81
	s_ashr_i32 s4, s3, 7
	v_lshl_add_u32 v65, v65, 4, 0
	s_lshl_b32 s5, s4, 4
	v_lshl_add_u32 v66, s14, 14, v65
	s_addk_i32 s5, 0x4000
	ds_write_b128 v66, v[56:59]
	ds_write_b128 v66, v[52:55] offset:1024
	ds_write_b128 v66, v[48:51] offset:2048
	ds_write_b128 v66, v[44:47] offset:3072
	ds_write_b128 v66, v[12:15] offset:4096
	ds_write_b128 v66, v[8:11] offset:5120
	ds_write_b128 v66, v[4:7] offset:6144
	ds_write_b128 v66, v[0:3] offset:7168
	ds_write_b128 v66, v[16:19] offset:8192
	ds_write_b128 v66, v[24:27] offset:9216
	ds_write_b128 v66, v[28:31] offset:10240
	ds_write_b128 v66, v[36:39] offset:11264
	ds_write_b128 v66, v[20:23] offset:12288
	ds_write_b128 v66, v[32:35] offset:13312
	ds_write_b128 v66, v[40:43] offset:14336
	ds_write_b128 v66, v[60:63] offset:15360
	v_or_b32_e32 v0, s5, v80
	v_ashrrev_i32_e32 v1, 31, v0
	v_bfe_u32 v64, v81, 4, 2
	v_lshlrev_b64 v[2:3], 7, v[0:1]
	v_lshl_add_u64 v[2:3], s[10:11], 0, v[2:3]
	v_lshlrev_b32_e32 v128, 5, v64
	v_lshl_add_u64 v[6:7], v[2:3], 0, v[128:129]
	s_waitcnt lgkmcnt(0)
	s_barrier
	global_load_dwordx4 v[2:5], v[6:7], off
	s_nop 0
	global_load_dwordx4 v[6:9], v[6:7], off offset:16
	s_bfe_u32 s3, s3, 0x10006
	s_lshl_b32 s5, s3, 2
	s_add_i32 s5, s5, s4
	v_lshl_add_u32 v62, s5, 10, v65
	ds_read_b128 v[10:13], v62
	ds_read_b128 v[14:17], v62 offset:8192
	ds_read_b128 v[18:21], v62 offset:16384
	ds_read_b128 v[22:25], v62 offset:24576
	ds_read_b128 v[26:29], v62 offset:32768
	ds_read_b128 v[30:33], v62 offset:40960
	ds_read_b128 v[34:37], v62 offset:49152
	ds_read_b128 v[38:41], v62 offset:57344
	s_waitcnt lgkmcnt(0)
	v_pk_add_f32 v[10:11], v[10:11], 0 op_sel_hi:[1,0]
	v_add_u32_e32 v42, 0x10000, v62
	v_add_u32_e32 v46, 0x12000, v62
	v_add_u32_e32 v50, 0x14000, v62
	v_add_u32_e32 v54, 0x16000, v62
	v_add_u32_e32 v58, 0x18000, v62
	v_pk_add_f32 v[10:11], v[10:11], v[18:19]
	v_add_u32_e32 v63, 0x1a000, v62
	ds_read_b128 v[42:45], v42
	ds_read_b128 v[46:49], v46
	ds_read_b128 v[50:53], v50
	ds_read_b128 v[54:57], v54
	ds_read_b128 v[58:61], v58
	ds_read_b128 v[66:69], v63
	v_pk_add_f32 v[10:11], v[10:11], v[26:27]
	v_pk_add_f32 v[12:13], v[12:13], 0 op_sel_hi:[1,0]
	v_pk_add_f32 v[10:11], v[10:11], v[34:35]
	v_pk_add_f32 v[12:13], v[12:13], v[20:21]
	s_waitcnt lgkmcnt(0)
	v_pk_add_f32 v[10:11], v[10:11], v[42:43]
	v_pk_add_f32 v[14:15], v[14:15], 0 op_sel_hi:[1,0]
	v_pk_add_f32 v[10:11], v[10:11], v[50:51]
	v_pk_add_f32 v[14:15], v[14:15], v[22:23]
	v_pk_add_f32 v[20:21], v[10:11], v[58:59]
	v_pk_add_f32 v[12:13], v[12:13], v[28:29]
	v_pk_add_f32 v[14:15], v[14:15], v[30:31]
	v_pk_add_f32 v[12:13], v[12:13], v[36:37]
	v_pk_add_f32 v[14:15], v[14:15], v[38:39]
	v_pk_add_f32 v[12:13], v[12:13], v[44:45]
	v_pk_add_f32 v[14:15], v[14:15], v[46:47]
	v_pk_add_f32 v[12:13], v[12:13], v[52:53]
	v_pk_add_f32 v[14:15], v[14:15], v[54:55]
	v_pk_add_f32 v[18:19], v[12:13], v[60:61]
	v_pk_add_f32 v[14:15], v[14:15], v[66:67]
	v_pk_add_f32 v[16:17], v[16:17], 0 op_sel_hi:[1,0]
	s_mov_b64 s[4:5], -1
	v_pk_add_f32 v[16:17], v[16:17], v[24:25]
	s_cmp_gt_i32 s0, 7
	v_pk_add_f32 v[16:17], v[16:17], v[32:33]
	v_lshlrev_b64 v[0:1], 12, v[0:1]
	v_pk_add_f32 v[16:17], v[16:17], v[40:41]
	s_waitcnt vmcnt(0)
	v_mov_b32_e32 v10, v2
	v_mov_b32_e32 v11, v6
	v_mov_b32_e32 v6, v3
	v_pk_add_f32 v[2:3], v[10:11], v[6:7]
	v_mov_b32_e32 v6, v4
	v_mov_b32_e32 v7, v8
	v_mov_b32_e32 v8, v5
	v_pk_add_f32 v[4:5], v[6:7], v[8:9]
	v_add_u32_e32 v9, 0x1e000, v62
	v_pk_add_f32 v[2:3], v[2:3], v[4:5]
	v_pk_add_f32 v[16:17], v[16:17], v[48:49]
	v_add_f32_e32 v6, v2, v3
	v_and_b32_e32 v3, 64, v214
	v_xor_b32_e32 v2, 16, v214
	v_add_u32_e32 v7, 64, v3
	v_cmp_lt_i32_e32 vcc, v2, v7
	v_pk_add_f32 v[16:17], v[16:17], v[56:57]
	s_nop 0
	v_cndmask_b32_e32 v2, v214, v2, vcc
	v_lshlrev_b32_e32 v2, 2, v2
	ds_bpermute_b32 v8, v2, v6
	v_add_u32_e32 v2, 0x1c000, v62
	ds_read_b128 v[2:5], v2
	ds_read_b128 v[10:13], v9
	v_pk_add_f32 v[16:17], v[16:17], v[68:69]
	s_waitcnt lgkmcnt(2)
	v_add_f32_e32 v22, v6, v8
	v_xor_b32_e32 v6, 32, v214
	v_cmp_lt_i32_e32 vcc, v6, v7
	s_waitcnt lgkmcnt(1)
	v_pk_add_f32 v[8:9], v[20:21], v[2:3]
	s_waitcnt lgkmcnt(0)
	v_pk_add_f32 v[2:3], v[16:17], v[12:13]
	v_cndmask_b32_e32 v6, v214, v6, vcc
	v_lshlrev_b32_e32 v6, 2, v6
	ds_bpermute_b32 v23, v6, v22
	v_pk_add_f32 v[6:7], v[18:19], v[4:5]
	v_pk_add_f32 v[4:5], v[14:15], v[10:11]
	s_waitcnt lgkmcnt(0)
	v_add_f32_e32 v10, v22, v23
	v_fmamk_f32 v10, v10, 0x3a000000, v190
	v_mul_f32_e32 v11, 0x4b800000, v10
	v_cmp_gt_f32_e32 vcc, s70, v10
	s_nop 1
	v_cndmask_b32_e32 v10, v10, v11, vcc
	v_rsq_f32_e32 v10, v10
	v_lshlrev_b32_e32 v11, 2, v64
	v_lshl_or_b32 v11, s3, 4, v11
	v_or_b32_e32 v11, s1, v11
	v_mul_f32_e32 v12, 0x45800000, v10
	v_cndmask_b32_e32 v10, v10, v12, vcc
	v_lshlrev_b32_e32 v128, 1, v11
	s_cbranch_scc0 .LBB0_887
	v_pk_mul_f32 v[12:13], v[6:7], v[2:3]
	v_pk_mul_f32 v[14:15], v[8:9], v[4:5]
	v_mul_f32_e32 v16, v10, v10
	v_pk_mul_f32 v[12:13], v[12:13], v[16:17] op_sel_hi:[1,0]
	v_pk_mul_f32 v[14:15], v[14:15], v[16:17] op_sel_hi:[1,0]
	s_mov_b32 s3, s95
	v_cvt_pk_bf16_f32 v14, v14, v15
	v_cvt_pk_bf16_f32 v15, v12, v13
	v_lshl_add_u64 v[12:13], s[8:9], 0, v[0:1]
	v_lshl_add_u64 v[12:13], v[12:13], 0, s[2:3]
	v_lshl_add_u64 v[12:13], v[12:13], 0, v[128:129]
	v_add_co_u32_e32 v12, vcc, 0xfffff800, v12
	s_mov_b64 s[4:5], 0
	s_nop 0
	v_addc_co_u32_e32 v13, vcc, -1, v13, vcc
	global_store_dwordx2 v[12:13], v[14:15], off

.LBB0_1031:
	v_add_co_u32_e32 v82, vcc, 0x3b1d0000, v66
	s_nop 1
	v_addc_co_u32_e32 v83, vcc, 0, v67, vcc
	v_add_co_u32_e32 v130, vcc, 0x3b1e0000, v66
	s_nop 1
	v_addc_co_u32_e32 v131, vcc, 0, v67, vcc
	v_add_co_u32_e32 v172, vcc, 0x3b1f0000, v66
	s_nop 1
	v_addc_co_u32_e32 v173, vcc, 0, v67, vcc
	v_add_co_u32_e32 v174, vcc, 0x3b200000, v66
	s_nop 1
	v_addc_co_u32_e32 v175, vcc, 0, v67, vcc
	v_add_co_u32_e32 v176, vcc, 0x3008000, v64
	s_nop 1
	v_addc_co_u32_e32 v177, vcc, 0, v65, vcc
	v_add_co_u32_e32 v178, vcc, 0x3018000, v64
	s_nop 1
	v_addc_co_u32_e32 v179, vcc, 0, v65, vcc
	v_add_co_u32_e32 v180, vcc, 0x3088000, v64
	s_nop 1
	v_addc_co_u32_e32 v181, vcc, 0, v65, vcc
	v_add_co_u32_e32 v182, vcc, 0x3098000, v64
	s_nop 1
	v_addc_co_u32_e32 v183, vcc, 0, v65, vcc
	global_load_dwordx4 v[68:71], v[82:83], off
	global_load_dwordx4 v[72:75], v[130:131], off
	global_load_dwordx4 v[76:79], v[172:173], off
	global_load_dwordx4 v[84:87], v[174:175], off
	global_load_dwordx4 v[88:91], v[176:177], off
	global_load_dwordx4 v[92:95], v[178:179], off
	global_load_dwordx4 v[96:99], v[180:181], off
	global_load_dwordx4 v[100:103], v[182:183], off
	global_load_dwordx4 v[104:107], v[82:83], off offset:64
	global_load_dwordx4 v[108:111], v[130:131], off offset:64
	global_load_dwordx4 v[112:115], v[172:173], off offset:64
	global_load_dwordx4 v[116:119], v[174:175], off offset:64
	global_load_dwordx4 v[120:123], v[176:177], off offset:64
	global_load_dwordx4 v[124:127], v[178:179], off offset:64
	global_load_dwordx4 v[132:135], v[180:181], off offset:64
	global_load_dwordx4 v[136:139], v[182:183], off offset:64
	global_load_dwordx4 v[140:143], v[82:83], off offset:128
	global_load_dwordx4 v[144:147], v[130:131], off offset:128
	global_load_dwordx4 v[148:151], v[172:173], off offset:128
	global_load_dwordx4 v[152:155], v[174:175], off offset:128
	global_load_dwordx4 v[156:159], v[176:177], off offset:128
	global_load_dwordx4 v[160:163], v[178:179], off offset:128
	global_load_dwordx4 v[164:167], v[180:181], off offset:128
	global_load_dwordx4 v[168:171], v[182:183], off offset:128
	s_waitcnt vmcnt(16)
	v_mfma_f32_16x16x32_bf16 v[56:59], v[88:91], v[68:71], 0
	v_mfma_f32_16x16x32_bf16 v[52:55], v[88:91], v[72:75], 0
	v_mfma_f32_16x16x32_bf16 v[48:51], v[88:91], v[76:79], 0
	v_mfma_f32_16x16x32_bf16 v[44:47], v[88:91], v[84:87], 0
	v_mfma_f32_16x16x32_bf16 v[12:15], v[92:95], v[68:71], 0
	v_mfma_f32_16x16x32_bf16 v[8:11], v[92:95], v[72:75], 0
	v_mfma_f32_16x16x32_bf16 v[4:7], v[92:95], v[76:79], 0
	v_mfma_f32_16x16x32_bf16 v[0:3], v[92:95], v[84:87], 0
	v_mfma_f32_16x16x32_bf16 v[16:19], v[96:99], v[68:71], 0
	v_mfma_f32_16x16x32_bf16 v[24:27], v[96:99], v[72:75], 0
	v_mfma_f32_16x16x32_bf16 v[28:31], v[96:99], v[76:79], 0
	v_mfma_f32_16x16x32_bf16 v[36:39], v[96:99], v[84:87], 0
	v_mfma_f32_16x16x32_bf16 v[20:23], v[100:103], v[68:71], 0
	v_mfma_f32_16x16x32_bf16 v[32:35], v[100:103], v[72:75], 0
	v_mfma_f32_16x16x32_bf16 v[40:43], v[100:103], v[76:79], 0
	v_mfma_f32_16x16x32_bf16 v[60:63], v[100:103], v[84:87], 0
	global_load_dwordx4 v[68:71], v[82:83], off offset:192
	global_load_dwordx4 v[72:75], v[130:131], off offset:192
	global_load_dwordx4 v[76:79], v[172:173], off offset:192
	global_load_dwordx4 v[84:87], v[174:175], off offset:192
	global_load_dwordx4 v[88:91], v[176:177], off offset:192
	global_load_dwordx4 v[92:95], v[178:179], off offset:192
	global_load_dwordx4 v[96:99], v[180:181], off offset:192
	global_load_dwordx4 v[100:103], v[182:183], off offset:192
	s_waitcnt vmcnt(16)
	v_mfma_f32_16x16x32_bf16 v[56:59], v[120:123], v[104:107], v[56:59]
	v_mfma_f32_16x16x32_bf16 v[52:55], v[120:123], v[108:111], v[52:55]
	v_mfma_f32_16x16x32_bf16 v[48:51], v[120:123], v[112:115], v[48:51]
	v_mfma_f32_16x16x32_bf16 v[44:47], v[120:123], v[116:119], v[44:47]
	v_mfma_f32_16x16x32_bf16 v[12:15], v[124:127], v[104:107], v[12:15]
	v_mfma_f32_16x16x32_bf16 v[8:11], v[124:127], v[108:111], v[8:11]
	v_mfma_f32_16x16x32_bf16 v[4:7], v[124:127], v[112:115], v[4:7]
	v_mfma_f32_16x16x32_bf16 v[0:3], v[124:127], v[116:119], v[0:3]
	v_mfma_f32_16x16x32_bf16 v[16:19], v[132:135], v[104:107], v[16:19]
	v_mfma_f32_16x16x32_bf16 v[24:27], v[132:135], v[108:111], v[24:27]
	v_mfma_f32_16x16x32_bf16 v[28:31], v[132:135], v[112:115], v[28:31]
	v_mfma_f32_16x16x32_bf16 v[36:39], v[132:135], v[116:119], v[36:39]
	v_mfma_f32_16x16x32_bf16 v[20:23], v[136:139], v[104:107], v[20:23]
	v_mfma_f32_16x16x32_bf16 v[32:35], v[136:139], v[108:111], v[32:35]
	v_mfma_f32_16x16x32_bf16 v[40:43], v[136:139], v[112:115], v[40:43]
	v_mfma_f32_16x16x32_bf16 v[60:63], v[136:139], v[116:119], v[60:63]
	global_load_dwordx4 v[104:107], v[82:83], off offset:256
	global_load_dwordx4 v[108:111], v[130:131], off offset:256
	global_load_dwordx4 v[112:115], v[172:173], off offset:256
	global_load_dwordx4 v[116:119], v[174:175], off offset:256
	global_load_dwordx4 v[120:123], v[176:177], off offset:256
	global_load_dwordx4 v[124:127], v[178:179], off offset:256
	global_load_dwordx4 v[132:135], v[180:181], off offset:256
	global_load_dwordx4 v[136:139], v[182:183], off offset:256
	s_waitcnt vmcnt(16)
	v_mfma_f32_16x16x32_bf16 v[56:59], v[156:159], v[140:143], v[56:59]
	v_mfma_f32_16x16x32_bf16 v[52:55], v[156:159], v[144:147], v[52:55]
	v_mfma_f32_16x16x32_bf16 v[48:51], v[156:159], v[148:151], v[48:51]
	v_mfma_f32_16x16x32_bf16 v[44:47], v[156:159], v[152:155], v[44:47]
	v_mfma_f32_16x16x32_bf16 v[12:15], v[160:163], v[140:143], v[12:15]
	v_mfma_f32_16x16x32_bf16 v[8:11], v[160:163], v[144:147], v[8:11]
	v_mfma_f32_16x16x32_bf16 v[4:7], v[160:163], v[148:151], v[4:7]
	v_mfma_f32_16x16x32_bf16 v[0:3], v[160:163], v[152:155], v[0:3]
	v_mfma_f32_16x16x32_bf16 v[16:19], v[164:167], v[140:143], v[16:19]
	v_mfma_f32_16x16x32_bf16 v[24:27], v[164:167], v[144:147], v[24:27]
	v_mfma_f32_16x16x32_bf16 v[28:31], v[164:167], v[148:151], v[28:31]
	v_mfma_f32_16x16x32_bf16 v[36:39], v[164:167], v[152:155], v[36:39]
	v_mfma_f32_16x16x32_bf16 v[20:23], v[168:171], v[140:143], v[20:23]
	v_mfma_f32_16x16x32_bf16 v[32:35], v[168:171], v[144:147], v[32:35]
	v_mfma_f32_16x16x32_bf16 v[40:43], v[168:171], v[148:151], v[40:43]
	v_mfma_f32_16x16x32_bf16 v[60:63], v[168:171], v[152:155], v[60:63]
	global_load_dwordx4 v[140:143], v[82:83], off offset:320
	global_load_dwordx4 v[144:147], v[130:131], off offset:320
	global_load_dwordx4 v[148:151], v[172:173], off offset:320
	global_load_dwordx4 v[152:155], v[174:175], off offset:320
	global_load_dwordx4 v[156:159], v[176:177], off offset:320
	global_load_dwordx4 v[160:163], v[178:179], off offset:320
	global_load_dwordx4 v[164:167], v[180:181], off offset:320
	global_load_dwordx4 v[168:171], v[182:183], off offset:320
	s_waitcnt vmcnt(16)
	v_mfma_f32_16x16x32_bf16 v[56:59], v[88:91], v[68:71], v[56:59]
	v_mfma_f32_16x16x32_bf16 v[52:55], v[88:91], v[72:75], v[52:55]
	v_mfma_f32_16x16x32_bf16 v[48:51], v[88:91], v[76:79], v[48:51]
	v_mfma_f32_16x16x32_bf16 v[44:47], v[88:91], v[84:87], v[44:47]
	v_mfma_f32_16x16x32_bf16 v[12:15], v[92:95], v[68:71], v[12:15]
	v_mfma_f32_16x16x32_bf16 v[8:11], v[92:95], v[72:75], v[8:11]
	v_mfma_f32_16x16x32_bf16 v[4:7], v[92:95], v[76:79], v[4:7]
	v_mfma_f32_16x16x32_bf16 v[0:3], v[92:95], v[84:87], v[0:3]
	v_mfma_f32_16x16x32_bf16 v[16:19], v[96:99], v[68:71], v[16:19]
	v_mfma_f32_16x16x32_bf16 v[24:27], v[96:99], v[72:75], v[24:27]
	v_mfma_f32_16x16x32_bf16 v[28:31], v[96:99], v[76:79], v[28:31]
	v_mfma_f32_16x16x32_bf16 v[36:39], v[96:99], v[84:87], v[36:39]
	v_mfma_f32_16x16x32_bf16 v[20:23], v[100:103], v[68:71], v[20:23]
	v_mfma_f32_16x16x32_bf16 v[32:35], v[100:103], v[72:75], v[32:35]
	v_mfma_f32_16x16x32_bf16 v[40:43], v[100:103], v[76:79], v[40:43]
	v_mfma_f32_16x16x32_bf16 v[60:63], v[100:103], v[84:87], v[60:63]
	global_load_dwordx4 v[68:71], v[82:83], off offset:384
	global_load_dwordx4 v[72:75], v[130:131], off offset:384
	global_load_dwordx4 v[76:79], v[172:173], off offset:384
	global_load_dwordx4 v[84:87], v[174:175], off offset:384
	global_load_dwordx4 v[88:91], v[176:177], off offset:384
	global_load_dwordx4 v[92:95], v[178:179], off offset:384
	global_load_dwordx4 v[96:99], v[180:181], off offset:384
	global_load_dwordx4 v[100:103], v[182:183], off offset:384
	s_waitcnt vmcnt(16)
	v_mfma_f32_16x16x32_bf16 v[56:59], v[120:123], v[104:107], v[56:59]
	v_mfma_f32_16x16x32_bf16 v[52:55], v[120:123], v[108:111], v[52:55]
	v_mfma_f32_16x16x32_bf16 v[48:51], v[120:123], v[112:115], v[48:51]
	v_mfma_f32_16x16x32_bf16 v[44:47], v[120:123], v[116:119], v[44:47]
	v_mfma_f32_16x16x32_bf16 v[12:15], v[124:127], v[104:107], v[12:15]
	v_mfma_f32_16x16x32_bf16 v[8:11], v[124:127], v[108:111], v[8:11]
	v_mfma_f32_16x16x32_bf16 v[4:7], v[124:127], v[112:115], v[4:7]
	v_mfma_f32_16x16x32_bf16 v[0:3], v[124:127], v[116:119], v[0:3]
	v_mfma_f32_16x16x32_bf16 v[16:19], v[132:135], v[104:107], v[16:19]
	v_mfma_f32_16x16x32_bf16 v[24:27], v[132:135], v[108:111], v[24:27]
	v_mfma_f32_16x16x32_bf16 v[28:31], v[132:135], v[112:115], v[28:31]
	v_mfma_f32_16x16x32_bf16 v[36:39], v[132:135], v[116:119], v[36:39]
	v_mfma_f32_16x16x32_bf16 v[20:23], v[136:139], v[104:107], v[20:23]
	v_mfma_f32_16x16x32_bf16 v[32:35], v[136:139], v[108:111], v[32:35]
	v_mfma_f32_16x16x32_bf16 v[40:43], v[136:139], v[112:115], v[40:43]
	v_mfma_f32_16x16x32_bf16 v[60:63], v[136:139], v[116:119], v[60:63]
	global_load_dwordx4 v[104:107], v[82:83], off offset:448
	global_load_dwordx4 v[108:111], v[130:131], off offset:448
	global_load_dwordx4 v[112:115], v[172:173], off offset:448
	global_load_dwordx4 v[116:119], v[174:175], off offset:448
	global_load_dwordx4 v[120:123], v[176:177], off offset:448
	global_load_dwordx4 v[124:127], v[178:179], off offset:448
	global_load_dwordx4 v[132:135], v[180:181], off offset:448
	global_load_dwordx4 v[136:139], v[182:183], off offset:448
	s_waitcnt vmcnt(16)
	v_mfma_f32_16x16x32_bf16 v[56:59], v[156:159], v[140:143], v[56:59]
	v_mfma_f32_16x16x32_bf16 v[52:55], v[156:159], v[144:147], v[52:55]
	v_mfma_f32_16x16x32_bf16 v[48:51], v[156:159], v[148:151], v[48:51]
	v_mfma_f32_16x16x32_bf16 v[44:47], v[156:159], v[152:155], v[44:47]
	v_mfma_f32_16x16x32_bf16 v[12:15], v[160:163], v[140:143], v[12:15]
	v_mfma_f32_16x16x32_bf16 v[8:11], v[160:163], v[144:147], v[8:11]
	v_mfma_f32_16x16x32_bf16 v[4:7], v[160:163], v[148:151], v[4:7]
	v_mfma_f32_16x16x32_bf16 v[0:3], v[160:163], v[152:155], v[0:3]
	v_mfma_f32_16x16x32_bf16 v[16:19], v[164:167], v[140:143], v[16:19]
	v_mfma_f32_16x16x32_bf16 v[24:27], v[164:167], v[144:147], v[24:27]
	v_mfma_f32_16x16x32_bf16 v[28:31], v[164:167], v[148:151], v[28:31]
	v_mfma_f32_16x16x32_bf16 v[36:39], v[164:167], v[152:155], v[36:39]
	v_mfma_f32_16x16x32_bf16 v[20:23], v[168:171], v[140:143], v[20:23]
	v_mfma_f32_16x16x32_bf16 v[32:35], v[168:171], v[144:147], v[32:35]
	v_mfma_f32_16x16x32_bf16 v[40:43], v[168:171], v[148:151], v[40:43]
	v_mfma_f32_16x16x32_bf16 v[60:63], v[168:171], v[152:155], v[60:63]
	s_waitcnt vmcnt(8)
	v_mfma_f32_16x16x32_bf16 v[56:59], v[88:91], v[68:71], v[56:59]
	v_mfma_f32_16x16x32_bf16 v[52:55], v[88:91], v[72:75], v[52:55]
	v_mfma_f32_16x16x32_bf16 v[48:51], v[88:91], v[76:79], v[48:51]
	v_mfma_f32_16x16x32_bf16 v[44:47], v[88:91], v[84:87], v[44:47]
	v_mfma_f32_16x16x32_bf16 v[12:15], v[92:95], v[68:71], v[12:15]
	v_mfma_f32_16x16x32_bf16 v[8:11], v[92:95], v[72:75], v[8:11]
	v_mfma_f32_16x16x32_bf16 v[4:7], v[92:95], v[76:79], v[4:7]
	v_mfma_f32_16x16x32_bf16 v[0:3], v[92:95], v[84:87], v[0:3]
	v_mfma_f32_16x16x32_bf16 v[16:19], v[96:99], v[68:71], v[16:19]
	v_mfma_f32_16x16x32_bf16 v[24:27], v[96:99], v[72:75], v[24:27]
	v_mfma_f32_16x16x32_bf16 v[28:31], v[96:99], v[76:79], v[28:31]
	v_mfma_f32_16x16x32_bf16 v[36:39], v[96:99], v[84:87], v[36:39]
	v_mfma_f32_16x16x32_bf16 v[20:23], v[100:103], v[68:71], v[20:23]
	v_mfma_f32_16x16x32_bf16 v[32:35], v[100:103], v[72:75], v[32:35]
	v_mfma_f32_16x16x32_bf16 v[40:43], v[100:103], v[76:79], v[40:43]
	v_mfma_f32_16x16x32_bf16 v[60:63], v[100:103], v[84:87], v[60:63]
	s_waitcnt vmcnt(0)
	v_mfma_f32_16x16x32_bf16 v[56:59], v[120:123], v[104:107], v[56:59]
	v_mfma_f32_16x16x32_bf16 v[52:55], v[120:123], v[108:111], v[52:55]
	v_mfma_f32_16x16x32_bf16 v[48:51], v[120:123], v[112:115], v[48:51]
	v_mfma_f32_16x16x32_bf16 v[44:47], v[120:123], v[116:119], v[44:47]
	v_mfma_f32_16x16x32_bf16 v[12:15], v[124:127], v[104:107], v[12:15]
	v_mfma_f32_16x16x32_bf16 v[8:11], v[124:127], v[108:111], v[8:11]
	v_mfma_f32_16x16x32_bf16 v[4:7], v[124:127], v[112:115], v[4:7]
	v_mfma_f32_16x16x32_bf16 v[0:3], v[124:127], v[116:119], v[0:3]
	v_mfma_f32_16x16x32_bf16 v[16:19], v[132:135], v[104:107], v[16:19]
	v_mfma_f32_16x16x32_bf16 v[24:27], v[132:135], v[108:111], v[24:27]
	v_mfma_f32_16x16x32_bf16 v[28:31], v[132:135], v[112:115], v[28:31]
	v_mfma_f32_16x16x32_bf16 v[36:39], v[132:135], v[116:119], v[36:39]
	v_mfma_f32_16x16x32_bf16 v[20:23], v[136:139], v[104:107], v[20:23]
	v_mfma_f32_16x16x32_bf16 v[32:35], v[136:139], v[108:111], v[32:35]
	v_mfma_f32_16x16x32_bf16 v[40:43], v[136:139], v[112:115], v[40:43]
	v_mfma_f32_16x16x32_bf16 v[60:63], v[136:139], v[116:119], v[60:63]
	s_nop 7
	s_nop 3
	v_and_b32_e32 v65, 63, v81
	v_lshl_add_u32 v66, v65, 4, 0
	s_ashr_i32 s10, s0, 7
	v_bfe_u32 v64, v81, 4, 2
	v_lshl_add_u32 v67, s3, 14, v66
	s_lshl_b32 s5, s10, 4
	ds_write_b128 v67, v[56:59]
	ds_write_b128 v67, v[52:55] offset:1024
	ds_write_b128 v67, v[48:51] offset:2048
	ds_write_b128 v67, v[44:47] offset:3072
	ds_write_b128 v67, v[12:15] offset:4096
	ds_write_b128 v67, v[8:11] offset:5120
	ds_write_b128 v67, v[4:7] offset:6144
	ds_write_b128 v67, v[0:3] offset:7168
	ds_write_b128 v67, v[16:19] offset:8192
	ds_write_b128 v67, v[24:27] offset:9216
	ds_write_b128 v67, v[28:31] offset:10240
	ds_write_b128 v67, v[36:39] offset:11264
	ds_write_b128 v67, v[20:23] offset:12288
	ds_write_b128 v67, v[32:35] offset:13312
	ds_write_b128 v67, v[40:43] offset:14336
	ds_write_b128 v67, v[60:63] offset:15360
	s_bfe_u32 s3, s0, 0x10006
	s_addk_i32 s5, 0x4000
	v_lshlrev_b32_e32 v1, 2, v64
	v_or_b32_e32 v0, s5, v80
	v_lshl_or_b32 v1, s3, 4, v1
	v_or_b32_e32 v4, s1, v1
	v_ashrrev_i32_e32 v1, 31, v0
	v_lshlrev_b64 v[2:3], 12, v[0:1]
	s_ashr_i32 s5, s4, 31
	v_lshl_add_u64 v[2:3], s[8:9], 0, v[2:3]
	v_lshl_add_u64 v[2:3], s[4:5], 1, v[2:3]
	v_lshlrev_b32_e32 v128, 1, v4
	v_lshl_add_u64 v[14:15], v[2:3], 0, v[128:129]
	s_waitcnt lgkmcnt(0)
	s_barrier
	global_load_dwordx2 v[16:17], v[14:15], off
	global_load_dwordx2 v[18:19], v[14:15], off offset:256
	s_lshl_b32 s1, s3, 2
	s_add_i32 s1, s1, s10
	v_lshl_add_u32 v28, s1, 10, v66
	ds_read_b128 v[2:5], v28
	ds_read_b128 v[6:9], v28 offset:8192
	ds_read_b128 v[10:13], v28 offset:16384
	s_waitcnt lgkmcnt(0)
	v_pk_add_f32 v[20:21], v[4:5], 0 op_sel_hi:[1,0]
	v_pk_add_f32 v[22:23], v[2:3], 0 op_sel_hi:[1,0]
	ds_read_b128 v[2:5], v28 offset:24576
	v_pk_add_f32 v[24:25], v[8:9], 0 op_sel_hi:[1,0]
	v_pk_add_f32 v[26:27], v[6:7], 0 op_sel_hi:[1,0]
	ds_read_b128 v[6:9], v28 offset:32768
	v_pk_add_f32 v[22:23], v[22:23], v[10:11]
	s_waitcnt lgkmcnt(0)
	v_pk_add_f32 v[24:25], v[24:25], v[4:5]
	v_pk_add_f32 v[26:27], v[26:27], v[2:3]
	ds_read_b128 v[2:5], v28 offset:49152
	v_pk_add_f32 v[20:21], v[20:21], v[12:13]
	ds_read_b128 v[10:13], v28 offset:40960
	v_pk_add_f32 v[22:23], v[22:23], v[6:7]
	v_pk_add_f32 v[20:21], v[20:21], v[8:9]
	ds_read_b128 v[6:9], v28 offset:57344
	s_waitcnt lgkmcnt(0)
	v_pk_add_f32 v[22:23], v[22:23], v[2:3]
	v_add_u32_e32 v2, 0x10000, v28
	v_pk_add_f32 v[20:21], v[20:21], v[4:5]
	ds_read_b128 v[2:5], v2
	v_pk_add_f32 v[10:11], v[26:27], v[10:11]
	v_pk_add_f32 v[12:13], v[24:25], v[12:13]
	v_pk_add_f32 v[10:11], v[10:11], v[6:7]
	v_add_u32_e32 v6, 0x12000, v28
	v_pk_add_f32 v[12:13], v[12:13], v[8:9]
	ds_read_b128 v[6:9], v6
	s_waitcnt lgkmcnt(0)
	v_pk_add_f32 v[22:23], v[22:23], v[2:3]
	v_add_u32_e32 v2, 0x14000, v28
	v_pk_add_f32 v[20:21], v[20:21], v[4:5]
	ds_read_b128 v[2:5], v2
	v_pk_add_f32 v[10:11], v[10:11], v[6:7]
	v_add_u32_e32 v6, 0x16000, v28
	v_pk_add_f32 v[12:13], v[12:13], v[8:9]
	ds_read_b128 v[6:9], v6
	s_waitcnt lgkmcnt(0)
	v_pk_add_f32 v[22:23], v[22:23], v[2:3]
	v_add_u32_e32 v2, 0x18000, v28
	v_pk_add_f32 v[20:21], v[20:21], v[4:5]
	ds_read_b128 v[2:5], v2
	v_pk_add_f32 v[26:27], v[10:11], v[6:7]
	v_add_u32_e32 v6, 0x1a000, v28
	v_pk_add_f32 v[24:25], v[12:13], v[8:9]
	ds_read_b128 v[6:9], v6
	s_waitcnt lgkmcnt(0)
	v_pk_add_f32 v[22:23], v[22:23], v[2:3]
	v_add_u32_e32 v2, 0x1c000, v28
	v_add_u32_e32 v10, 0x1e000, v28
	v_pk_add_f32 v[20:21], v[20:21], v[4:5]
	ds_read_b128 v[2:5], v2
	ds_read_b128 v[10:13], v10
	v_pk_add_f32 v[6:7], v[26:27], v[6:7]
	v_pk_add_f32 v[8:9], v[24:25], v[8:9]
	s_waitcnt lgkmcnt(0)
	v_pk_add_f32 v[2:3], v[22:23], v[2:3]
	v_pk_add_f32 v[6:7], v[6:7], v[10:11]
	v_pk_add_f32 v[4:5], v[20:21], v[4:5]
	v_pk_add_f32 v[8:9], v[8:9], v[12:13]
	s_waitcnt vmcnt(0)
	v_lshlrev_b32_e32 v10, 16, v16
	v_and_b32_e32 v11, 0xffff0000, v16
	v_pk_add_f32 v[2:3], v[2:3], v[10:11]
	v_lshlrev_b32_e32 v10, 16, v18
	v_and_b32_e32 v11, 0xffff0000, v18
	v_lshlrev_b32_e32 v12, 16, v17
	v_and_b32_e32 v13, 0xffff0000, v17
	v_pk_add_f32 v[6:7], v[6:7], v[10:11]
	v_pk_add_f32 v[4:5], v[4:5], v[12:13]
	v_lshlrev_b32_e32 v12, 16, v19
	v_and_b32_e32 v13, 0xffff0000, v19
	v_mul_f32_e32 v10, v6, v6
	v_mul_f32_e32 v11, v7, v7
	v_pk_add_f32 v[8:9], v[8:9], v[12:13]
	v_fmac_f32_e32 v10, v2, v2
	v_fmac_f32_e32 v11, v3, v3
	v_add_f32_e32 v10, v10, v11
	v_mul_f32_e32 v11, v8, v8
	v_fmac_f32_e32 v11, v4, v4
	v_add_f32_e32 v10, v11, v10
	v_mul_f32_e32 v11, v9, v9
	v_fmac_f32_e32 v11, v5, v5
	v_and_b32_e32 v12, 64, v214
	v_add_f32_e32 v10, v11, v10
	v_xor_b32_e32 v11, 16, v214
	v_add_u32_e32 v12, 64, v12
	v_cmp_lt_i32_e32 vcc, v11, v12
	v_cvt_pk_bf16_f32 v2, v2, v3
	v_cvt_pk_bf16_f32 v3, v4, v5
	v_xor_b32_e32 v5, 32, v214
	global_store_dwordx2 v[14:15], v[2:3], off
	v_cndmask_b32_e32 v11, v214, v11, vcc
	v_lshlrev_b32_e32 v11, 2, v11
	ds_bpermute_b32 v11, v11, v10
	v_cmp_lt_i32_e32 vcc, v5, v12
	v_cvt_pk_bf16_f32 v2, v6, v7
	v_cvt_pk_bf16_f32 v3, v8, v9
	global_store_dwordx2 v[14:15], v[2:3], off offset:256
	s_waitcnt lgkmcnt(0)
	v_add_f32_e32 v4, v10, v11
	v_cndmask_b32_e32 v5, v214, v5, vcc
	v_lshlrev_b32_e32 v5, 2, v5
	ds_bpermute_b32 v5, v5, v4
	v_cmp_gt_u32_e32 vcc, 16, v65
	s_waitcnt lgkmcnt(0)
	v_add_f32_e32 v2, v4, v5
	s_and_saveexec_b64 s[4:5], vcc
	s_and_b32 s1, s0, 0xffffffc0
	s_add_i32 s1, s1, 0
	v_lshl_add_u32 v3, v80, 2, s1
	v_add_u32_e32 v3, 0x20100, v3
	ds_write_b32 v3, v2
	s_or_b64 exec, exec, s[4:5]
	v_or_b32_e32 v3, s3, v64
	v_cmp_eq_u32_e32 vcc, 0, v3
	s_waitcnt lgkmcnt(0)
	s_barrier
	s_and_saveexec_b64 s[4:5], vcc
	s_cbranch_execz .LBB0_1036
	s_andn2_b32 s0, s0, 63
	s_add_i32 s0, s0, 0
	s_add_i32 s0, s0, 0x20100
	v_lshl_add_u32 v3, v80, 2, s0
	ds_read_b32 v3, v3 offset:64
	v_lshlrev_b64 v[0:1], 7, v[0:1]
	v_lshl_add_u64 v[0:1], s[6:7], 0, v[0:1]
	s_ashr_i32 s3, s2, 31
	v_lshl_add_u64 v[0:1], s[2:3], 2, v[0:1]
	s_waitcnt lgkmcnt(0)
	v_add_f32_e32 v2, v2, v3
	global_store_dword v[0:1], v2, off

.LBB0_1111:
	v_add_co_u32_e32 v82, vcc, s84, v66
	s_nop 1
	v_addc_co_u32_e32 v83, vcc, 0, v67, vcc
	v_add_co_u32_e32 v130, vcc, s85, v66
	s_nop 1
	v_addc_co_u32_e32 v131, vcc, 0, v67, vcc
	v_add_co_u32_e32 v172, vcc, s88, v66
	s_nop 1
	v_addc_co_u32_e32 v173, vcc, 0, v67, vcc
	v_add_co_u32_e32 v174, vcc, s89, v66
	s_nop 1
	v_addc_co_u32_e32 v175, vcc, 0, v67, vcc
	v_add_co_u32_e32 v176, vcc, 0x7008000, v64
	s_nop 1
	v_addc_co_u32_e32 v177, vcc, 0, v65, vcc
	v_add_co_u32_e32 v178, vcc, 0x7018000, v64
	s_nop 1
	v_addc_co_u32_e32 v179, vcc, 0, v65, vcc
	v_add_co_u32_e32 v180, vcc, 0x7088000, v64
	s_nop 1
	v_addc_co_u32_e32 v181, vcc, 0, v65, vcc
	v_add_co_u32_e32 v182, vcc, 0x7098000, v64
	s_nop 1
	v_addc_co_u32_e32 v183, vcc, 0, v65, vcc
	global_load_dwordx4 v[68:71], v[82:83], off
	global_load_dwordx4 v[72:75], v[130:131], off
	global_load_dwordx4 v[76:79], v[172:173], off
	global_load_dwordx4 v[84:87], v[174:175], off
	global_load_dwordx4 v[88:91], v[176:177], off
	global_load_dwordx4 v[92:95], v[178:179], off
	global_load_dwordx4 v[96:99], v[180:181], off
	global_load_dwordx4 v[100:103], v[182:183], off
	global_load_dwordx4 v[104:107], v[82:83], off offset:64
	global_load_dwordx4 v[108:111], v[130:131], off offset:64
	global_load_dwordx4 v[112:115], v[172:173], off offset:64
	global_load_dwordx4 v[116:119], v[174:175], off offset:64
	global_load_dwordx4 v[120:123], v[176:177], off offset:64
	global_load_dwordx4 v[124:127], v[178:179], off offset:64
	global_load_dwordx4 v[132:135], v[180:181], off offset:64
	global_load_dwordx4 v[136:139], v[182:183], off offset:64
	global_load_dwordx4 v[140:143], v[82:83], off offset:128
	global_load_dwordx4 v[144:147], v[130:131], off offset:128
	global_load_dwordx4 v[148:151], v[172:173], off offset:128
	global_load_dwordx4 v[152:155], v[174:175], off offset:128
	global_load_dwordx4 v[156:159], v[176:177], off offset:128
	global_load_dwordx4 v[160:163], v[178:179], off offset:128
	global_load_dwordx4 v[164:167], v[180:181], off offset:128
	global_load_dwordx4 v[168:171], v[182:183], off offset:128
	s_waitcnt vmcnt(16)
	v_mfma_f32_16x16x32_bf16 v[56:59], v[88:91], v[68:71], 0
	v_mfma_f32_16x16x32_bf16 v[52:55], v[88:91], v[72:75], 0
	v_mfma_f32_16x16x32_bf16 v[48:51], v[88:91], v[76:79], 0
	v_mfma_f32_16x16x32_bf16 v[44:47], v[88:91], v[84:87], 0
	v_mfma_f32_16x16x32_bf16 v[12:15], v[92:95], v[68:71], 0
	v_mfma_f32_16x16x32_bf16 v[8:11], v[92:95], v[72:75], 0
	v_mfma_f32_16x16x32_bf16 v[4:7], v[92:95], v[76:79], 0
	v_mfma_f32_16x16x32_bf16 v[0:3], v[92:95], v[84:87], 0
	v_mfma_f32_16x16x32_bf16 v[16:19], v[96:99], v[68:71], 0
	v_mfma_f32_16x16x32_bf16 v[24:27], v[96:99], v[72:75], 0
	v_mfma_f32_16x16x32_bf16 v[28:31], v[96:99], v[76:79], 0
	v_mfma_f32_16x16x32_bf16 v[36:39], v[96:99], v[84:87], 0
	v_mfma_f32_16x16x32_bf16 v[20:23], v[100:103], v[68:71], 0
	v_mfma_f32_16x16x32_bf16 v[32:35], v[100:103], v[72:75], 0
	v_mfma_f32_16x16x32_bf16 v[40:43], v[100:103], v[76:79], 0
	v_mfma_f32_16x16x32_bf16 v[60:63], v[100:103], v[84:87], 0
	global_load_dwordx4 v[68:71], v[82:83], off offset:192
	global_load_dwordx4 v[72:75], v[130:131], off offset:192
	global_load_dwordx4 v[76:79], v[172:173], off offset:192
	global_load_dwordx4 v[84:87], v[174:175], off offset:192
	global_load_dwordx4 v[88:91], v[176:177], off offset:192
	global_load_dwordx4 v[92:95], v[178:179], off offset:192
	global_load_dwordx4 v[96:99], v[180:181], off offset:192
	global_load_dwordx4 v[100:103], v[182:183], off offset:192
	s_waitcnt vmcnt(16)
	v_mfma_f32_16x16x32_bf16 v[56:59], v[120:123], v[104:107], v[56:59]
	v_mfma_f32_16x16x32_bf16 v[52:55], v[120:123], v[108:111], v[52:55]
	v_mfma_f32_16x16x32_bf16 v[48:51], v[120:123], v[112:115], v[48:51]
	v_mfma_f32_16x16x32_bf16 v[44:47], v[120:123], v[116:119], v[44:47]
	v_mfma_f32_16x16x32_bf16 v[12:15], v[124:127], v[104:107], v[12:15]
	v_mfma_f32_16x16x32_bf16 v[8:11], v[124:127], v[108:111], v[8:11]
	v_mfma_f32_16x16x32_bf16 v[4:7], v[124:127], v[112:115], v[4:7]
	v_mfma_f32_16x16x32_bf16 v[0:3], v[124:127], v[116:119], v[0:3]
	v_mfma_f32_16x16x32_bf16 v[16:19], v[132:135], v[104:107], v[16:19]
	v_mfma_f32_16x16x32_bf16 v[24:27], v[132:135], v[108:111], v[24:27]
	v_mfma_f32_16x16x32_bf16 v[28:31], v[132:135], v[112:115], v[28:31]
	v_mfma_f32_16x16x32_bf16 v[36:39], v[132:135], v[116:119], v[36:39]
	v_mfma_f32_16x16x32_bf16 v[20:23], v[136:139], v[104:107], v[20:23]
	v_mfma_f32_16x16x32_bf16 v[32:35], v[136:139], v[108:111], v[32:35]
	v_mfma_f32_16x16x32_bf16 v[40:43], v[136:139], v[112:115], v[40:43]
	v_mfma_f32_16x16x32_bf16 v[60:63], v[136:139], v[116:119], v[60:63]
	global_load_dwordx4 v[104:107], v[82:83], off offset:256
	global_load_dwordx4 v[108:111], v[130:131], off offset:256
	global_load_dwordx4 v[112:115], v[172:173], off offset:256
	global_load_dwordx4 v[116:119], v[174:175], off offset:256
	global_load_dwordx4 v[120:123], v[176:177], off offset:256
	global_load_dwordx4 v[124:127], v[178:179], off offset:256
	global_load_dwordx4 v[132:135], v[180:181], off offset:256
	global_load_dwordx4 v[136:139], v[182:183], off offset:256
	s_waitcnt vmcnt(16)
	v_mfma_f32_16x16x32_bf16 v[56:59], v[156:159], v[140:143], v[56:59]
	v_mfma_f32_16x16x32_bf16 v[52:55], v[156:159], v[144:147], v[52:55]
	v_mfma_f32_16x16x32_bf16 v[48:51], v[156:159], v[148:151], v[48:51]
	v_mfma_f32_16x16x32_bf16 v[44:47], v[156:159], v[152:155], v[44:47]
	v_mfma_f32_16x16x32_bf16 v[12:15], v[160:163], v[140:143], v[12:15]
	v_mfma_f32_16x16x32_bf16 v[8:11], v[160:163], v[144:147], v[8:11]
	v_mfma_f32_16x16x32_bf16 v[4:7], v[160:163], v[148:151], v[4:7]
	v_mfma_f32_16x16x32_bf16 v[0:3], v[160:163], v[152:155], v[0:3]
	v_mfma_f32_16x16x32_bf16 v[16:19], v[164:167], v[140:143], v[16:19]
	v_mfma_f32_16x16x32_bf16 v[24:27], v[164:167], v[144:147], v[24:27]
	v_mfma_f32_16x16x32_bf16 v[28:31], v[164:167], v[148:151], v[28:31]
	v_mfma_f32_16x16x32_bf16 v[36:39], v[164:167], v[152:155], v[36:39]
	v_mfma_f32_16x16x32_bf16 v[20:23], v[168:171], v[140:143], v[20:23]
	v_mfma_f32_16x16x32_bf16 v[32:35], v[168:171], v[144:147], v[32:35]
	v_mfma_f32_16x16x32_bf16 v[40:43], v[168:171], v[148:151], v[40:43]
	v_mfma_f32_16x16x32_bf16 v[60:63], v[168:171], v[152:155], v[60:63]
	global_load_dwordx4 v[140:143], v[82:83], off offset:320
	global_load_dwordx4 v[144:147], v[130:131], off offset:320
	global_load_dwordx4 v[148:151], v[172:173], off offset:320
	global_load_dwordx4 v[152:155], v[174:175], off offset:320
	global_load_dwordx4 v[156:159], v[176:177], off offset:320
	global_load_dwordx4 v[160:163], v[178:179], off offset:320
	global_load_dwordx4 v[164:167], v[180:181], off offset:320
	global_load_dwordx4 v[168:171], v[182:183], off offset:320
	s_waitcnt vmcnt(16)
	v_mfma_f32_16x16x32_bf16 v[56:59], v[88:91], v[68:71], v[56:59]
	v_mfma_f32_16x16x32_bf16 v[52:55], v[88:91], v[72:75], v[52:55]
	v_mfma_f32_16x16x32_bf16 v[48:51], v[88:91], v[76:79], v[48:51]
	v_mfma_f32_16x16x32_bf16 v[44:47], v[88:91], v[84:87], v[44:47]
	v_mfma_f32_16x16x32_bf16 v[12:15], v[92:95], v[68:71], v[12:15]
	v_mfma_f32_16x16x32_bf16 v[8:11], v[92:95], v[72:75], v[8:11]
	v_mfma_f32_16x16x32_bf16 v[4:7], v[92:95], v[76:79], v[4:7]
	v_mfma_f32_16x16x32_bf16 v[0:3], v[92:95], v[84:87], v[0:3]
	v_mfma_f32_16x16x32_bf16 v[16:19], v[96:99], v[68:71], v[16:19]
	v_mfma_f32_16x16x32_bf16 v[24:27], v[96:99], v[72:75], v[24:27]
	v_mfma_f32_16x16x32_bf16 v[28:31], v[96:99], v[76:79], v[28:31]
	v_mfma_f32_16x16x32_bf16 v[36:39], v[96:99], v[84:87], v[36:39]
	v_mfma_f32_16x16x32_bf16 v[20:23], v[100:103], v[68:71], v[20:23]
	v_mfma_f32_16x16x32_bf16 v[32:35], v[100:103], v[72:75], v[32:35]
	v_mfma_f32_16x16x32_bf16 v[40:43], v[100:103], v[76:79], v[40:43]
	v_mfma_f32_16x16x32_bf16 v[60:63], v[100:103], v[84:87], v[60:63]
	global_load_dwordx4 v[68:71], v[82:83], off offset:384
	global_load_dwordx4 v[72:75], v[130:131], off offset:384
	global_load_dwordx4 v[76:79], v[172:173], off offset:384
	global_load_dwordx4 v[84:87], v[174:175], off offset:384
	global_load_dwordx4 v[88:91], v[176:177], off offset:384
	global_load_dwordx4 v[92:95], v[178:179], off offset:384
	global_load_dwordx4 v[96:99], v[180:181], off offset:384
	global_load_dwordx4 v[100:103], v[182:183], off offset:384
	s_waitcnt vmcnt(16)
	v_mfma_f32_16x16x32_bf16 v[56:59], v[120:123], v[104:107], v[56:59]
	v_mfma_f32_16x16x32_bf16 v[52:55], v[120:123], v[108:111], v[52:55]
	v_mfma_f32_16x16x32_bf16 v[48:51], v[120:123], v[112:115], v[48:51]
	v_mfma_f32_16x16x32_bf16 v[44:47], v[120:123], v[116:119], v[44:47]
	v_mfma_f32_16x16x32_bf16 v[12:15], v[124:127], v[104:107], v[12:15]
	v_mfma_f32_16x16x32_bf16 v[8:11], v[124:127], v[108:111], v[8:11]
	v_mfma_f32_16x16x32_bf16 v[4:7], v[124:127], v[112:115], v[4:7]
	v_mfma_f32_16x16x32_bf16 v[0:3], v[124:127], v[116:119], v[0:3]
	v_mfma_f32_16x16x32_bf16 v[16:19], v[132:135], v[104:107], v[16:19]
	v_mfma_f32_16x16x32_bf16 v[24:27], v[132:135], v[108:111], v[24:27]
	v_mfma_f32_16x16x32_bf16 v[28:31], v[132:135], v[112:115], v[28:31]
	v_mfma_f32_16x16x32_bf16 v[36:39], v[132:135], v[116:119], v[36:39]
	v_mfma_f32_16x16x32_bf16 v[20:23], v[136:139], v[104:107], v[20:23]
	v_mfma_f32_16x16x32_bf16 v[32:35], v[136:139], v[108:111], v[32:35]
	v_mfma_f32_16x16x32_bf16 v[40:43], v[136:139], v[112:115], v[40:43]
	v_mfma_f32_16x16x32_bf16 v[60:63], v[136:139], v[116:119], v[60:63]
	global_load_dwordx4 v[104:107], v[82:83], off offset:448
	global_load_dwordx4 v[108:111], v[130:131], off offset:448
	global_load_dwordx4 v[112:115], v[172:173], off offset:448
	global_load_dwordx4 v[116:119], v[174:175], off offset:448
	global_load_dwordx4 v[120:123], v[176:177], off offset:448
	global_load_dwordx4 v[124:127], v[178:179], off offset:448
	global_load_dwordx4 v[132:135], v[180:181], off offset:448
	global_load_dwordx4 v[136:139], v[182:183], off offset:448
	s_waitcnt vmcnt(16)
	v_mfma_f32_16x16x32_bf16 v[56:59], v[156:159], v[140:143], v[56:59]
	v_mfma_f32_16x16x32_bf16 v[52:55], v[156:159], v[144:147], v[52:55]
	v_mfma_f32_16x16x32_bf16 v[48:51], v[156:159], v[148:151], v[48:51]
	v_mfma_f32_16x16x32_bf16 v[44:47], v[156:159], v[152:155], v[44:47]
	v_mfma_f32_16x16x32_bf16 v[12:15], v[160:163], v[140:143], v[12:15]
	v_mfma_f32_16x16x32_bf16 v[8:11], v[160:163], v[144:147], v[8:11]
	v_mfma_f32_16x16x32_bf16 v[4:7], v[160:163], v[148:151], v[4:7]
	v_mfma_f32_16x16x32_bf16 v[0:3], v[160:163], v[152:155], v[0:3]
	v_mfma_f32_16x16x32_bf16 v[16:19], v[164:167], v[140:143], v[16:19]
	v_mfma_f32_16x16x32_bf16 v[24:27], v[164:167], v[144:147], v[24:27]
	v_mfma_f32_16x16x32_bf16 v[28:31], v[164:167], v[148:151], v[28:31]
	v_mfma_f32_16x16x32_bf16 v[36:39], v[164:167], v[152:155], v[36:39]
	v_mfma_f32_16x16x32_bf16 v[20:23], v[168:171], v[140:143], v[20:23]
	v_mfma_f32_16x16x32_bf16 v[32:35], v[168:171], v[144:147], v[32:35]
	v_mfma_f32_16x16x32_bf16 v[40:43], v[168:171], v[148:151], v[40:43]
	v_mfma_f32_16x16x32_bf16 v[60:63], v[168:171], v[152:155], v[60:63]
	s_waitcnt vmcnt(8)
	v_mfma_f32_16x16x32_bf16 v[56:59], v[88:91], v[68:71], v[56:59]
	v_mfma_f32_16x16x32_bf16 v[52:55], v[88:91], v[72:75], v[52:55]
	v_mfma_f32_16x16x32_bf16 v[48:51], v[88:91], v[76:79], v[48:51]
	v_mfma_f32_16x16x32_bf16 v[44:47], v[88:91], v[84:87], v[44:47]
	v_mfma_f32_16x16x32_bf16 v[12:15], v[92:95], v[68:71], v[12:15]
	v_mfma_f32_16x16x32_bf16 v[8:11], v[92:95], v[72:75], v[8:11]
	v_mfma_f32_16x16x32_bf16 v[4:7], v[92:95], v[76:79], v[4:7]
	v_mfma_f32_16x16x32_bf16 v[0:3], v[92:95], v[84:87], v[0:3]
	v_mfma_f32_16x16x32_bf16 v[16:19], v[96:99], v[68:71], v[16:19]
	v_mfma_f32_16x16x32_bf16 v[24:27], v[96:99], v[72:75], v[24:27]
	v_mfma_f32_16x16x32_bf16 v[28:31], v[96:99], v[76:79], v[28:31]
	v_mfma_f32_16x16x32_bf16 v[36:39], v[96:99], v[84:87], v[36:39]
	v_mfma_f32_16x16x32_bf16 v[20:23], v[100:103], v[68:71], v[20:23]
	v_mfma_f32_16x16x32_bf16 v[32:35], v[100:103], v[72:75], v[32:35]
	v_mfma_f32_16x16x32_bf16 v[40:43], v[100:103], v[76:79], v[40:43]
	v_mfma_f32_16x16x32_bf16 v[60:63], v[100:103], v[84:87], v[60:63]
	s_waitcnt vmcnt(0)
	v_mfma_f32_16x16x32_bf16 v[56:59], v[120:123], v[104:107], v[56:59]
	v_mfma_f32_16x16x32_bf16 v[52:55], v[120:123], v[108:111], v[52:55]
	v_mfma_f32_16x16x32_bf16 v[48:51], v[120:123], v[112:115], v[48:51]
	v_mfma_f32_16x16x32_bf16 v[44:47], v[120:123], v[116:119], v[44:47]
	v_mfma_f32_16x16x32_bf16 v[12:15], v[124:127], v[104:107], v[12:15]
	v_mfma_f32_16x16x32_bf16 v[8:11], v[124:127], v[108:111], v[8:11]
	v_mfma_f32_16x16x32_bf16 v[4:7], v[124:127], v[112:115], v[4:7]
	v_mfma_f32_16x16x32_bf16 v[0:3], v[124:127], v[116:119], v[0:3]
	v_mfma_f32_16x16x32_bf16 v[16:19], v[132:135], v[104:107], v[16:19]
	v_mfma_f32_16x16x32_bf16 v[24:27], v[132:135], v[108:111], v[24:27]
	v_mfma_f32_16x16x32_bf16 v[28:31], v[132:135], v[112:115], v[28:31]
	v_mfma_f32_16x16x32_bf16 v[36:39], v[132:135], v[116:119], v[36:39]
	v_mfma_f32_16x16x32_bf16 v[20:23], v[136:139], v[104:107], v[20:23]
	v_mfma_f32_16x16x32_bf16 v[32:35], v[136:139], v[108:111], v[32:35]
	v_mfma_f32_16x16x32_bf16 v[40:43], v[136:139], v[112:115], v[40:43]
	v_mfma_f32_16x16x32_bf16 v[60:63], v[136:139], v[116:119], v[60:63]
	s_nop 7
	s_nop 3
	v_and_b32_e32 v65, 63, v81
	s_ashr_i32 s2, s4, 7
	v_lshl_add_u32 v65, v65, 4, 0
	s_lshl_b32 s3, s2, 4
	v_lshl_add_u32 v66, s5, 14, v65
	s_addk_i32 s3, 0x4000
	ds_write_b128 v66, v[56:59]
	ds_write_b128 v66, v[52:55] offset:1024
	ds_write_b128 v66, v[48:51] offset:2048
	ds_write_b128 v66, v[44:47] offset:3072
	ds_write_b128 v66, v[12:15] offset:4096
	ds_write_b128 v66, v[8:11] offset:5120
	ds_write_b128 v66, v[4:7] offset:6144
	ds_write_b128 v66, v[0:3] offset:7168
	ds_write_b128 v66, v[16:19] offset:8192
	ds_write_b128 v66, v[24:27] offset:9216
	ds_write_b128 v66, v[28:31] offset:10240
	ds_write_b128 v66, v[36:39] offset:11264
	ds_write_b128 v66, v[20:23] offset:12288
	ds_write_b128 v66, v[32:35] offset:13312
	ds_write_b128 v66, v[40:43] offset:14336
	ds_write_b128 v66, v[60:63] offset:15360
	v_or_b32_e32 v0, s3, v80
	v_ashrrev_i32_e32 v1, 31, v0
	v_bfe_u32 v64, v81, 4, 2
	v_lshlrev_b64 v[2:3], 7, v[0:1]
	v_lshl_add_u64 v[2:3], s[8:9], 0, v[2:3]
	v_lshlrev_b32_e32 v128, 5, v64
	v_lshl_add_u64 v[6:7], v[2:3], 0, v[128:129]
	s_waitcnt lgkmcnt(0)
	s_barrier
	global_load_dwordx4 v[2:5], v[6:7], off
	s_nop 0
	global_load_dwordx4 v[6:9], v[6:7], off offset:16
	s_bfe_u32 s3, s4, 0x10006
	s_lshl_b32 s4, s3, 2
	s_add_i32 s4, s4, s2
	v_lshl_add_u32 v1, s4, 10, v65
	ds_read_b128 v[10:13], v1
	ds_read_b128 v[14:17], v1 offset:8192
	ds_read_b128 v[18:21], v1 offset:16384
	ds_read_b128 v[22:25], v1 offset:24576
	ds_read_b128 v[26:29], v1 offset:32768
	ds_read_b128 v[30:33], v1 offset:40960
	ds_read_b128 v[34:37], v1 offset:49152
	ds_read_b128 v[38:41], v1 offset:57344
	s_waitcnt lgkmcnt(0)
	v_pk_add_f32 v[10:11], v[10:11], 0 op_sel_hi:[1,0]
	v_add_u32_e32 v42, 0x10000, v1
	v_pk_add_f32 v[10:11], v[10:11], v[18:19]
	v_add_u32_e32 v46, 0x12000, v1
	v_add_u32_e32 v50, 0x14000, v1
	v_add_u32_e32 v54, 0x16000, v1
	v_add_u32_e32 v58, 0x18000, v1
	v_add_u32_e32 v62, 0x1a000, v1
	ds_read_b128 v[42:45], v42
	ds_read_b128 v[46:49], v46
	ds_read_b128 v[50:53], v50
	ds_read_b128 v[54:57], v54
	ds_read_b128 v[58:61], v58
	ds_read_b128 v[66:69], v62
	v_pk_add_f32 v[14:15], v[14:15], 0 op_sel_hi:[1,0]
	v_pk_add_f32 v[12:13], v[12:13], 0 op_sel_hi:[1,0]
	v_pk_add_f32 v[14:15], v[14:15], v[22:23]
	v_pk_add_f32 v[12:13], v[12:13], v[20:21]
	v_pk_add_f32 v[10:11], v[10:11], v[26:27]
	v_pk_add_f32 v[14:15], v[14:15], v[30:31]
	v_pk_add_f32 v[12:13], v[12:13], v[28:29]
	v_pk_add_f32 v[10:11], v[10:11], v[34:35]
	v_pk_add_f32 v[14:15], v[14:15], v[38:39]
	v_pk_add_f32 v[12:13], v[12:13], v[36:37]
	s_waitcnt lgkmcnt(0)
	v_pk_add_f32 v[10:11], v[10:11], v[42:43]
	v_pk_add_f32 v[14:15], v[14:15], v[46:47]
	v_pk_add_f32 v[12:13], v[12:13], v[44:45]
	v_pk_add_f32 v[10:11], v[10:11], v[50:51]
	v_pk_add_f32 v[14:15], v[14:15], v[54:55]
	v_pk_add_f32 v[12:13], v[12:13], v[52:53]
	v_pk_add_f32 v[10:11], v[10:11], v[58:59]
	v_pk_add_f32 v[14:15], v[14:15], v[66:67]
	v_pk_add_f32 v[12:13], v[12:13], v[60:61]
	v_pk_add_f32 v[16:17], v[16:17], 0 op_sel_hi:[1,0]
	s_lshl_b32 s0, s0, 7
	v_pk_add_f32 v[16:17], v[16:17], v[24:25]
	s_waitcnt vmcnt(0)
	v_mov_b32_e32 v18, v2
	v_mov_b32_e32 v19, v6
	v_mov_b32_e32 v6, v3
	v_mov_b32_e32 v2, v4
	v_mov_b32_e32 v3, v8
	v_mov_b32_e32 v8, v5
	v_pk_add_f32 v[4:5], v[18:19], v[6:7]
	v_pk_add_f32 v[2:3], v[2:3], v[8:9]
	v_pk_add_f32 v[16:17], v[16:17], v[32:33]
	v_pk_add_f32 v[2:3], v[4:5], v[2:3]
	v_and_b32_e32 v4, 64, v214
	v_add_f32_e32 v2, v2, v3
	v_xor_b32_e32 v3, 16, v214
	v_add_u32_e32 v4, 64, v4
	v_cmp_lt_i32_e32 vcc, v3, v4
	v_pk_add_f32 v[16:17], v[16:17], v[40:41]
	s_nop 0
	v_cndmask_b32_e32 v3, v214, v3, vcc
	v_lshlrev_b32_e32 v3, 2, v3
	ds_bpermute_b32 v3, v3, v2
	v_pk_add_f32 v[16:17], v[16:17], v[48:49]
	s_waitcnt lgkmcnt(0)
	v_add_f32_e32 v18, v2, v3
	v_xor_b32_e32 v2, 32, v214
	v_cmp_lt_i32_e32 vcc, v2, v4
	v_pk_add_f32 v[16:17], v[16:17], v[56:57]
	s_nop 0
	v_cndmask_b32_e32 v2, v214, v2, vcc
	v_lshlrev_b32_e32 v2, 2, v2
	ds_bpermute_b32 v19, v2, v18
	v_add_u32_e32 v2, 0x1c000, v1
	v_add_u32_e32 v1, 0x1e000, v1
	ds_read_b128 v[2:5], v2
	ds_read_b128 v[6:9], v1
	v_pk_add_f32 v[16:17], v[16:17], v[68:69]
	s_waitcnt lgkmcnt(2)
	v_add_f32_e32 v1, v18, v19
	v_fmamk_f32 v1, v1, 0x3a000000, v190
	v_mul_f32_e32 v18, 0x4b800000, v1
	v_cmp_gt_f32_e32 vcc, s70, v1
	s_waitcnt lgkmcnt(1)
	v_pk_add_f32 v[2:3], v[10:11], v[2:3]
	s_waitcnt lgkmcnt(0)
	v_pk_add_f32 v[6:7], v[14:15], v[6:7]
	v_cndmask_b32_e32 v1, v1, v18, vcc
	v_rsq_f32_e32 v1, v1
	v_pk_add_f32 v[4:5], v[12:13], v[4:5]
	v_mov_b32_e32 v12, v6
	v_mov_b32_e32 v13, v2
	v_mul_f32_e32 v10, 0x45800000, v1
	v_cndmask_b32_e32 v10, v1, v10, vcc
	v_pk_mul_f32 v[12:13], v[12:13], v[10:11] op_sel_hi:[1,0]
	v_lshlrev_b32_e32 v2, 2, v64
	v_mul_f32_e32 v1, 0xbfb8aa3b, v13
	v_exp_f32_e32 v1, v1
	v_lshl_or_b32 v6, s3, 4, v2
	v_mov_b32_e32 v2, v7
	v_pk_mul_f32 v[2:3], v[2:3], v[10:11] op_sel_hi:[1,0]
	v_add_f32_e32 v1, 1.0, v1
	v_mul_f32_e32 v7, 0xbfb8aa3b, v3
	v_rcp_f32_e32 v1, v1
	v_exp_f32_e32 v7, v7
	v_pk_add_f32 v[8:9], v[16:17], v[8:9]
	v_or_b32_e32 v11, s1, v6
	v_mul_f32_e32 v1, v13, v1
	v_add_f32_e32 v6, 1.0, v7
	v_mul_f32_e32 v1, v12, v1
	v_rcp_f32_e32 v12, v6
	v_mov_b32_e32 v6, v8
	v_mov_b32_e32 v7, v4
	v_pk_mul_f32 v[6:7], v[6:7], v[10:11] op_sel_hi:[1,0]
	v_mul_f32_e32 v3, v3, v12
	v_mul_f32_e32 v4, 0xbfb8aa3b, v7
	v_exp_f32_e32 v8, v4
	v_mov_b32_e32 v4, v9
	v_pk_mul_f32 v[4:5], v[4:5], v[10:11] op_sel_hi:[1,0]
	v_mul_f32_e32 v2, v2, v3
	v_mul_f32_e32 v9, 0xbfb8aa3b, v5
	v_exp_f32_e32 v9, v9
	v_add_f32_e32 v8, 1.0, v8
	v_rcp_f32_e32 v8, v8
	v_cvt_pk_bf16_f32 v2, v1, v2
	v_add_f32_e32 v9, 1.0, v9
	v_rcp_f32_e32 v9, v9
	v_mul_f32_e32 v3, v7, v8
	v_mul_f32_e32 v3, v6, v3
	s_movk_i32 s1, 0x2c00
	v_mul_f32_e32 v5, v5, v9
	v_mul_f32_e32 v4, v4, v5
	v_cvt_pk_bf16_f32 v3, v3, v4
	v_mov_b64_e32 v[4:5], s[6:7]
	v_mad_i64_i32 v[0:1], s[2:3], v0, s1, v[4:5]
	s_ashr_i32 s1, s0, 31
	v_lshl_add_u64 v[0:1], s[0:1], 1, v[0:1]
	v_lshlrev_b32_e32 v128, 1, v11
	v_lshl_add_u64 v[0:1], v[0:1], 0, v[128:129]
	global_store_dwordx2 v[0:1], v[2:3], off
	s_waitcnt lgkmcnt(0)
	s_barrier

.LBB0_1205:
	v_mov_b32_e32 v97, v210
	s_mov_b32 s2, s73
	s_cmp_gt_i32 s2, 31
	v_readfirstlane_b32 s1, v97
	s_cbranch_scc1 .LBB0_1211
	v_and_b32_e32 v96, 15, v97
	s_ashr_i32 s5, s1, 6
	v_mul_u32_u24_e32 v0, 0x1600, v96
	v_lshlrev_b32_e32 v128, 1, v0
	s_mul_i32 s6, s5, 0x2c0
	s_lshl_b32 s3, s2, 5
	s_waitcnt lgkmcnt(0)
	v_lshl_add_u64 v[0:1], s[14:15], 0, v[128:129]
	v_and_b32_e32 v128, 48, v97
	s_ashr_i32 s7, s6, 31
	s_lshl_b32 s4, s2, 6
	s_and_b32 s3, s3, 0x60
	v_lshl_add_u64 v[0:1], v[0:1], 0, v[128:129]
	s_lshl_b64 s[6:7], s[6:7], 1
	s_and_b32 s4, s4, 0xffffff00
	v_lshl_add_u64 v[28:29], v[0:1], 0, s[6:7]
	v_or_b32_e32 v0, s3, v96
	v_or_b32_e32 v2, s4, v0
	v_mov_b64_e32 v[0:1], s[12:13]
	s_movk_i32 s12, 0x2c00
	v_mad_i64_i32 v[0:1], s[12:13], v2, s12, v[0:1]
	v_lshl_add_u64 v[0:1], v[0:1], 0, v[128:129]
	v_lshl_add_u64 v[24:25], v[0:1], 0, s[6:7]
	s_mov_b32 s6, 0xb000000
	s_mov_b32 s6, 0xb02c000
	s_mov_b32 s6, 0xb058000
	s_mov_b64 s[6:7], 0xb000000
	s_mov_b32 s6, 0xb084000
	s_mov_b32 s6, 0x2c000
	s_mov_b32 s6, 0x160000
	s_mov_b32 s6, 0x18c000
	s_ashr_i32 s7, s1, 7
	s_and_b32 s6, s5, 1
	v_add_co_u32_e32 v26, vcc, 0xb000000, v28
	s_nop 1
	v_addc_co_u32_e32 v27, vcc, 0, v29, vcc
	v_add_co_u32_e32 v30, vcc, 0xb02c000, v28
	s_nop 1
	v_addc_co_u32_e32 v31, vcc, 0, v29, vcc
	v_add_co_u32_e32 v70, vcc, 0xb058000, v28
	s_nop 1
	v_addc_co_u32_e32 v71, vcc, 0, v29, vcc
	v_add_co_u32_e32 v98, vcc, 0xb084000, v28
	s_nop 1
	v_addc_co_u32_e32 v99, vcc, 0, v29, vcc
	v_mov_b32_e32 v130, v24
	v_mov_b32_e32 v131, v25
	v_add_co_u32_e32 v152, vcc, 0x2c000, v24
	s_nop 1
	v_addc_co_u32_e32 v153, vcc, 0, v25, vcc
	v_add_co_u32_e32 v154, vcc, 0x160000, v24
	s_nop 1
	v_addc_co_u32_e32 v155, vcc, 0, v25, vcc
	v_add_co_u32_e32 v156, vcc, 0x18c000, v24
	s_nop 1
	v_addc_co_u32_e32 v157, vcc, 0, v25, vcc
	global_load_dwordx4 v[80:83], v[26:27], off
	global_load_dwordx4 v[84:87], v[30:31], off
	global_load_dwordx4 v[88:91], v[70:71], off
	global_load_dwordx4 v[92:95], v[98:99], off
	global_load_dwordx4 v[100:103], v[130:131], off
	global_load_dwordx4 v[104:107], v[152:153], off
	global_load_dwordx4 v[108:111], v[154:155], off
	global_load_dwordx4 v[112:115], v[156:157], off
	global_load_dwordx4 v[116:119], v[26:27], off offset:64
	global_load_dwordx4 v[120:123], v[30:31], off offset:64
	global_load_dwordx4 v[124:127], v[70:71], off offset:64
	global_load_dwordx4 v[132:135], v[98:99], off offset:64
	global_load_dwordx4 v[136:139], v[130:131], off offset:64
	global_load_dwordx4 v[140:143], v[152:153], off offset:64
	global_load_dwordx4 v[144:147], v[154:155], off offset:64
	global_load_dwordx4 v[148:151], v[156:157], off offset:64
	s_waitcnt vmcnt(8)
	v_mfma_f32_16x16x32_bf16 v[4:7], v[100:103], v[80:83], 0
	v_mfma_f32_16x16x32_bf16 v[8:11], v[100:103], v[84:87], 0
	v_mfma_f32_16x16x32_bf16 v[12:15], v[100:103], v[88:91], 0
	v_mfma_f32_16x16x32_bf16 v[16:19], v[100:103], v[92:95], 0
	v_mfma_f32_16x16x32_bf16 v[20:23], v[104:107], v[80:83], 0
	v_mfma_f32_16x16x32_bf16 v[32:35], v[104:107], v[84:87], 0
	v_mfma_f32_16x16x32_bf16 v[36:39], v[104:107], v[88:91], 0
	v_mfma_f32_16x16x32_bf16 v[40:43], v[104:107], v[92:95], 0
	v_mfma_f32_16x16x32_bf16 v[44:47], v[108:111], v[80:83], 0
	v_mfma_f32_16x16x32_bf16 v[48:51], v[108:111], v[84:87], 0
	v_mfma_f32_16x16x32_bf16 v[52:55], v[108:111], v[88:91], 0
	v_mfma_f32_16x16x32_bf16 v[56:59], v[108:111], v[92:95], 0
	v_mfma_f32_16x16x32_bf16 v[60:63], v[112:115], v[80:83], 0
	v_mfma_f32_16x16x32_bf16 v[64:67], v[112:115], v[84:87], 0
	v_mfma_f32_16x16x32_bf16 v[72:75], v[112:115], v[88:91], 0
	v_mfma_f32_16x16x32_bf16 v[76:79], v[112:115], v[92:95], 0
	global_load_dwordx4 v[80:83], v[26:27], off offset:128
	global_load_dwordx4 v[84:87], v[30:31], off offset:128
	global_load_dwordx4 v[88:91], v[70:71], off offset:128
	global_load_dwordx4 v[92:95], v[98:99], off offset:128
	global_load_dwordx4 v[100:103], v[130:131], off offset:128
	global_load_dwordx4 v[104:107], v[152:153], off offset:128
	global_load_dwordx4 v[108:111], v[154:155], off offset:128
	global_load_dwordx4 v[112:115], v[156:157], off offset:128
	s_waitcnt vmcnt(8)
	v_mfma_f32_16x16x32_bf16 v[4:7], v[136:139], v[116:119], v[4:7]
	v_mfma_f32_16x16x32_bf16 v[8:11], v[136:139], v[120:123], v[8:11]
	v_mfma_f32_16x16x32_bf16 v[12:15], v[136:139], v[124:127], v[12:15]
	v_mfma_f32_16x16x32_bf16 v[16:19], v[136:139], v[132:135], v[16:19]
	v_mfma_f32_16x16x32_bf16 v[20:23], v[140:143], v[116:119], v[20:23]
	v_mfma_f32_16x16x32_bf16 v[32:35], v[140:143], v[120:123], v[32:35]
	v_mfma_f32_16x16x32_bf16 v[36:39], v[140:143], v[124:127], v[36:39]
	v_mfma_f32_16x16x32_bf16 v[40:43], v[140:143], v[132:135], v[40:43]
	v_mfma_f32_16x16x32_bf16 v[44:47], v[144:147], v[116:119], v[44:47]
	v_mfma_f32_16x16x32_bf16 v[48:51], v[144:147], v[120:123], v[48:51]
	v_mfma_f32_16x16x32_bf16 v[52:55], v[144:147], v[124:127], v[52:55]
	v_mfma_f32_16x16x32_bf16 v[56:59], v[144:147], v[132:135], v[56:59]
	v_mfma_f32_16x16x32_bf16 v[60:63], v[148:151], v[116:119], v[60:63]
	v_mfma_f32_16x16x32_bf16 v[64:67], v[148:151], v[120:123], v[64:67]
	v_mfma_f32_16x16x32_bf16 v[72:75], v[148:151], v[124:127], v[72:75]
	v_mfma_f32_16x16x32_bf16 v[76:79], v[148:151], v[132:135], v[76:79]
	global_load_dwordx4 v[116:119], v[26:27], off offset:192
	global_load_dwordx4 v[120:123], v[30:31], off offset:192
	global_load_dwordx4 v[124:127], v[70:71], off offset:192
	global_load_dwordx4 v[132:135], v[98:99], off offset:192
	global_load_dwordx4 v[136:139], v[130:131], off offset:192
	global_load_dwordx4 v[140:143], v[152:153], off offset:192
	global_load_dwordx4 v[144:147], v[154:155], off offset:192
	global_load_dwordx4 v[148:151], v[156:157], off offset:192
	s_waitcnt vmcnt(8)
	v_mfma_f32_16x16x32_bf16 v[4:7], v[100:103], v[80:83], v[4:7]
	v_mfma_f32_16x16x32_bf16 v[8:11], v[100:103], v[84:87], v[8:11]
	v_mfma_f32_16x16x32_bf16 v[12:15], v[100:103], v[88:91], v[12:15]
	v_mfma_f32_16x16x32_bf16 v[16:19], v[100:103], v[92:95], v[16:19]
	v_mfma_f32_16x16x32_bf16 v[20:23], v[104:107], v[80:83], v[20:23]
	v_mfma_f32_16x16x32_bf16 v[32:35], v[104:107], v[84:87], v[32:35]
	v_mfma_f32_16x16x32_bf16 v[36:39], v[104:107], v[88:91], v[36:39]
	v_mfma_f32_16x16x32_bf16 v[40:43], v[104:107], v[92:95], v[40:43]
	v_mfma_f32_16x16x32_bf16 v[44:47], v[108:111], v[80:83], v[44:47]
	v_mfma_f32_16x16x32_bf16 v[48:51], v[108:111], v[84:87], v[48:51]
	v_mfma_f32_16x16x32_bf16 v[52:55], v[108:111], v[88:91], v[52:55]
	v_mfma_f32_16x16x32_bf16 v[56:59], v[108:111], v[92:95], v[56:59]
	v_mfma_f32_16x16x32_bf16 v[60:63], v[112:115], v[80:83], v[60:63]
	v_mfma_f32_16x16x32_bf16 v[64:67], v[112:115], v[84:87], v[64:67]
	v_mfma_f32_16x16x32_bf16 v[72:75], v[112:115], v[88:91], v[72:75]
	v_mfma_f32_16x16x32_bf16 v[76:79], v[112:115], v[92:95], v[76:79]
	global_load_dwordx4 v[80:83], v[26:27], off offset:256
	global_load_dwordx4 v[84:87], v[30:31], off offset:256
	global_load_dwordx4 v[88:91], v[70:71], off offset:256
	global_load_dwordx4 v[92:95], v[98:99], off offset:256
	global_load_dwordx4 v[100:103], v[130:131], off offset:256
	global_load_dwordx4 v[104:107], v[152:153], off offset:256
	global_load_dwordx4 v[108:111], v[154:155], off offset:256
	global_load_dwordx4 v[112:115], v[156:157], off offset:256
	s_waitcnt vmcnt(8)
	v_mfma_f32_16x16x32_bf16 v[4:7], v[136:139], v[116:119], v[4:7]
	v_mfma_f32_16x16x32_bf16 v[8:11], v[136:139], v[120:123], v[8:11]
	v_mfma_f32_16x16x32_bf16 v[12:15], v[136:139], v[124:127], v[12:15]
	v_mfma_f32_16x16x32_bf16 v[16:19], v[136:139], v[132:135], v[16:19]
	v_mfma_f32_16x16x32_bf16 v[20:23], v[140:143], v[116:119], v[20:23]
	v_mfma_f32_16x16x32_bf16 v[32:35], v[140:143], v[120:123], v[32:35]
	v_mfma_f32_16x16x32_bf16 v[36:39], v[140:143], v[124:127], v[36:39]
	v_mfma_f32_16x16x32_bf16 v[40:43], v[140:143], v[132:135], v[40:43]
	v_mfma_f32_16x16x32_bf16 v[44:47], v[144:147], v[116:119], v[44:47]
	v_mfma_f32_16x16x32_bf16 v[48:51], v[144:147], v[120:123], v[48:51]
	v_mfma_f32_16x16x32_bf16 v[52:55], v[144:147], v[124:127], v[52:55]
	v_mfma_f32_16x16x32_bf16 v[56:59], v[144:147], v[132:135], v[56:59]
	v_mfma_f32_16x16x32_bf16 v[60:63], v[148:151], v[116:119], v[60:63]
	v_mfma_f32_16x16x32_bf16 v[64:67], v[148:151], v[120:123], v[64:67]
	v_mfma_f32_16x16x32_bf16 v[72:75], v[148:151], v[124:127], v[72:75]
	v_mfma_f32_16x16x32_bf16 v[76:79], v[148:151], v[132:135], v[76:79]
	global_load_dwordx4 v[116:119], v[26:27], off offset:320
	global_load_dwordx4 v[120:123], v[30:31], off offset:320
	global_load_dwordx4 v[124:127], v[70:71], off offset:320
	global_load_dwordx4 v[132:135], v[98:99], off offset:320
	global_load_dwordx4 v[136:139], v[130:131], off offset:320
	global_load_dwordx4 v[140:143], v[152:153], off offset:320
	global_load_dwordx4 v[144:147], v[154:155], off offset:320
	global_load_dwordx4 v[148:151], v[156:157], off offset:320
	s_waitcnt vmcnt(8)
	v_mfma_f32_16x16x32_bf16 v[4:7], v[100:103], v[80:83], v[4:7]
	v_mfma_f32_16x16x32_bf16 v[8:11], v[100:103], v[84:87], v[8:11]
	v_mfma_f32_16x16x32_bf16 v[12:15], v[100:103], v[88:91], v[12:15]
	v_mfma_f32_16x16x32_bf16 v[16:19], v[100:103], v[92:95], v[16:19]
	v_mfma_f32_16x16x32_bf16 v[20:23], v[104:107], v[80:83], v[20:23]
	v_mfma_f32_16x16x32_bf16 v[32:35], v[104:107], v[84:87], v[32:35]
	v_mfma_f32_16x16x32_bf16 v[36:39], v[104:107], v[88:91], v[36:39]
	v_mfma_f32_16x16x32_bf16 v[40:43], v[104:107], v[92:95], v[40:43]
	v_mfma_f32_16x16x32_bf16 v[44:47], v[108:111], v[80:83], v[44:47]
	v_mfma_f32_16x16x32_bf16 v[48:51], v[108:111], v[84:87], v[48:51]
	v_mfma_f32_16x16x32_bf16 v[52:55], v[108:111], v[88:91], v[52:55]
	v_mfma_f32_16x16x32_bf16 v[56:59], v[108:111], v[92:95], v[56:59]
	v_mfma_f32_16x16x32_bf16 v[60:63], v[112:115], v[80:83], v[60:63]
	v_mfma_f32_16x16x32_bf16 v[64:67], v[112:115], v[84:87], v[64:67]
	v_mfma_f32_16x16x32_bf16 v[72:75], v[112:115], v[88:91], v[72:75]
	v_mfma_f32_16x16x32_bf16 v[76:79], v[112:115], v[92:95], v[76:79]
	global_load_dwordx4 v[80:83], v[26:27], off offset:384
	global_load_dwordx4 v[84:87], v[30:31], off offset:384
	global_load_dwordx4 v[88:91], v[70:71], off offset:384
	global_load_dwordx4 v[92:95], v[98:99], off offset:384
	global_load_dwordx4 v[100:103], v[130:131], off offset:384
	global_load_dwordx4 v[104:107], v[152:153], off offset:384
	global_load_dwordx4 v[108:111], v[154:155], off offset:384
	global_load_dwordx4 v[112:115], v[156:157], off offset:384
	s_waitcnt vmcnt(8)
	v_mfma_f32_16x16x32_bf16 v[4:7], v[136:139], v[116:119], v[4:7]
	v_mfma_f32_16x16x32_bf16 v[8:11], v[136:139], v[120:123], v[8:11]
	v_mfma_f32_16x16x32_bf16 v[12:15], v[136:139], v[124:127], v[12:15]
	v_mfma_f32_16x16x32_bf16 v[16:19], v[136:139], v[132:135], v[16:19]
	v_mfma_f32_16x16x32_bf16 v[20:23], v[140:143], v[116:119], v[20:23]
	v_mfma_f32_16x16x32_bf16 v[32:35], v[140:143], v[120:123], v[32:35]
	v_mfma_f32_16x16x32_bf16 v[36:39], v[140:143], v[124:127], v[36:39]
	v_mfma_f32_16x16x32_bf16 v[40:43], v[140:143], v[132:135], v[40:43]
	v_mfma_f32_16x16x32_bf16 v[44:47], v[144:147], v[116:119], v[44:47]
	v_mfma_f32_16x16x32_bf16 v[48:51], v[144:147], v[120:123], v[48:51]
	v_mfma_f32_16x16x32_bf16 v[52:55], v[144:147], v[124:127], v[52:55]
	v_mfma_f32_16x16x32_bf16 v[56:59], v[144:147], v[132:135], v[56:59]
	v_mfma_f32_16x16x32_bf16 v[60:63], v[148:151], v[116:119], v[60:63]
	v_mfma_f32_16x16x32_bf16 v[64:67], v[148:151], v[120:123], v[64:67]
	v_mfma_f32_16x16x32_bf16 v[72:75], v[148:151], v[124:127], v[72:75]
	v_mfma_f32_16x16x32_bf16 v[76:79], v[148:151], v[132:135], v[76:79]
	global_load_dwordx4 v[116:119], v[26:27], off offset:448
	global_load_dwordx4 v[120:123], v[30:31], off offset:448
	global_load_dwordx4 v[124:127], v[70:71], off offset:448
	global_load_dwordx4 v[132:135], v[98:99], off offset:448
	global_load_dwordx4 v[136:139], v[130:131], off offset:448
	global_load_dwordx4 v[140:143], v[152:153], off offset:448
	global_load_dwordx4 v[144:147], v[154:155], off offset:448
	global_load_dwordx4 v[148:151], v[156:157], off offset:448
	s_waitcnt vmcnt(8)
	v_mfma_f32_16x16x32_bf16 v[4:7], v[100:103], v[80:83], v[4:7]
	v_mfma_f32_16x16x32_bf16 v[8:11], v[100:103], v[84:87], v[8:11]
	v_mfma_f32_16x16x32_bf16 v[12:15], v[100:103], v[88:91], v[12:15]
	v_mfma_f32_16x16x32_bf16 v[16:19], v[100:103], v[92:95], v[16:19]
	v_mfma_f32_16x16x32_bf16 v[20:23], v[104:107], v[80:83], v[20:23]
	v_mfma_f32_16x16x32_bf16 v[32:35], v[104:107], v[84:87], v[32:35]
	v_mfma_f32_16x16x32_bf16 v[36:39], v[104:107], v[88:91], v[36:39]
	v_mfma_f32_16x16x32_bf16 v[40:43], v[104:107], v[92:95], v[40:43]
	v_mfma_f32_16x16x32_bf16 v[44:47], v[108:111], v[80:83], v[44:47]
	v_mfma_f32_16x16x32_bf16 v[48:51], v[108:111], v[84:87], v[48:51]
	v_mfma_f32_16x16x32_bf16 v[52:55], v[108:111], v[88:91], v[52:55]
	v_mfma_f32_16x16x32_bf16 v[56:59], v[108:111], v[92:95], v[56:59]
	v_mfma_f32_16x16x32_bf16 v[60:63], v[112:115], v[80:83], v[60:63]
	v_mfma_f32_16x16x32_bf16 v[64:67], v[112:115], v[84:87], v[64:67]
	v_mfma_f32_16x16x32_bf16 v[72:75], v[112:115], v[88:91], v[72:75]
	v_mfma_f32_16x16x32_bf16 v[76:79], v[112:115], v[92:95], v[76:79]
	global_load_dwordx4 v[80:83], v[26:27], off offset:512
	global_load_dwordx4 v[84:87], v[30:31], off offset:512
	global_load_dwordx4 v[88:91], v[70:71], off offset:512
	global_load_dwordx4 v[92:95], v[98:99], off offset:512
	global_load_dwordx4 v[100:103], v[130:131], off offset:512
	global_load_dwordx4 v[104:107], v[152:153], off offset:512
	global_load_dwordx4 v[108:111], v[154:155], off offset:512
	global_load_dwordx4 v[112:115], v[156:157], off offset:512
	s_waitcnt vmcnt(8)
	v_mfma_f32_16x16x32_bf16 v[4:7], v[136:139], v[116:119], v[4:7]
	v_mfma_f32_16x16x32_bf16 v[8:11], v[136:139], v[120:123], v[8:11]
	v_mfma_f32_16x16x32_bf16 v[12:15], v[136:139], v[124:127], v[12:15]
	v_mfma_f32_16x16x32_bf16 v[16:19], v[136:139], v[132:135], v[16:19]
	v_mfma_f32_16x16x32_bf16 v[20:23], v[140:143], v[116:119], v[20:23]
	v_mfma_f32_16x16x32_bf16 v[32:35], v[140:143], v[120:123], v[32:35]
	v_mfma_f32_16x16x32_bf16 v[36:39], v[140:143], v[124:127], v[36:39]
	v_mfma_f32_16x16x32_bf16 v[40:43], v[140:143], v[132:135], v[40:43]
	v_mfma_f32_16x16x32_bf16 v[44:47], v[144:147], v[116:119], v[44:47]
	v_mfma_f32_16x16x32_bf16 v[48:51], v[144:147], v[120:123], v[48:51]
	v_mfma_f32_16x16x32_bf16 v[52:55], v[144:147], v[124:127], v[52:55]
	v_mfma_f32_16x16x32_bf16 v[56:59], v[144:147], v[132:135], v[56:59]
	v_mfma_f32_16x16x32_bf16 v[60:63], v[148:151], v[116:119], v[60:63]
	v_mfma_f32_16x16x32_bf16 v[64:67], v[148:151], v[120:123], v[64:67]
	v_mfma_f32_16x16x32_bf16 v[72:75], v[148:151], v[124:127], v[72:75]
	v_mfma_f32_16x16x32_bf16 v[76:79], v[148:151], v[132:135], v[76:79]
	global_load_dwordx4 v[116:119], v[26:27], off offset:576
	global_load_dwordx4 v[120:123], v[30:31], off offset:576
	global_load_dwordx4 v[124:127], v[70:71], off offset:576
	global_load_dwordx4 v[132:135], v[98:99], off offset:576
	global_load_dwordx4 v[136:139], v[130:131], off offset:576
	global_load_dwordx4 v[140:143], v[152:153], off offset:576
	global_load_dwordx4 v[144:147], v[154:155], off offset:576
	global_load_dwordx4 v[148:151], v[156:157], off offset:576
	s_waitcnt vmcnt(8)
	v_mfma_f32_16x16x32_bf16 v[4:7], v[100:103], v[80:83], v[4:7]
	v_mfma_f32_16x16x32_bf16 v[8:11], v[100:103], v[84:87], v[8:11]
	v_mfma_f32_16x16x32_bf16 v[12:15], v[100:103], v[88:91], v[12:15]
	v_mfma_f32_16x16x32_bf16 v[16:19], v[100:103], v[92:95], v[16:19]
	v_mfma_f32_16x16x32_bf16 v[20:23], v[104:107], v[80:83], v[20:23]
	v_mfma_f32_16x16x32_bf16 v[32:35], v[104:107], v[84:87], v[32:35]
	v_mfma_f32_16x16x32_bf16 v[36:39], v[104:107], v[88:91], v[36:39]
	v_mfma_f32_16x16x32_bf16 v[40:43], v[104:107], v[92:95], v[40:43]
	v_mfma_f32_16x16x32_bf16 v[44:47], v[108:111], v[80:83], v[44:47]
	v_mfma_f32_16x16x32_bf16 v[48:51], v[108:111], v[84:87], v[48:51]
	v_mfma_f32_16x16x32_bf16 v[52:55], v[108:111], v[88:91], v[52:55]
	v_mfma_f32_16x16x32_bf16 v[56:59], v[108:111], v[92:95], v[56:59]
	v_mfma_f32_16x16x32_bf16 v[60:63], v[112:115], v[80:83], v[60:63]
	v_mfma_f32_16x16x32_bf16 v[64:67], v[112:115], v[84:87], v[64:67]
	v_mfma_f32_16x16x32_bf16 v[72:75], v[112:115], v[88:91], v[72:75]
	v_mfma_f32_16x16x32_bf16 v[76:79], v[112:115], v[92:95], v[76:79]
	global_load_dwordx4 v[80:83], v[26:27], off offset:640
	global_load_dwordx4 v[84:87], v[30:31], off offset:640
	global_load_dwordx4 v[88:91], v[70:71], off offset:640
	global_load_dwordx4 v[92:95], v[98:99], off offset:640
	global_load_dwordx4 v[100:103], v[130:131], off offset:640
	global_load_dwordx4 v[104:107], v[152:153], off offset:640
	global_load_dwordx4 v[108:111], v[154:155], off offset:640
	global_load_dwordx4 v[112:115], v[156:157], off offset:640
	s_waitcnt vmcnt(8)
	v_mfma_f32_16x16x32_bf16 v[4:7], v[136:139], v[116:119], v[4:7]
	v_mfma_f32_16x16x32_bf16 v[8:11], v[136:139], v[120:123], v[8:11]
	v_mfma_f32_16x16x32_bf16 v[12:15], v[136:139], v[124:127], v[12:15]
	v_mfma_f32_16x16x32_bf16 v[16:19], v[136:139], v[132:135], v[16:19]
	v_mfma_f32_16x16x32_bf16 v[20:23], v[140:143], v[116:119], v[20:23]
	v_mfma_f32_16x16x32_bf16 v[32:35], v[140:143], v[120:123], v[32:35]
	v_mfma_f32_16x16x32_bf16 v[36:39], v[140:143], v[124:127], v[36:39]
	v_mfma_f32_16x16x32_bf16 v[40:43], v[140:143], v[132:135], v[40:43]
	v_mfma_f32_16x16x32_bf16 v[44:47], v[144:147], v[116:119], v[44:47]
	v_mfma_f32_16x16x32_bf16 v[48:51], v[144:147], v[120:123], v[48:51]
	v_mfma_f32_16x16x32_bf16 v[52:55], v[144:147], v[124:127], v[52:55]
	v_mfma_f32_16x16x32_bf16 v[56:59], v[144:147], v[132:135], v[56:59]
	v_mfma_f32_16x16x32_bf16 v[60:63], v[148:151], v[116:119], v[60:63]
	v_mfma_f32_16x16x32_bf16 v[64:67], v[148:151], v[120:123], v[64:67]
	v_mfma_f32_16x16x32_bf16 v[72:75], v[148:151], v[124:127], v[72:75]
	v_mfma_f32_16x16x32_bf16 v[76:79], v[148:151], v[132:135], v[76:79]
	global_load_dwordx4 v[116:119], v[26:27], off offset:704
	global_load_dwordx4 v[120:123], v[30:31], off offset:704
	global_load_dwordx4 v[124:127], v[70:71], off offset:704
	global_load_dwordx4 v[132:135], v[98:99], off offset:704
	global_load_dwordx4 v[136:139], v[130:131], off offset:704
	global_load_dwordx4 v[140:143], v[152:153], off offset:704
	global_load_dwordx4 v[144:147], v[154:155], off offset:704
	global_load_dwordx4 v[148:151], v[156:157], off offset:704
	s_waitcnt vmcnt(8)
	v_mfma_f32_16x16x32_bf16 v[4:7], v[100:103], v[80:83], v[4:7]
	v_mfma_f32_16x16x32_bf16 v[8:11], v[100:103], v[84:87], v[8:11]
	v_mfma_f32_16x16x32_bf16 v[12:15], v[100:103], v[88:91], v[12:15]
	v_mfma_f32_16x16x32_bf16 v[16:19], v[100:103], v[92:95], v[16:19]
	v_mfma_f32_16x16x32_bf16 v[20:23], v[104:107], v[80:83], v[20:23]
	v_mfma_f32_16x16x32_bf16 v[32:35], v[104:107], v[84:87], v[32:35]
	v_mfma_f32_16x16x32_bf16 v[36:39], v[104:107], v[88:91], v[36:39]
	v_mfma_f32_16x16x32_bf16 v[40:43], v[104:107], v[92:95], v[40:43]
	v_mfma_f32_16x16x32_bf16 v[44:47], v[108:111], v[80:83], v[44:47]
	v_mfma_f32_16x16x32_bf16 v[48:51], v[108:111], v[84:87], v[48:51]
	v_mfma_f32_16x16x32_bf16 v[52:55], v[108:111], v[88:91], v[52:55]
	v_mfma_f32_16x16x32_bf16 v[56:59], v[108:111], v[92:95], v[56:59]
	v_mfma_f32_16x16x32_bf16 v[60:63], v[112:115], v[80:83], v[60:63]
	v_mfma_f32_16x16x32_bf16 v[64:67], v[112:115], v[84:87], v[64:67]
	v_mfma_f32_16x16x32_bf16 v[72:75], v[112:115], v[88:91], v[72:75]
	v_mfma_f32_16x16x32_bf16 v[76:79], v[112:115], v[92:95], v[76:79]
	global_load_dwordx4 v[80:83], v[26:27], off offset:768
	global_load_dwordx4 v[84:87], v[30:31], off offset:768
	global_load_dwordx4 v[88:91], v[70:71], off offset:768
	global_load_dwordx4 v[92:95], v[98:99], off offset:768
	global_load_dwordx4 v[100:103], v[130:131], off offset:768
	global_load_dwordx4 v[104:107], v[152:153], off offset:768
	global_load_dwordx4 v[108:111], v[154:155], off offset:768
	global_load_dwordx4 v[112:115], v[156:157], off offset:768
	s_waitcnt vmcnt(8)
	v_mfma_f32_16x16x32_bf16 v[4:7], v[136:139], v[116:119], v[4:7]
	v_mfma_f32_16x16x32_bf16 v[8:11], v[136:139], v[120:123], v[8:11]
	v_mfma_f32_16x16x32_bf16 v[12:15], v[136:139], v[124:127], v[12:15]
	v_mfma_f32_16x16x32_bf16 v[16:19], v[136:139], v[132:135], v[16:19]
	v_mfma_f32_16x16x32_bf16 v[20:23], v[140:143], v[116:119], v[20:23]
	v_mfma_f32_16x16x32_bf16 v[32:35], v[140:143], v[120:123], v[32:35]
	v_mfma_f32_16x16x32_bf16 v[36:39], v[140:143], v[124:127], v[36:39]
	v_mfma_f32_16x16x32_bf16 v[40:43], v[140:143], v[132:135], v[40:43]
	v_mfma_f32_16x16x32_bf16 v[44:47], v[144:147], v[116:119], v[44:47]
	v_mfma_f32_16x16x32_bf16 v[48:51], v[144:147], v[120:123], v[48:51]
	v_mfma_f32_16x16x32_bf16 v[52:55], v[144:147], v[124:127], v[52:55]
	v_mfma_f32_16x16x32_bf16 v[56:59], v[144:147], v[132:135], v[56:59]
	v_mfma_f32_16x16x32_bf16 v[60:63], v[148:151], v[116:119], v[60:63]
	v_mfma_f32_16x16x32_bf16 v[64:67], v[148:151], v[120:123], v[64:67]
	v_mfma_f32_16x16x32_bf16 v[72:75], v[148:151], v[124:127], v[72:75]
	v_mfma_f32_16x16x32_bf16 v[76:79], v[148:151], v[132:135], v[76:79]
	global_load_dwordx4 v[116:119], v[26:27], off offset:832
	global_load_dwordx4 v[120:123], v[30:31], off offset:832
	global_load_dwordx4 v[124:127], v[70:71], off offset:832
	global_load_dwordx4 v[132:135], v[98:99], off offset:832
	global_load_dwordx4 v[136:139], v[130:131], off offset:832
	global_load_dwordx4 v[140:143], v[152:153], off offset:832
	global_load_dwordx4 v[144:147], v[154:155], off offset:832
	global_load_dwordx4 v[148:151], v[156:157], off offset:832
	s_waitcnt vmcnt(8)
	v_mfma_f32_16x16x32_bf16 v[4:7], v[100:103], v[80:83], v[4:7]
	v_mfma_f32_16x16x32_bf16 v[8:11], v[100:103], v[84:87], v[8:11]
	v_mfma_f32_16x16x32_bf16 v[12:15], v[100:103], v[88:91], v[12:15]
	v_mfma_f32_16x16x32_bf16 v[16:19], v[100:103], v[92:95], v[16:19]
	v_mfma_f32_16x16x32_bf16 v[20:23], v[104:107], v[80:83], v[20:23]
	v_mfma_f32_16x16x32_bf16 v[32:35], v[104:107], v[84:87], v[32:35]
	v_mfma_f32_16x16x32_bf16 v[36:39], v[104:107], v[88:91], v[36:39]
	v_mfma_f32_16x16x32_bf16 v[40:43], v[104:107], v[92:95], v[40:43]
	v_mfma_f32_16x16x32_bf16 v[44:47], v[108:111], v[80:83], v[44:47]
	v_mfma_f32_16x16x32_bf16 v[48:51], v[108:111], v[84:87], v[48:51]
	v_mfma_f32_16x16x32_bf16 v[52:55], v[108:111], v[88:91], v[52:55]
	v_mfma_f32_16x16x32_bf16 v[56:59], v[108:111], v[92:95], v[56:59]
	v_mfma_f32_16x16x32_bf16 v[60:63], v[112:115], v[80:83], v[60:63]
	v_mfma_f32_16x16x32_bf16 v[64:67], v[112:115], v[84:87], v[64:67]
	v_mfma_f32_16x16x32_bf16 v[72:75], v[112:115], v[88:91], v[72:75]
	v_mfma_f32_16x16x32_bf16 v[76:79], v[112:115], v[92:95], v[76:79]
	global_load_dwordx4 v[80:83], v[26:27], off offset:896
	global_load_dwordx4 v[84:87], v[30:31], off offset:896
	global_load_dwordx4 v[88:91], v[70:71], off offset:896
	global_load_dwordx4 v[92:95], v[98:99], off offset:896
	global_load_dwordx4 v[100:103], v[130:131], off offset:896
	global_load_dwordx4 v[104:107], v[152:153], off offset:896
	global_load_dwordx4 v[108:111], v[154:155], off offset:896
	global_load_dwordx4 v[112:115], v[156:157], off offset:896
	s_waitcnt vmcnt(8)
	v_mfma_f32_16x16x32_bf16 v[4:7], v[136:139], v[116:119], v[4:7]
	v_mfma_f32_16x16x32_bf16 v[8:11], v[136:139], v[120:123], v[8:11]
	v_mfma_f32_16x16x32_bf16 v[12:15], v[136:139], v[124:127], v[12:15]
	v_mfma_f32_16x16x32_bf16 v[16:19], v[136:139], v[132:135], v[16:19]
	v_mfma_f32_16x16x32_bf16 v[20:23], v[140:143], v[116:119], v[20:23]
	v_mfma_f32_16x16x32_bf16 v[32:35], v[140:143], v[120:123], v[32:35]
	v_mfma_f32_16x16x32_bf16 v[36:39], v[140:143], v[124:127], v[36:39]
	v_mfma_f32_16x16x32_bf16 v[40:43], v[140:143], v[132:135], v[40:43]
	v_mfma_f32_16x16x32_bf16 v[44:47], v[144:147], v[116:119], v[44:47]
	v_mfma_f32_16x16x32_bf16 v[48:51], v[144:147], v[120:123], v[48:51]
	v_mfma_f32_16x16x32_bf16 v[52:55], v[144:147], v[124:127], v[52:55]
	v_mfma_f32_16x16x32_bf16 v[56:59], v[144:147], v[132:135], v[56:59]
	v_mfma_f32_16x16x32_bf16 v[60:63], v[148:151], v[116:119], v[60:63]
	v_mfma_f32_16x16x32_bf16 v[64:67], v[148:151], v[120:123], v[64:67]
	v_mfma_f32_16x16x32_bf16 v[72:75], v[148:151], v[124:127], v[72:75]
	v_mfma_f32_16x16x32_bf16 v[76:79], v[148:151], v[132:135], v[76:79]
	global_load_dwordx4 v[116:119], v[26:27], off offset:960
	global_load_dwordx4 v[120:123], v[30:31], off offset:960
	global_load_dwordx4 v[124:127], v[70:71], off offset:960
	global_load_dwordx4 v[132:135], v[98:99], off offset:960
	global_load_dwordx4 v[136:139], v[130:131], off offset:960
	global_load_dwordx4 v[140:143], v[152:153], off offset:960
	global_load_dwordx4 v[144:147], v[154:155], off offset:960
	global_load_dwordx4 v[148:151], v[156:157], off offset:960
	s_waitcnt vmcnt(8)
	v_mfma_f32_16x16x32_bf16 v[4:7], v[100:103], v[80:83], v[4:7]
	v_mfma_f32_16x16x32_bf16 v[8:11], v[100:103], v[84:87], v[8:11]
	v_mfma_f32_16x16x32_bf16 v[12:15], v[100:103], v[88:91], v[12:15]
	v_mfma_f32_16x16x32_bf16 v[16:19], v[100:103], v[92:95], v[16:19]
	v_mfma_f32_16x16x32_bf16 v[20:23], v[104:107], v[80:83], v[20:23]
	v_mfma_f32_16x16x32_bf16 v[32:35], v[104:107], v[84:87], v[32:35]
	v_mfma_f32_16x16x32_bf16 v[36:39], v[104:107], v[88:91], v[36:39]
	v_mfma_f32_16x16x32_bf16 v[40:43], v[104:107], v[92:95], v[40:43]
	v_mfma_f32_16x16x32_bf16 v[44:47], v[108:111], v[80:83], v[44:47]
	v_mfma_f32_16x16x32_bf16 v[48:51], v[108:111], v[84:87], v[48:51]
	v_mfma_f32_16x16x32_bf16 v[52:55], v[108:111], v[88:91], v[52:55]
	v_mfma_f32_16x16x32_bf16 v[56:59], v[108:111], v[92:95], v[56:59]
	v_mfma_f32_16x16x32_bf16 v[60:63], v[112:115], v[80:83], v[60:63]
	v_mfma_f32_16x16x32_bf16 v[64:67], v[112:115], v[84:87], v[64:67]
	v_mfma_f32_16x16x32_bf16 v[72:75], v[112:115], v[88:91], v[72:75]
	v_mfma_f32_16x16x32_bf16 v[76:79], v[112:115], v[92:95], v[76:79]
	global_load_dwordx4 v[80:83], v[26:27], off offset:1024
	global_load_dwordx4 v[84:87], v[30:31], off offset:1024
	global_load_dwordx4 v[88:91], v[70:71], off offset:1024
	global_load_dwordx4 v[92:95], v[98:99], off offset:1024
	global_load_dwordx4 v[100:103], v[130:131], off offset:1024
	global_load_dwordx4 v[104:107], v[152:153], off offset:1024
	global_load_dwordx4 v[108:111], v[154:155], off offset:1024
	global_load_dwordx4 v[112:115], v[156:157], off offset:1024
	s_waitcnt vmcnt(8)
	v_mfma_f32_16x16x32_bf16 v[4:7], v[136:139], v[116:119], v[4:7]
	v_mfma_f32_16x16x32_bf16 v[8:11], v[136:139], v[120:123], v[8:11]
	v_mfma_f32_16x16x32_bf16 v[12:15], v[136:139], v[124:127], v[12:15]
	v_mfma_f32_16x16x32_bf16 v[16:19], v[136:139], v[132:135], v[16:19]
	v_mfma_f32_16x16x32_bf16 v[20:23], v[140:143], v[116:119], v[20:23]
	v_mfma_f32_16x16x32_bf16 v[32:35], v[140:143], v[120:123], v[32:35]
	v_mfma_f32_16x16x32_bf16 v[36:39], v[140:143], v[124:127], v[36:39]
	v_mfma_f32_16x16x32_bf16 v[40:43], v[140:143], v[132:135], v[40:43]
	v_mfma_f32_16x16x32_bf16 v[44:47], v[144:147], v[116:119], v[44:47]
	v_mfma_f32_16x16x32_bf16 v[48:51], v[144:147], v[120:123], v[48:51]
	v_mfma_f32_16x16x32_bf16 v[52:55], v[144:147], v[124:127], v[52:55]
	v_mfma_f32_16x16x32_bf16 v[56:59], v[144:147], v[132:135], v[56:59]
	v_mfma_f32_16x16x32_bf16 v[60:63], v[148:151], v[116:119], v[60:63]
	v_mfma_f32_16x16x32_bf16 v[64:67], v[148:151], v[120:123], v[64:67]
	v_mfma_f32_16x16x32_bf16 v[72:75], v[148:151], v[124:127], v[72:75]
	v_mfma_f32_16x16x32_bf16 v[76:79], v[148:151], v[132:135], v[76:79]
	global_load_dwordx4 v[116:119], v[26:27], off offset:1088
	global_load_dwordx4 v[120:123], v[30:31], off offset:1088
	global_load_dwordx4 v[124:127], v[70:71], off offset:1088
	global_load_dwordx4 v[132:135], v[98:99], off offset:1088
	global_load_dwordx4 v[136:139], v[130:131], off offset:1088
	global_load_dwordx4 v[140:143], v[152:153], off offset:1088
	global_load_dwordx4 v[144:147], v[154:155], off offset:1088
	global_load_dwordx4 v[148:151], v[156:157], off offset:1088
	s_waitcnt vmcnt(8)
	v_mfma_f32_16x16x32_bf16 v[4:7], v[100:103], v[80:83], v[4:7]
	v_mfma_f32_16x16x32_bf16 v[8:11], v[100:103], v[84:87], v[8:11]
	v_mfma_f32_16x16x32_bf16 v[12:15], v[100:103], v[88:91], v[12:15]
	v_mfma_f32_16x16x32_bf16 v[16:19], v[100:103], v[92:95], v[16:19]
	v_mfma_f32_16x16x32_bf16 v[20:23], v[104:107], v[80:83], v[20:23]
	v_mfma_f32_16x16x32_bf16 v[32:35], v[104:107], v[84:87], v[32:35]
	v_mfma_f32_16x16x32_bf16 v[36:39], v[104:107], v[88:91], v[36:39]
	v_mfma_f32_16x16x32_bf16 v[40:43], v[104:107], v[92:95], v[40:43]
	v_mfma_f32_16x16x32_bf16 v[44:47], v[108:111], v[80:83], v[44:47]
	v_mfma_f32_16x16x32_bf16 v[48:51], v[108:111], v[84:87], v[48:51]
	v_mfma_f32_16x16x32_bf16 v[52:55], v[108:111], v[88:91], v[52:55]
	v_mfma_f32_16x16x32_bf16 v[56:59], v[108:111], v[92:95], v[56:59]
	v_mfma_f32_16x16x32_bf16 v[60:63], v[112:115], v[80:83], v[60:63]
	v_mfma_f32_16x16x32_bf16 v[64:67], v[112:115], v[84:87], v[64:67]
	v_mfma_f32_16x16x32_bf16 v[72:75], v[112:115], v[88:91], v[72:75]
	v_mfma_f32_16x16x32_bf16 v[76:79], v[112:115], v[92:95], v[76:79]
	global_load_dwordx4 v[80:83], v[26:27], off offset:1152
	global_load_dwordx4 v[84:87], v[30:31], off offset:1152
	global_load_dwordx4 v[88:91], v[70:71], off offset:1152
	global_load_dwordx4 v[92:95], v[98:99], off offset:1152
	global_load_dwordx4 v[100:103], v[130:131], off offset:1152
	global_load_dwordx4 v[104:107], v[152:153], off offset:1152
	global_load_dwordx4 v[108:111], v[154:155], off offset:1152
	global_load_dwordx4 v[112:115], v[156:157], off offset:1152
	s_waitcnt vmcnt(8)
	v_mfma_f32_16x16x32_bf16 v[4:7], v[136:139], v[116:119], v[4:7]
	v_mfma_f32_16x16x32_bf16 v[8:11], v[136:139], v[120:123], v[8:11]
	v_mfma_f32_16x16x32_bf16 v[12:15], v[136:139], v[124:127], v[12:15]
	v_mfma_f32_16x16x32_bf16 v[16:19], v[136:139], v[132:135], v[16:19]
	v_mfma_f32_16x16x32_bf16 v[20:23], v[140:143], v[116:119], v[20:23]
	v_mfma_f32_16x16x32_bf16 v[32:35], v[140:143], v[120:123], v[32:35]
	v_mfma_f32_16x16x32_bf16 v[36:39], v[140:143], v[124:127], v[36:39]
	v_mfma_f32_16x16x32_bf16 v[40:43], v[140:143], v[132:135], v[40:43]
	v_mfma_f32_16x16x32_bf16 v[44:47], v[144:147], v[116:119], v[44:47]
	v_mfma_f32_16x16x32_bf16 v[48:51], v[144:147], v[120:123], v[48:51]
	v_mfma_f32_16x16x32_bf16 v[52:55], v[144:147], v[124:127], v[52:55]
	v_mfma_f32_16x16x32_bf16 v[56:59], v[144:147], v[132:135], v[56:59]
	v_mfma_f32_16x16x32_bf16 v[60:63], v[148:151], v[116:119], v[60:63]
	v_mfma_f32_16x16x32_bf16 v[64:67], v[148:151], v[120:123], v[64:67]
	v_mfma_f32_16x16x32_bf16 v[72:75], v[148:151], v[124:127], v[72:75]
	v_mfma_f32_16x16x32_bf16 v[76:79], v[148:151], v[132:135], v[76:79]
	global_load_dwordx4 v[116:119], v[26:27], off offset:1216
	global_load_dwordx4 v[120:123], v[30:31], off offset:1216
	global_load_dwordx4 v[124:127], v[70:71], off offset:1216
	global_load_dwordx4 v[132:135], v[98:99], off offset:1216
	global_load_dwordx4 v[136:139], v[130:131], off offset:1216
	global_load_dwordx4 v[140:143], v[152:153], off offset:1216
	global_load_dwordx4 v[144:147], v[154:155], off offset:1216
	global_load_dwordx4 v[148:151], v[156:157], off offset:1216
	s_waitcnt vmcnt(8)
	v_mfma_f32_16x16x32_bf16 v[4:7], v[100:103], v[80:83], v[4:7]
	v_mfma_f32_16x16x32_bf16 v[8:11], v[100:103], v[84:87], v[8:11]
	v_mfma_f32_16x16x32_bf16 v[12:15], v[100:103], v[88:91], v[12:15]
	v_mfma_f32_16x16x32_bf16 v[16:19], v[100:103], v[92:95], v[16:19]
	v_mfma_f32_16x16x32_bf16 v[20:23], v[104:107], v[80:83], v[20:23]
	v_mfma_f32_16x16x32_bf16 v[32:35], v[104:107], v[84:87], v[32:35]
	v_mfma_f32_16x16x32_bf16 v[36:39], v[104:107], v[88:91], v[36:39]
	v_mfma_f32_16x16x32_bf16 v[40:43], v[104:107], v[92:95], v[40:43]
	v_mfma_f32_16x16x32_bf16 v[44:47], v[108:111], v[80:83], v[44:47]
	v_mfma_f32_16x16x32_bf16 v[48:51], v[108:111], v[84:87], v[48:51]
	v_mfma_f32_16x16x32_bf16 v[52:55], v[108:111], v[88:91], v[52:55]
	v_mfma_f32_16x16x32_bf16 v[56:59], v[108:111], v[92:95], v[56:59]
	v_mfma_f32_16x16x32_bf16 v[60:63], v[112:115], v[80:83], v[60:63]
	v_mfma_f32_16x16x32_bf16 v[64:67], v[112:115], v[84:87], v[64:67]
	v_mfma_f32_16x16x32_bf16 v[72:75], v[112:115], v[88:91], v[72:75]
	v_mfma_f32_16x16x32_bf16 v[76:79], v[112:115], v[92:95], v[76:79]
	global_load_dwordx4 v[80:83], v[26:27], off offset:1280
	global_load_dwordx4 v[84:87], v[30:31], off offset:1280
	global_load_dwordx4 v[88:91], v[70:71], off offset:1280
	global_load_dwordx4 v[92:95], v[98:99], off offset:1280
	global_load_dwordx4 v[100:103], v[130:131], off offset:1280
	global_load_dwordx4 v[104:107], v[152:153], off offset:1280
	global_load_dwordx4 v[108:111], v[154:155], off offset:1280
	global_load_dwordx4 v[112:115], v[156:157], off offset:1280
	s_waitcnt vmcnt(8)
	v_mfma_f32_16x16x32_bf16 v[4:7], v[136:139], v[116:119], v[4:7]
	v_mfma_f32_16x16x32_bf16 v[8:11], v[136:139], v[120:123], v[8:11]
	v_mfma_f32_16x16x32_bf16 v[12:15], v[136:139], v[124:127], v[12:15]
	v_mfma_f32_16x16x32_bf16 v[16:19], v[136:139], v[132:135], v[16:19]
	v_mfma_f32_16x16x32_bf16 v[20:23], v[140:143], v[116:119], v[20:23]
	v_mfma_f32_16x16x32_bf16 v[32:35], v[140:143], v[120:123], v[32:35]
	v_mfma_f32_16x16x32_bf16 v[36:39], v[140:143], v[124:127], v[36:39]
	v_mfma_f32_16x16x32_bf16 v[40:43], v[140:143], v[132:135], v[40:43]
	v_mfma_f32_16x16x32_bf16 v[44:47], v[144:147], v[116:119], v[44:47]
	v_mfma_f32_16x16x32_bf16 v[48:51], v[144:147], v[120:123], v[48:51]
	v_mfma_f32_16x16x32_bf16 v[52:55], v[144:147], v[124:127], v[52:55]
	v_mfma_f32_16x16x32_bf16 v[56:59], v[144:147], v[132:135], v[56:59]
	v_mfma_f32_16x16x32_bf16 v[60:63], v[148:151], v[116:119], v[60:63]
	v_mfma_f32_16x16x32_bf16 v[64:67], v[148:151], v[120:123], v[64:67]
	v_mfma_f32_16x16x32_bf16 v[72:75], v[148:151], v[124:127], v[72:75]
	v_mfma_f32_16x16x32_bf16 v[76:79], v[148:151], v[132:135], v[76:79]
	global_load_dwordx4 v[116:119], v[26:27], off offset:1344
	global_load_dwordx4 v[120:123], v[30:31], off offset:1344
	global_load_dwordx4 v[124:127], v[70:71], off offset:1344
	global_load_dwordx4 v[132:135], v[98:99], off offset:1344
	global_load_dwordx4 v[136:139], v[130:131], off offset:1344
	global_load_dwordx4 v[140:143], v[152:153], off offset:1344
	global_load_dwordx4 v[144:147], v[154:155], off offset:1344
	global_load_dwordx4 v[148:151], v[156:157], off offset:1344
	s_waitcnt vmcnt(8)
	v_mfma_f32_16x16x32_bf16 v[4:7], v[100:103], v[80:83], v[4:7]
	v_mfma_f32_16x16x32_bf16 v[8:11], v[100:103], v[84:87], v[8:11]
	v_mfma_f32_16x16x32_bf16 v[12:15], v[100:103], v[88:91], v[12:15]
	v_mfma_f32_16x16x32_bf16 v[16:19], v[100:103], v[92:95], v[16:19]
	v_mfma_f32_16x16x32_bf16 v[20:23], v[104:107], v[80:83], v[20:23]
	v_mfma_f32_16x16x32_bf16 v[32:35], v[104:107], v[84:87], v[32:35]
	v_mfma_f32_16x16x32_bf16 v[36:39], v[104:107], v[88:91], v[36:39]
	v_mfma_f32_16x16x32_bf16 v[40:43], v[104:107], v[92:95], v[40:43]
	v_mfma_f32_16x16x32_bf16 v[44:47], v[108:111], v[80:83], v[44:47]
	v_mfma_f32_16x16x32_bf16 v[48:51], v[108:111], v[84:87], v[48:51]
	v_mfma_f32_16x16x32_bf16 v[52:55], v[108:111], v[88:91], v[52:55]
	v_mfma_f32_16x16x32_bf16 v[56:59], v[108:111], v[92:95], v[56:59]
	v_mfma_f32_16x16x32_bf16 v[60:63], v[112:115], v[80:83], v[60:63]
	v_mfma_f32_16x16x32_bf16 v[64:67], v[112:115], v[84:87], v[64:67]
	v_mfma_f32_16x16x32_bf16 v[72:75], v[112:115], v[88:91], v[72:75]
	v_mfma_f32_16x16x32_bf16 v[76:79], v[112:115], v[92:95], v[76:79]
	s_waitcnt vmcnt(0)
	v_mfma_f32_16x16x32_bf16 v[4:7], v[136:139], v[116:119], v[4:7]
	v_mfma_f32_16x16x32_bf16 v[8:11], v[136:139], v[120:123], v[8:11]
	v_mfma_f32_16x16x32_bf16 v[12:15], v[136:139], v[124:127], v[12:15]
	v_mfma_f32_16x16x32_bf16 v[16:19], v[136:139], v[132:135], v[16:19]
	v_mfma_f32_16x16x32_bf16 v[20:23], v[140:143], v[116:119], v[20:23]
	v_mfma_f32_16x16x32_bf16 v[32:35], v[140:143], v[120:123], v[32:35]
	v_mfma_f32_16x16x32_bf16 v[36:39], v[140:143], v[124:127], v[36:39]
	v_mfma_f32_16x16x32_bf16 v[40:43], v[140:143], v[132:135], v[40:43]
	v_mfma_f32_16x16x32_bf16 v[44:47], v[144:147], v[116:119], v[44:47]
	v_mfma_f32_16x16x32_bf16 v[48:51], v[144:147], v[120:123], v[48:51]
	v_mfma_f32_16x16x32_bf16 v[52:55], v[144:147], v[124:127], v[52:55]
	v_mfma_f32_16x16x32_bf16 v[56:59], v[144:147], v[132:135], v[56:59]
	v_mfma_f32_16x16x32_bf16 v[60:63], v[148:151], v[116:119], v[60:63]
	v_mfma_f32_16x16x32_bf16 v[64:67], v[148:151], v[120:123], v[64:67]
	v_mfma_f32_16x16x32_bf16 v[72:75], v[148:151], v[124:127], v[72:75]
	v_mfma_f32_16x16x32_bf16 v[76:79], v[148:151], v[132:135], v[76:79]
	s_nop 7
	s_nop 3
	v_bfe_u32 v2, v97, 4, 2
	v_lshlrev_b32_e32 v1, 2, v2
	v_lshl_or_b32 v1, s6, 4, v1
	s_nop 2
	v_and_b32_e32 v68, 63, v97
	v_lshl_add_u32 v3, v68, 4, 0
	v_lshl_add_u32 v0, s5, 14, v3
	ds_write_b128 v0, v[4:7]
	ds_write_b128 v0, v[8:11] offset:1024
	ds_write_b128 v0, v[12:15] offset:2048
	ds_write_b128 v0, v[16:19] offset:3072
	ds_write_b128 v0, v[20:23] offset:4096
	ds_write_b128 v0, v[32:35] offset:5120
	ds_write_b128 v0, v[36:39] offset:6144
	ds_write_b128 v0, v[40:43] offset:7168
	ds_write_b128 v0, v[44:47] offset:8192
	ds_write_b128 v0, v[48:51] offset:9216
	ds_write_b128 v0, v[52:55] offset:10240
	ds_write_b128 v0, v[56:59] offset:11264
	ds_write_b128 v0, v[60:63] offset:12288
	ds_write_b128 v0, v[64:67] offset:13312
	ds_write_b128 v0, v[72:75] offset:14336
	ds_write_b128 v0, v[76:79] offset:15360
	s_lshl_b32 s5, s7, 4
	s_addk_i32 s5, 0x4000
	s_waitcnt vmcnt(0) lgkmcnt(0)
	s_nop 2
	s_nop 2
	s_nop 5
	s_nop 5
	s_nop 5
	s_nop 7
	v_or_b32_e32 v0, s5, v96
	v_or_b32_e32 v6, s3, v1
	v_ashrrev_i32_e32 v1, 31, v0
	v_lshlrev_b64 v[4:5], 12, v[0:1]
	s_ashr_i32 s5, s4, 31
	v_lshl_add_u64 v[4:5], s[10:11], 0, v[4:5]
	v_lshl_add_u64 v[4:5], s[4:5], 1, v[4:5]
	v_lshlrev_b32_e32 v128, 1, v6
	v_lshl_add_u64 v[16:17], v[4:5], 0, v[128:129]
	s_waitcnt lgkmcnt(0)
	s_barrier
	global_load_dwordx2 v[18:19], v[16:17], off
	global_load_dwordx2 v[20:21], v[16:17], off offset:256
	s_lshl_b32 s3, s6, 2
	s_add_i32 s3, s3, s7
	v_lshl_add_u32 v3, s3, 10, v3
	ds_read_b128 v[4:7], v3
	ds_read_b128 v[8:11], v3 offset:8192
	ds_read_b128 v[12:15], v3 offset:16384
	s_waitcnt lgkmcnt(0)
	v_pk_add_f32 v[22:23], v[6:7], 0 op_sel_hi:[1,0]
	v_pk_add_f32 v[24:25], v[4:5], 0 op_sel_hi:[1,0]
	ds_read_b128 v[4:7], v3 offset:24576
	v_pk_add_f32 v[26:27], v[10:11], 0 op_sel_hi:[1,0]
	v_pk_add_f32 v[28:29], v[8:9], 0 op_sel_hi:[1,0]
	v_pk_add_f32 v[22:23], v[22:23], v[14:15]
	v_pk_add_f32 v[24:25], v[24:25], v[12:13]
	ds_read_b128 v[8:11], v3 offset:32768
	ds_read_b128 v[12:15], v3 offset:40960
	s_waitcnt lgkmcnt(0)
	v_pk_add_f32 v[26:27], v[26:27], v[6:7]
	v_pk_add_f32 v[28:29], v[28:29], v[4:5]
	ds_read_b128 v[4:7], v3 offset:49152
	v_pk_add_f32 v[22:23], v[22:23], v[10:11]
	v_pk_add_f32 v[24:25], v[24:25], v[8:9]
	v_pk_add_f32 v[28:29], v[28:29], v[12:13]
	ds_read_b128 v[8:11], v3 offset:57344
	v_add_u32_e32 v12, 0x12000, v3
	v_pk_add_f32 v[26:27], v[26:27], v[14:15]
	s_waitcnt lgkmcnt(0)
	v_pk_add_f32 v[24:25], v[24:25], v[4:5]
	v_add_u32_e32 v4, 0x10000, v3
	ds_read_b128 v[12:15], v12
	v_pk_add_f32 v[22:23], v[22:23], v[6:7]
	ds_read_b128 v[4:7], v4
	v_pk_add_f32 v[8:9], v[28:29], v[8:9]
	v_pk_add_f32 v[10:11], v[26:27], v[10:11]
	s_waitcnt lgkmcnt(0)
	v_pk_add_f32 v[28:29], v[8:9], v[12:13]
	v_add_u32_e32 v8, 0x16000, v3
	v_pk_add_f32 v[26:27], v[10:11], v[14:15]
	ds_read_b128 v[8:11], v8
	v_pk_add_f32 v[24:25], v[24:25], v[4:5]
	v_add_u32_e32 v4, 0x14000, v3
	v_pk_add_f32 v[22:23], v[22:23], v[6:7]
	ds_read_b128 v[4:7], v4
	v_add_u32_e32 v12, 0x18000, v3
	ds_read_b128 v[12:15], v12
	s_waitcnt lgkmcnt(0)
	v_pk_add_f32 v[28:29], v[28:29], v[8:9]
	v_add_u32_e32 v8, 0x1c000, v3
	v_pk_add_f32 v[26:27], v[26:27], v[10:11]
	ds_read_b128 v[8:11], v8
	v_pk_add_f32 v[24:25], v[24:25], v[4:5]
	v_add_u32_e32 v4, 0x1a000, v3
	v_pk_add_f32 v[22:23], v[22:23], v[6:7]
	ds_read_b128 v[4:7], v4
	v_add_u32_e32 v3, 0x1e000, v3
	v_pk_add_f32 v[22:23], v[22:23], v[14:15]
	v_pk_add_f32 v[24:25], v[24:25], v[12:13]
	ds_read_b128 v[12:15], v3
	s_waitcnt lgkmcnt(0)
	v_pk_add_f32 v[4:5], v[28:29], v[4:5]
	v_pk_add_f32 v[8:9], v[24:25], v[8:9]
	v_pk_add_f32 v[6:7], v[26:27], v[6:7]
	v_pk_add_f32 v[10:11], v[22:23], v[10:11]
	v_pk_add_f32 v[4:5], v[4:5], v[12:13]
	v_pk_add_f32 v[6:7], v[6:7], v[14:15]
	s_waitcnt vmcnt(0)
	v_lshlrev_b32_e32 v12, 16, v18
	v_and_b32_e32 v13, 0xffff0000, v18
	v_pk_add_f32 v[8:9], v[8:9], v[12:13]
	v_lshlrev_b32_e32 v12, 16, v20
	v_and_b32_e32 v13, 0xffff0000, v20
	v_lshlrev_b32_e32 v14, 16, v19
	v_and_b32_e32 v15, 0xffff0000, v19
	v_pk_add_f32 v[4:5], v[4:5], v[12:13]
	v_pk_add_f32 v[10:11], v[10:11], v[14:15]
	v_lshlrev_b32_e32 v14, 16, v21
	v_and_b32_e32 v15, 0xffff0000, v21
	v_mul_f32_e32 v3, v4, v4
	v_mul_f32_e32 v12, v5, v5
	v_pk_add_f32 v[6:7], v[6:7], v[14:15]
	v_fmac_f32_e32 v3, v8, v8
	v_fmac_f32_e32 v12, v9, v9
	v_add_f32_e32 v3, v3, v12
	v_mul_f32_e32 v12, v6, v6
	v_fmac_f32_e32 v12, v10, v10
	v_add_f32_e32 v3, v12, v3
	v_mul_f32_e32 v12, v7, v7
	v_fmac_f32_e32 v12, v11, v11
	v_and_b32_e32 v13, 64, v214
	v_add_f32_e32 v3, v12, v3
	v_xor_b32_e32 v12, 16, v214
	v_add_u32_e32 v13, 64, v13
	v_cmp_lt_i32_e32 vcc, v12, v13
	v_cvt_pk_bf16_f32 v8, v8, v9
	v_cvt_pk_bf16_f32 v9, v10, v11
	v_xor_b32_e32 v10, 32, v214
	global_store_dwordx2 v[16:17], v[8:9], off
	v_cndmask_b32_e32 v12, v214, v12, vcc
	v_lshlrev_b32_e32 v12, 2, v12
	ds_bpermute_b32 v12, v12, v3
	v_cmp_lt_i32_e32 vcc, v10, v13
	v_cvt_pk_bf16_f32 v4, v4, v5
	v_cvt_pk_bf16_f32 v5, v6, v7
	global_store_dwordx2 v[16:17], v[4:5], off offset:256
	s_waitcnt lgkmcnt(0)
	v_add_f32_e32 v3, v3, v12
	v_cndmask_b32_e32 v10, v214, v10, vcc
	v_lshlrev_b32_e32 v10, 2, v10
	ds_bpermute_b32 v10, v10, v3
	v_cmp_gt_u32_e32 vcc, 16, v68
	s_waitcnt lgkmcnt(0)
	v_add_f32_e32 v3, v3, v10
	s_and_saveexec_b64 s[4:5], vcc
	s_and_b32 s3, s1, 0xffffffc0
	s_add_i32 s3, s3, 0
	v_lshl_add_u32 v4, v96, 2, s3
	v_add_u32_e32 v4, 0x20100, v4
	ds_write_b32 v4, v3
	s_or_b64 exec, exec, s[4:5]
	v_or_b32_e32 v2, s6, v2
	v_cmp_eq_u32_e32 vcc, 0, v2
	s_waitcnt lgkmcnt(0)
	s_barrier
	s_and_saveexec_b64 s[4:5], vcc
	s_cbranch_execz .LBB0_1210
	s_andn2_b32 s1, s1, 63
	s_add_i32 s1, s1, 0
	s_add_i32 s1, s1, 0x20100
	v_lshl_add_u32 v2, v96, 2, s1
	ds_read_b32 v2, v2 offset:64
	v_lshlrev_b64 v[0:1], 7, v[0:1]
	v_lshl_add_u64 v[0:1], s[8:9], 0, v[0:1]
	s_ashr_i32 s3, s2, 31
	v_lshl_add_u64 v[0:1], s[2:3], 2, v[0:1]
	s_waitcnt lgkmcnt(0)
	v_add_f32_e32 v2, v3, v2
	global_store_dword v[0:1], v2, off

.LBB0_1302:
	s_waitcnt vmcnt(0) lgkmcnt(0)
	v_mov_b32_e32 v96, v210
	s_mov_b32 s0, s73
	s_cmp_gt_i32 s0, 31
	v_readfirstlane_b32 s1, v96
	s_cbranch_scc1 .LBB0_1304
	v_and_b32_e32 v97, 15, v96
	s_ashr_i32 s3, s1, 6
	v_mul_u32_u24_e32 v0, 0x1600, v97
	v_lshlrev_b32_e32 v128, 1, v0
	s_mul_i32 s4, s3, 0x2c0
	s_lshl_b32 s2, s0, 6
	s_lshl_b32 s0, s0, 5
	v_lshl_add_u64 v[0:1], s[14:15], 0, v[128:129]
	v_and_b32_e32 v128, 48, v96
	s_ashr_i32 s5, s4, 31
	s_and_b32 s0, s0, 0x60
	v_lshl_add_u64 v[0:1], v[0:1], 0, v[128:129]
	s_lshl_b64 s[4:5], s[4:5], 1
	s_and_b32 s2, s2, 0xffffff00
	v_lshl_add_u64 v[28:29], v[0:1], 0, s[4:5]
	v_or_b32_e32 v0, s0, v97
	v_or_b32_e32 v2, s2, v0
	v_mov_b64_e32 v[0:1], s[12:13]
	s_movk_i32 s10, 0x2c00
	v_mad_i64_i32 v[0:1], s[10:11], v2, s10, v[0:1]
	v_lshl_add_u64 v[0:1], v[0:1], 0, v[128:129]
	v_lshl_add_u64 v[24:25], v[0:1], 0, s[4:5]
	s_mov_b32 s4, 0xb000000
	s_mov_b32 s4, 0xb02c000
	s_mov_b32 s4, 0xb058000
	s_mov_b64 s[4:5], 0xb000000
	s_mov_b32 s4, 0xb084000
	s_mov_b32 s4, 0x2c000
	s_mov_b32 s4, 0x160000
	s_mov_b32 s4, 0x18c000
	s_ashr_i32 s1, s1, 7
	s_and_b32 s4, s3, 1
	s_mov_b64 s[10:11], -1
	v_add_co_u32_e32 v14, vcc, 0xb000000, v28
	s_nop 1
	v_addc_co_u32_e32 v15, vcc, 0, v29, vcc
	v_add_co_u32_e32 v26, vcc, 0xb02c000, v28
	s_nop 1
	v_addc_co_u32_e32 v27, vcc, 0, v29, vcc
	v_add_co_u32_e32 v30, vcc, 0xb058000, v28
	s_nop 1
	v_addc_co_u32_e32 v31, vcc, 0, v29, vcc
	v_add_co_u32_e32 v70, vcc, 0xb084000, v28
	s_nop 1
	v_addc_co_u32_e32 v71, vcc, 0, v29, vcc
	v_mov_b32_e32 v98, v24
	v_mov_b32_e32 v99, v25
	v_add_co_u32_e32 v130, vcc, 0x2c000, v24
	s_nop 1
	v_addc_co_u32_e32 v131, vcc, 0, v25, vcc
	v_add_co_u32_e32 v152, vcc, 0x160000, v24
	s_nop 1
	v_addc_co_u32_e32 v153, vcc, 0, v25, vcc
	v_add_co_u32_e32 v154, vcc, 0x18c000, v24
	s_nop 1
	v_addc_co_u32_e32 v155, vcc, 0, v25, vcc
	global_load_dwordx4 v[80:83], v[14:15], off
	global_load_dwordx4 v[84:87], v[26:27], off
	global_load_dwordx4 v[88:91], v[30:31], off
	global_load_dwordx4 v[92:95], v[70:71], off
	global_load_dwordx4 v[100:103], v[98:99], off
	global_load_dwordx4 v[104:107], v[130:131], off
	global_load_dwordx4 v[108:111], v[152:153], off
	global_load_dwordx4 v[112:115], v[154:155], off
	global_load_dwordx4 v[116:119], v[14:15], off offset:64
	global_load_dwordx4 v[120:123], v[26:27], off offset:64
	global_load_dwordx4 v[124:127], v[30:31], off offset:64
	global_load_dwordx4 v[132:135], v[70:71], off offset:64
	global_load_dwordx4 v[136:139], v[98:99], off offset:64
	global_load_dwordx4 v[140:143], v[130:131], off offset:64
	global_load_dwordx4 v[144:147], v[152:153], off offset:64
	global_load_dwordx4 v[148:151], v[154:155], off offset:64
	s_waitcnt vmcnt(8)
	v_mfma_f32_16x16x32_bf16 v[0:3], v[100:103], v[80:83], 0
	v_mfma_f32_16x16x32_bf16 v[4:7], v[100:103], v[84:87], 0
	v_mfma_f32_16x16x32_bf16 v[8:11], v[100:103], v[88:91], 0
	v_mfma_f32_16x16x32_bf16 v[16:19], v[100:103], v[92:95], 0
	v_mfma_f32_16x16x32_bf16 v[20:23], v[104:107], v[80:83], 0
	v_mfma_f32_16x16x32_bf16 v[32:35], v[104:107], v[84:87], 0
	v_mfma_f32_16x16x32_bf16 v[36:39], v[104:107], v[88:91], 0
	v_mfma_f32_16x16x32_bf16 v[40:43], v[104:107], v[92:95], 0
	v_mfma_f32_16x16x32_bf16 v[44:47], v[108:111], v[80:83], 0
	v_mfma_f32_16x16x32_bf16 v[48:51], v[108:111], v[84:87], 0
	v_mfma_f32_16x16x32_bf16 v[52:55], v[108:111], v[88:91], 0
	v_mfma_f32_16x16x32_bf16 v[56:59], v[108:111], v[92:95], 0
	v_mfma_f32_16x16x32_bf16 v[60:63], v[112:115], v[80:83], 0
	v_mfma_f32_16x16x32_bf16 v[64:67], v[112:115], v[84:87], 0
	v_mfma_f32_16x16x32_bf16 v[72:75], v[112:115], v[88:91], 0
	v_mfma_f32_16x16x32_bf16 v[76:79], v[112:115], v[92:95], 0
	global_load_dwordx4 v[80:83], v[14:15], off offset:128
	global_load_dwordx4 v[84:87], v[26:27], off offset:128
	global_load_dwordx4 v[88:91], v[30:31], off offset:128
	global_load_dwordx4 v[92:95], v[70:71], off offset:128
	global_load_dwordx4 v[100:103], v[98:99], off offset:128
	global_load_dwordx4 v[104:107], v[130:131], off offset:128
	global_load_dwordx4 v[108:111], v[152:153], off offset:128
	global_load_dwordx4 v[112:115], v[154:155], off offset:128
	s_waitcnt vmcnt(8)
	v_mfma_f32_16x16x32_bf16 v[0:3], v[136:139], v[116:119], v[0:3]
	v_mfma_f32_16x16x32_bf16 v[4:7], v[136:139], v[120:123], v[4:7]
	v_mfma_f32_16x16x32_bf16 v[8:11], v[136:139], v[124:127], v[8:11]
	v_mfma_f32_16x16x32_bf16 v[16:19], v[136:139], v[132:135], v[16:19]
	v_mfma_f32_16x16x32_bf16 v[20:23], v[140:143], v[116:119], v[20:23]
	v_mfma_f32_16x16x32_bf16 v[32:35], v[140:143], v[120:123], v[32:35]
	v_mfma_f32_16x16x32_bf16 v[36:39], v[140:143], v[124:127], v[36:39]
	v_mfma_f32_16x16x32_bf16 v[40:43], v[140:143], v[132:135], v[40:43]
	v_mfma_f32_16x16x32_bf16 v[44:47], v[144:147], v[116:119], v[44:47]
	v_mfma_f32_16x16x32_bf16 v[48:51], v[144:147], v[120:123], v[48:51]
	v_mfma_f32_16x16x32_bf16 v[52:55], v[144:147], v[124:127], v[52:55]
	v_mfma_f32_16x16x32_bf16 v[56:59], v[144:147], v[132:135], v[56:59]
	v_mfma_f32_16x16x32_bf16 v[60:63], v[148:151], v[116:119], v[60:63]
	v_mfma_f32_16x16x32_bf16 v[64:67], v[148:151], v[120:123], v[64:67]
	v_mfma_f32_16x16x32_bf16 v[72:75], v[148:151], v[124:127], v[72:75]
	v_mfma_f32_16x16x32_bf16 v[76:79], v[148:151], v[132:135], v[76:79]
	global_load_dwordx4 v[116:119], v[14:15], off offset:192
	global_load_dwordx4 v[120:123], v[26:27], off offset:192
	global_load_dwordx4 v[124:127], v[30:31], off offset:192
	global_load_dwordx4 v[132:135], v[70:71], off offset:192
	global_load_dwordx4 v[136:139], v[98:99], off offset:192
	global_load_dwordx4 v[140:143], v[130:131], off offset:192
	global_load_dwordx4 v[144:147], v[152:153], off offset:192
	global_load_dwordx4 v[148:151], v[154:155], off offset:192
	s_waitcnt vmcnt(8)
	v_mfma_f32_16x16x32_bf16 v[0:3], v[100:103], v[80:83], v[0:3]
	v_mfma_f32_16x16x32_bf16 v[4:7], v[100:103], v[84:87], v[4:7]
	v_mfma_f32_16x16x32_bf16 v[8:11], v[100:103], v[88:91], v[8:11]
	v_mfma_f32_16x16x32_bf16 v[16:19], v[100:103], v[92:95], v[16:19]
	v_mfma_f32_16x16x32_bf16 v[20:23], v[104:107], v[80:83], v[20:23]
	v_mfma_f32_16x16x32_bf16 v[32:35], v[104:107], v[84:87], v[32:35]
	v_mfma_f32_16x16x32_bf16 v[36:39], v[104:107], v[88:91], v[36:39]
	v_mfma_f32_16x16x32_bf16 v[40:43], v[104:107], v[92:95], v[40:43]
	v_mfma_f32_16x16x32_bf16 v[44:47], v[108:111], v[80:83], v[44:47]
	v_mfma_f32_16x16x32_bf16 v[48:51], v[108:111], v[84:87], v[48:51]
	v_mfma_f32_16x16x32_bf16 v[52:55], v[108:111], v[88:91], v[52:55]
	v_mfma_f32_16x16x32_bf16 v[56:59], v[108:111], v[92:95], v[56:59]
	v_mfma_f32_16x16x32_bf16 v[60:63], v[112:115], v[80:83], v[60:63]
	v_mfma_f32_16x16x32_bf16 v[64:67], v[112:115], v[84:87], v[64:67]
	v_mfma_f32_16x16x32_bf16 v[72:75], v[112:115], v[88:91], v[72:75]
	v_mfma_f32_16x16x32_bf16 v[76:79], v[112:115], v[92:95], v[76:79]
	global_load_dwordx4 v[80:83], v[14:15], off offset:256
	global_load_dwordx4 v[84:87], v[26:27], off offset:256
	global_load_dwordx4 v[88:91], v[30:31], off offset:256
	global_load_dwordx4 v[92:95], v[70:71], off offset:256
	global_load_dwordx4 v[100:103], v[98:99], off offset:256
	global_load_dwordx4 v[104:107], v[130:131], off offset:256
	global_load_dwordx4 v[108:111], v[152:153], off offset:256
	global_load_dwordx4 v[112:115], v[154:155], off offset:256
	s_waitcnt vmcnt(8)
	v_mfma_f32_16x16x32_bf16 v[0:3], v[136:139], v[116:119], v[0:3]
	v_mfma_f32_16x16x32_bf16 v[4:7], v[136:139], v[120:123], v[4:7]
	v_mfma_f32_16x16x32_bf16 v[8:11], v[136:139], v[124:127], v[8:11]
	v_mfma_f32_16x16x32_bf16 v[16:19], v[136:139], v[132:135], v[16:19]
	v_mfma_f32_16x16x32_bf16 v[20:23], v[140:143], v[116:119], v[20:23]
	v_mfma_f32_16x16x32_bf16 v[32:35], v[140:143], v[120:123], v[32:35]
	v_mfma_f32_16x16x32_bf16 v[36:39], v[140:143], v[124:127], v[36:39]
	v_mfma_f32_16x16x32_bf16 v[40:43], v[140:143], v[132:135], v[40:43]
	v_mfma_f32_16x16x32_bf16 v[44:47], v[144:147], v[116:119], v[44:47]
	v_mfma_f32_16x16x32_bf16 v[48:51], v[144:147], v[120:123], v[48:51]
	v_mfma_f32_16x16x32_bf16 v[52:55], v[144:147], v[124:127], v[52:55]
	v_mfma_f32_16x16x32_bf16 v[56:59], v[144:147], v[132:135], v[56:59]
	v_mfma_f32_16x16x32_bf16 v[60:63], v[148:151], v[116:119], v[60:63]
	v_mfma_f32_16x16x32_bf16 v[64:67], v[148:151], v[120:123], v[64:67]
	v_mfma_f32_16x16x32_bf16 v[72:75], v[148:151], v[124:127], v[72:75]
	v_mfma_f32_16x16x32_bf16 v[76:79], v[148:151], v[132:135], v[76:79]
	global_load_dwordx4 v[116:119], v[14:15], off offset:320
	global_load_dwordx4 v[120:123], v[26:27], off offset:320
	global_load_dwordx4 v[124:127], v[30:31], off offset:320
	global_load_dwordx4 v[132:135], v[70:71], off offset:320
	global_load_dwordx4 v[136:139], v[98:99], off offset:320
	global_load_dwordx4 v[140:143], v[130:131], off offset:320
	global_load_dwordx4 v[144:147], v[152:153], off offset:320
	global_load_dwordx4 v[148:151], v[154:155], off offset:320
	s_waitcnt vmcnt(8)
	v_mfma_f32_16x16x32_bf16 v[0:3], v[100:103], v[80:83], v[0:3]
	v_mfma_f32_16x16x32_bf16 v[4:7], v[100:103], v[84:87], v[4:7]
	v_mfma_f32_16x16x32_bf16 v[8:11], v[100:103], v[88:91], v[8:11]
	v_mfma_f32_16x16x32_bf16 v[16:19], v[100:103], v[92:95], v[16:19]
	v_mfma_f32_16x16x32_bf16 v[20:23], v[104:107], v[80:83], v[20:23]
	v_mfma_f32_16x16x32_bf16 v[32:35], v[104:107], v[84:87], v[32:35]
	v_mfma_f32_16x16x32_bf16 v[36:39], v[104:107], v[88:91], v[36:39]
	v_mfma_f32_16x16x32_bf16 v[40:43], v[104:107], v[92:95], v[40:43]
	v_mfma_f32_16x16x32_bf16 v[44:47], v[108:111], v[80:83], v[44:47]
	v_mfma_f32_16x16x32_bf16 v[48:51], v[108:111], v[84:87], v[48:51]
	v_mfma_f32_16x16x32_bf16 v[52:55], v[108:111], v[88:91], v[52:55]
	v_mfma_f32_16x16x32_bf16 v[56:59], v[108:111], v[92:95], v[56:59]
	v_mfma_f32_16x16x32_bf16 v[60:63], v[112:115], v[80:83], v[60:63]
	v_mfma_f32_16x16x32_bf16 v[64:67], v[112:115], v[84:87], v[64:67]
	v_mfma_f32_16x16x32_bf16 v[72:75], v[112:115], v[88:91], v[72:75]
	v_mfma_f32_16x16x32_bf16 v[76:79], v[112:115], v[92:95], v[76:79]
	global_load_dwordx4 v[80:83], v[14:15], off offset:384
	global_load_dwordx4 v[84:87], v[26:27], off offset:384
	global_load_dwordx4 v[88:91], v[30:31], off offset:384
	global_load_dwordx4 v[92:95], v[70:71], off offset:384
	global_load_dwordx4 v[100:103], v[98:99], off offset:384
	global_load_dwordx4 v[104:107], v[130:131], off offset:384
	global_load_dwordx4 v[108:111], v[152:153], off offset:384
	global_load_dwordx4 v[112:115], v[154:155], off offset:384
	s_waitcnt vmcnt(8)
	v_mfma_f32_16x16x32_bf16 v[0:3], v[136:139], v[116:119], v[0:3]
	v_mfma_f32_16x16x32_bf16 v[4:7], v[136:139], v[120:123], v[4:7]
	v_mfma_f32_16x16x32_bf16 v[8:11], v[136:139], v[124:127], v[8:11]
	v_mfma_f32_16x16x32_bf16 v[16:19], v[136:139], v[132:135], v[16:19]
	v_mfma_f32_16x16x32_bf16 v[20:23], v[140:143], v[116:119], v[20:23]
	v_mfma_f32_16x16x32_bf16 v[32:35], v[140:143], v[120:123], v[32:35]
	v_mfma_f32_16x16x32_bf16 v[36:39], v[140:143], v[124:127], v[36:39]
	v_mfma_f32_16x16x32_bf16 v[40:43], v[140:143], v[132:135], v[40:43]
	v_mfma_f32_16x16x32_bf16 v[44:47], v[144:147], v[116:119], v[44:47]
	v_mfma_f32_16x16x32_bf16 v[48:51], v[144:147], v[120:123], v[48:51]
	v_mfma_f32_16x16x32_bf16 v[52:55], v[144:147], v[124:127], v[52:55]
	v_mfma_f32_16x16x32_bf16 v[56:59], v[144:147], v[132:135], v[56:59]
	v_mfma_f32_16x16x32_bf16 v[60:63], v[148:151], v[116:119], v[60:63]
	v_mfma_f32_16x16x32_bf16 v[64:67], v[148:151], v[120:123], v[64:67]
	v_mfma_f32_16x16x32_bf16 v[72:75], v[148:151], v[124:127], v[72:75]
	v_mfma_f32_16x16x32_bf16 v[76:79], v[148:151], v[132:135], v[76:79]
	global_load_dwordx4 v[116:119], v[14:15], off offset:448
	global_load_dwordx4 v[120:123], v[26:27], off offset:448
	global_load_dwordx4 v[124:127], v[30:31], off offset:448
	global_load_dwordx4 v[132:135], v[70:71], off offset:448
	global_load_dwordx4 v[136:139], v[98:99], off offset:448
	global_load_dwordx4 v[140:143], v[130:131], off offset:448
	global_load_dwordx4 v[144:147], v[152:153], off offset:448
	global_load_dwordx4 v[148:151], v[154:155], off offset:448
	s_waitcnt vmcnt(8)
	v_mfma_f32_16x16x32_bf16 v[0:3], v[100:103], v[80:83], v[0:3]
	v_mfma_f32_16x16x32_bf16 v[4:7], v[100:103], v[84:87], v[4:7]
	v_mfma_f32_16x16x32_bf16 v[8:11], v[100:103], v[88:91], v[8:11]
	v_mfma_f32_16x16x32_bf16 v[16:19], v[100:103], v[92:95], v[16:19]
	v_mfma_f32_16x16x32_bf16 v[20:23], v[104:107], v[80:83], v[20:23]
	v_mfma_f32_16x16x32_bf16 v[32:35], v[104:107], v[84:87], v[32:35]
	v_mfma_f32_16x16x32_bf16 v[36:39], v[104:107], v[88:91], v[36:39]
	v_mfma_f32_16x16x32_bf16 v[40:43], v[104:107], v[92:95], v[40:43]
	v_mfma_f32_16x16x32_bf16 v[44:47], v[108:111], v[80:83], v[44:47]
	v_mfma_f32_16x16x32_bf16 v[48:51], v[108:111], v[84:87], v[48:51]
	v_mfma_f32_16x16x32_bf16 v[52:55], v[108:111], v[88:91], v[52:55]
	v_mfma_f32_16x16x32_bf16 v[56:59], v[108:111], v[92:95], v[56:59]
	v_mfma_f32_16x16x32_bf16 v[60:63], v[112:115], v[80:83], v[60:63]
	v_mfma_f32_16x16x32_bf16 v[64:67], v[112:115], v[84:87], v[64:67]
	v_mfma_f32_16x16x32_bf16 v[72:75], v[112:115], v[88:91], v[72:75]
	v_mfma_f32_16x16x32_bf16 v[76:79], v[112:115], v[92:95], v[76:79]
	global_load_dwordx4 v[80:83], v[14:15], off offset:512
	global_load_dwordx4 v[84:87], v[26:27], off offset:512
	global_load_dwordx4 v[88:91], v[30:31], off offset:512
	global_load_dwordx4 v[92:95], v[70:71], off offset:512
	global_load_dwordx4 v[100:103], v[98:99], off offset:512
	global_load_dwordx4 v[104:107], v[130:131], off offset:512
	global_load_dwordx4 v[108:111], v[152:153], off offset:512
	global_load_dwordx4 v[112:115], v[154:155], off offset:512
	s_waitcnt vmcnt(8)
	v_mfma_f32_16x16x32_bf16 v[0:3], v[136:139], v[116:119], v[0:3]
	v_mfma_f32_16x16x32_bf16 v[4:7], v[136:139], v[120:123], v[4:7]
	v_mfma_f32_16x16x32_bf16 v[8:11], v[136:139], v[124:127], v[8:11]
	v_mfma_f32_16x16x32_bf16 v[16:19], v[136:139], v[132:135], v[16:19]
	v_mfma_f32_16x16x32_bf16 v[20:23], v[140:143], v[116:119], v[20:23]
	v_mfma_f32_16x16x32_bf16 v[32:35], v[140:143], v[120:123], v[32:35]
	v_mfma_f32_16x16x32_bf16 v[36:39], v[140:143], v[124:127], v[36:39]
	v_mfma_f32_16x16x32_bf16 v[40:43], v[140:143], v[132:135], v[40:43]
	v_mfma_f32_16x16x32_bf16 v[44:47], v[144:147], v[116:119], v[44:47]
	v_mfma_f32_16x16x32_bf16 v[48:51], v[144:147], v[120:123], v[48:51]
	v_mfma_f32_16x16x32_bf16 v[52:55], v[144:147], v[124:127], v[52:55]
	v_mfma_f32_16x16x32_bf16 v[56:59], v[144:147], v[132:135], v[56:59]
	v_mfma_f32_16x16x32_bf16 v[60:63], v[148:151], v[116:119], v[60:63]
	v_mfma_f32_16x16x32_bf16 v[64:67], v[148:151], v[120:123], v[64:67]
	v_mfma_f32_16x16x32_bf16 v[72:75], v[148:151], v[124:127], v[72:75]
	v_mfma_f32_16x16x32_bf16 v[76:79], v[148:151], v[132:135], v[76:79]
	global_load_dwordx4 v[116:119], v[14:15], off offset:576
	global_load_dwordx4 v[120:123], v[26:27], off offset:576
	global_load_dwordx4 v[124:127], v[30:31], off offset:576
	global_load_dwordx4 v[132:135], v[70:71], off offset:576
	global_load_dwordx4 v[136:139], v[98:99], off offset:576
	global_load_dwordx4 v[140:143], v[130:131], off offset:576
	global_load_dwordx4 v[144:147], v[152:153], off offset:576
	global_load_dwordx4 v[148:151], v[154:155], off offset:576
	s_waitcnt vmcnt(8)
	v_mfma_f32_16x16x32_bf16 v[0:3], v[100:103], v[80:83], v[0:3]
	v_mfma_f32_16x16x32_bf16 v[4:7], v[100:103], v[84:87], v[4:7]
	v_mfma_f32_16x16x32_bf16 v[8:11], v[100:103], v[88:91], v[8:11]
	v_mfma_f32_16x16x32_bf16 v[16:19], v[100:103], v[92:95], v[16:19]
	v_mfma_f32_16x16x32_bf16 v[20:23], v[104:107], v[80:83], v[20:23]
	v_mfma_f32_16x16x32_bf16 v[32:35], v[104:107], v[84:87], v[32:35]
	v_mfma_f32_16x16x32_bf16 v[36:39], v[104:107], v[88:91], v[36:39]
	v_mfma_f32_16x16x32_bf16 v[40:43], v[104:107], v[92:95], v[40:43]
	v_mfma_f32_16x16x32_bf16 v[44:47], v[108:111], v[80:83], v[44:47]
	v_mfma_f32_16x16x32_bf16 v[48:51], v[108:111], v[84:87], v[48:51]
	v_mfma_f32_16x16x32_bf16 v[52:55], v[108:111], v[88:91], v[52:55]
	v_mfma_f32_16x16x32_bf16 v[56:59], v[108:111], v[92:95], v[56:59]
	v_mfma_f32_16x16x32_bf16 v[60:63], v[112:115], v[80:83], v[60:63]
	v_mfma_f32_16x16x32_bf16 v[64:67], v[112:115], v[84:87], v[64:67]
	v_mfma_f32_16x16x32_bf16 v[72:75], v[112:115], v[88:91], v[72:75]
	v_mfma_f32_16x16x32_bf16 v[76:79], v[112:115], v[92:95], v[76:79]
	global_load_dwordx4 v[80:83], v[14:15], off offset:640
	global_load_dwordx4 v[84:87], v[26:27], off offset:640
	global_load_dwordx4 v[88:91], v[30:31], off offset:640
	global_load_dwordx4 v[92:95], v[70:71], off offset:640
	global_load_dwordx4 v[100:103], v[98:99], off offset:640
	global_load_dwordx4 v[104:107], v[130:131], off offset:640
	global_load_dwordx4 v[108:111], v[152:153], off offset:640
	global_load_dwordx4 v[112:115], v[154:155], off offset:640
	s_waitcnt vmcnt(8)
	v_mfma_f32_16x16x32_bf16 v[0:3], v[136:139], v[116:119], v[0:3]
	v_mfma_f32_16x16x32_bf16 v[4:7], v[136:139], v[120:123], v[4:7]
	v_mfma_f32_16x16x32_bf16 v[8:11], v[136:139], v[124:127], v[8:11]
	v_mfma_f32_16x16x32_bf16 v[16:19], v[136:139], v[132:135], v[16:19]
	v_mfma_f32_16x16x32_bf16 v[20:23], v[140:143], v[116:119], v[20:23]
	v_mfma_f32_16x16x32_bf16 v[32:35], v[140:143], v[120:123], v[32:35]
	v_mfma_f32_16x16x32_bf16 v[36:39], v[140:143], v[124:127], v[36:39]
	v_mfma_f32_16x16x32_bf16 v[40:43], v[140:143], v[132:135], v[40:43]
	v_mfma_f32_16x16x32_bf16 v[44:47], v[144:147], v[116:119], v[44:47]
	v_mfma_f32_16x16x32_bf16 v[48:51], v[144:147], v[120:123], v[48:51]
	v_mfma_f32_16x16x32_bf16 v[52:55], v[144:147], v[124:127], v[52:55]
	v_mfma_f32_16x16x32_bf16 v[56:59], v[144:147], v[132:135], v[56:59]
	v_mfma_f32_16x16x32_bf16 v[60:63], v[148:151], v[116:119], v[60:63]
	v_mfma_f32_16x16x32_bf16 v[64:67], v[148:151], v[120:123], v[64:67]
	v_mfma_f32_16x16x32_bf16 v[72:75], v[148:151], v[124:127], v[72:75]
	v_mfma_f32_16x16x32_bf16 v[76:79], v[148:151], v[132:135], v[76:79]
	global_load_dwordx4 v[116:119], v[14:15], off offset:704
	global_load_dwordx4 v[120:123], v[26:27], off offset:704
	global_load_dwordx4 v[124:127], v[30:31], off offset:704
	global_load_dwordx4 v[132:135], v[70:71], off offset:704
	global_load_dwordx4 v[136:139], v[98:99], off offset:704
	global_load_dwordx4 v[140:143], v[130:131], off offset:704
	global_load_dwordx4 v[144:147], v[152:153], off offset:704
	global_load_dwordx4 v[148:151], v[154:155], off offset:704
	s_waitcnt vmcnt(8)
	v_mfma_f32_16x16x32_bf16 v[0:3], v[100:103], v[80:83], v[0:3]
	v_mfma_f32_16x16x32_bf16 v[4:7], v[100:103], v[84:87], v[4:7]
	v_mfma_f32_16x16x32_bf16 v[8:11], v[100:103], v[88:91], v[8:11]
	v_mfma_f32_16x16x32_bf16 v[16:19], v[100:103], v[92:95], v[16:19]
	v_mfma_f32_16x16x32_bf16 v[20:23], v[104:107], v[80:83], v[20:23]
	v_mfma_f32_16x16x32_bf16 v[32:35], v[104:107], v[84:87], v[32:35]
	v_mfma_f32_16x16x32_bf16 v[36:39], v[104:107], v[88:91], v[36:39]
	v_mfma_f32_16x16x32_bf16 v[40:43], v[104:107], v[92:95], v[40:43]
	v_mfma_f32_16x16x32_bf16 v[44:47], v[108:111], v[80:83], v[44:47]
	v_mfma_f32_16x16x32_bf16 v[48:51], v[108:111], v[84:87], v[48:51]
	v_mfma_f32_16x16x32_bf16 v[52:55], v[108:111], v[88:91], v[52:55]
	v_mfma_f32_16x16x32_bf16 v[56:59], v[108:111], v[92:95], v[56:59]
	v_mfma_f32_16x16x32_bf16 v[60:63], v[112:115], v[80:83], v[60:63]
	v_mfma_f32_16x16x32_bf16 v[64:67], v[112:115], v[84:87], v[64:67]
	v_mfma_f32_16x16x32_bf16 v[72:75], v[112:115], v[88:91], v[72:75]
	v_mfma_f32_16x16x32_bf16 v[76:79], v[112:115], v[92:95], v[76:79]
	global_load_dwordx4 v[80:83], v[14:15], off offset:768
	global_load_dwordx4 v[84:87], v[26:27], off offset:768
	global_load_dwordx4 v[88:91], v[30:31], off offset:768
	global_load_dwordx4 v[92:95], v[70:71], off offset:768
	global_load_dwordx4 v[100:103], v[98:99], off offset:768
	global_load_dwordx4 v[104:107], v[130:131], off offset:768
	global_load_dwordx4 v[108:111], v[152:153], off offset:768
	global_load_dwordx4 v[112:115], v[154:155], off offset:768
	s_waitcnt vmcnt(8)
	v_mfma_f32_16x16x32_bf16 v[0:3], v[136:139], v[116:119], v[0:3]
	v_mfma_f32_16x16x32_bf16 v[4:7], v[136:139], v[120:123], v[4:7]
	v_mfma_f32_16x16x32_bf16 v[8:11], v[136:139], v[124:127], v[8:11]
	v_mfma_f32_16x16x32_bf16 v[16:19], v[136:139], v[132:135], v[16:19]
	v_mfma_f32_16x16x32_bf16 v[20:23], v[140:143], v[116:119], v[20:23]
	v_mfma_f32_16x16x32_bf16 v[32:35], v[140:143], v[120:123], v[32:35]
	v_mfma_f32_16x16x32_bf16 v[36:39], v[140:143], v[124:127], v[36:39]
	v_mfma_f32_16x16x32_bf16 v[40:43], v[140:143], v[132:135], v[40:43]
	v_mfma_f32_16x16x32_bf16 v[44:47], v[144:147], v[116:119], v[44:47]
	v_mfma_f32_16x16x32_bf16 v[48:51], v[144:147], v[120:123], v[48:51]
	v_mfma_f32_16x16x32_bf16 v[52:55], v[144:147], v[124:127], v[52:55]
	v_mfma_f32_16x16x32_bf16 v[56:59], v[144:147], v[132:135], v[56:59]
	v_mfma_f32_16x16x32_bf16 v[60:63], v[148:151], v[116:119], v[60:63]
	v_mfma_f32_16x16x32_bf16 v[64:67], v[148:151], v[120:123], v[64:67]
	v_mfma_f32_16x16x32_bf16 v[72:75], v[148:151], v[124:127], v[72:75]
	v_mfma_f32_16x16x32_bf16 v[76:79], v[148:151], v[132:135], v[76:79]
	global_load_dwordx4 v[116:119], v[14:15], off offset:832
	global_load_dwordx4 v[120:123], v[26:27], off offset:832
	global_load_dwordx4 v[124:127], v[30:31], off offset:832
	global_load_dwordx4 v[132:135], v[70:71], off offset:832
	global_load_dwordx4 v[136:139], v[98:99], off offset:832
	global_load_dwordx4 v[140:143], v[130:131], off offset:832
	global_load_dwordx4 v[144:147], v[152:153], off offset:832
	global_load_dwordx4 v[148:151], v[154:155], off offset:832
	s_waitcnt vmcnt(8)
	v_mfma_f32_16x16x32_bf16 v[0:3], v[100:103], v[80:83], v[0:3]
	v_mfma_f32_16x16x32_bf16 v[4:7], v[100:103], v[84:87], v[4:7]
	v_mfma_f32_16x16x32_bf16 v[8:11], v[100:103], v[88:91], v[8:11]
	v_mfma_f32_16x16x32_bf16 v[16:19], v[100:103], v[92:95], v[16:19]
	v_mfma_f32_16x16x32_bf16 v[20:23], v[104:107], v[80:83], v[20:23]
	v_mfma_f32_16x16x32_bf16 v[32:35], v[104:107], v[84:87], v[32:35]
	v_mfma_f32_16x16x32_bf16 v[36:39], v[104:107], v[88:91], v[36:39]
	v_mfma_f32_16x16x32_bf16 v[40:43], v[104:107], v[92:95], v[40:43]
	v_mfma_f32_16x16x32_bf16 v[44:47], v[108:111], v[80:83], v[44:47]
	v_mfma_f32_16x16x32_bf16 v[48:51], v[108:111], v[84:87], v[48:51]
	v_mfma_f32_16x16x32_bf16 v[52:55], v[108:111], v[88:91], v[52:55]
	v_mfma_f32_16x16x32_bf16 v[56:59], v[108:111], v[92:95], v[56:59]
	v_mfma_f32_16x16x32_bf16 v[60:63], v[112:115], v[80:83], v[60:63]
	v_mfma_f32_16x16x32_bf16 v[64:67], v[112:115], v[84:87], v[64:67]
	v_mfma_f32_16x16x32_bf16 v[72:75], v[112:115], v[88:91], v[72:75]
	v_mfma_f32_16x16x32_bf16 v[76:79], v[112:115], v[92:95], v[76:79]
	global_load_dwordx4 v[80:83], v[14:15], off offset:896
	global_load_dwordx4 v[84:87], v[26:27], off offset:896
	global_load_dwordx4 v[88:91], v[30:31], off offset:896
	global_load_dwordx4 v[92:95], v[70:71], off offset:896
	global_load_dwordx4 v[100:103], v[98:99], off offset:896
	global_load_dwordx4 v[104:107], v[130:131], off offset:896
	global_load_dwordx4 v[108:111], v[152:153], off offset:896
	global_load_dwordx4 v[112:115], v[154:155], off offset:896
	s_waitcnt vmcnt(8)
	v_mfma_f32_16x16x32_bf16 v[0:3], v[136:139], v[116:119], v[0:3]
	v_mfma_f32_16x16x32_bf16 v[4:7], v[136:139], v[120:123], v[4:7]
	v_mfma_f32_16x16x32_bf16 v[8:11], v[136:139], v[124:127], v[8:11]
	v_mfma_f32_16x16x32_bf16 v[16:19], v[136:139], v[132:135], v[16:19]
	v_mfma_f32_16x16x32_bf16 v[20:23], v[140:143], v[116:119], v[20:23]
	v_mfma_f32_16x16x32_bf16 v[32:35], v[140:143], v[120:123], v[32:35]
	v_mfma_f32_16x16x32_bf16 v[36:39], v[140:143], v[124:127], v[36:39]
	v_mfma_f32_16x16x32_bf16 v[40:43], v[140:143], v[132:135], v[40:43]
	v_mfma_f32_16x16x32_bf16 v[44:47], v[144:147], v[116:119], v[44:47]
	v_mfma_f32_16x16x32_bf16 v[48:51], v[144:147], v[120:123], v[48:51]
	v_mfma_f32_16x16x32_bf16 v[52:55], v[144:147], v[124:127], v[52:55]
	v_mfma_f32_16x16x32_bf16 v[56:59], v[144:147], v[132:135], v[56:59]
	v_mfma_f32_16x16x32_bf16 v[60:63], v[148:151], v[116:119], v[60:63]
	v_mfma_f32_16x16x32_bf16 v[64:67], v[148:151], v[120:123], v[64:67]
	v_mfma_f32_16x16x32_bf16 v[72:75], v[148:151], v[124:127], v[72:75]
	v_mfma_f32_16x16x32_bf16 v[76:79], v[148:151], v[132:135], v[76:79]
	global_load_dwordx4 v[116:119], v[14:15], off offset:960
	global_load_dwordx4 v[120:123], v[26:27], off offset:960
	global_load_dwordx4 v[124:127], v[30:31], off offset:960
	global_load_dwordx4 v[132:135], v[70:71], off offset:960
	global_load_dwordx4 v[136:139], v[98:99], off offset:960
	global_load_dwordx4 v[140:143], v[130:131], off offset:960
	global_load_dwordx4 v[144:147], v[152:153], off offset:960
	global_load_dwordx4 v[148:151], v[154:155], off offset:960
	s_waitcnt vmcnt(8)
	v_mfma_f32_16x16x32_bf16 v[0:3], v[100:103], v[80:83], v[0:3]
	v_mfma_f32_16x16x32_bf16 v[4:7], v[100:103], v[84:87], v[4:7]
	v_mfma_f32_16x16x32_bf16 v[8:11], v[100:103], v[88:91], v[8:11]
	v_mfma_f32_16x16x32_bf16 v[16:19], v[100:103], v[92:95], v[16:19]
	v_mfma_f32_16x16x32_bf16 v[20:23], v[104:107], v[80:83], v[20:23]
	v_mfma_f32_16x16x32_bf16 v[32:35], v[104:107], v[84:87], v[32:35]
	v_mfma_f32_16x16x32_bf16 v[36:39], v[104:107], v[88:91], v[36:39]
	v_mfma_f32_16x16x32_bf16 v[40:43], v[104:107], v[92:95], v[40:43]
	v_mfma_f32_16x16x32_bf16 v[44:47], v[108:111], v[80:83], v[44:47]
	v_mfma_f32_16x16x32_bf16 v[48:51], v[108:111], v[84:87], v[48:51]
	v_mfma_f32_16x16x32_bf16 v[52:55], v[108:111], v[88:91], v[52:55]
	v_mfma_f32_16x16x32_bf16 v[56:59], v[108:111], v[92:95], v[56:59]
	v_mfma_f32_16x16x32_bf16 v[60:63], v[112:115], v[80:83], v[60:63]
	v_mfma_f32_16x16x32_bf16 v[64:67], v[112:115], v[84:87], v[64:67]
	v_mfma_f32_16x16x32_bf16 v[72:75], v[112:115], v[88:91], v[72:75]
	v_mfma_f32_16x16x32_bf16 v[76:79], v[112:115], v[92:95], v[76:79]
	global_load_dwordx4 v[80:83], v[14:15], off offset:1024
	global_load_dwordx4 v[84:87], v[26:27], off offset:1024
	global_load_dwordx4 v[88:91], v[30:31], off offset:1024
	global_load_dwordx4 v[92:95], v[70:71], off offset:1024
	global_load_dwordx4 v[100:103], v[98:99], off offset:1024
	global_load_dwordx4 v[104:107], v[130:131], off offset:1024
	global_load_dwordx4 v[108:111], v[152:153], off offset:1024
	global_load_dwordx4 v[112:115], v[154:155], off offset:1024
	s_waitcnt vmcnt(8)
	v_mfma_f32_16x16x32_bf16 v[0:3], v[136:139], v[116:119], v[0:3]
	v_mfma_f32_16x16x32_bf16 v[4:7], v[136:139], v[120:123], v[4:7]
	v_mfma_f32_16x16x32_bf16 v[8:11], v[136:139], v[124:127], v[8:11]
	v_mfma_f32_16x16x32_bf16 v[16:19], v[136:139], v[132:135], v[16:19]
	v_mfma_f32_16x16x32_bf16 v[20:23], v[140:143], v[116:119], v[20:23]
	v_mfma_f32_16x16x32_bf16 v[32:35], v[140:143], v[120:123], v[32:35]
	v_mfma_f32_16x16x32_bf16 v[36:39], v[140:143], v[124:127], v[36:39]
	v_mfma_f32_16x16x32_bf16 v[40:43], v[140:143], v[132:135], v[40:43]
	v_mfma_f32_16x16x32_bf16 v[44:47], v[144:147], v[116:119], v[44:47]
	v_mfma_f32_16x16x32_bf16 v[48:51], v[144:147], v[120:123], v[48:51]
	v_mfma_f32_16x16x32_bf16 v[52:55], v[144:147], v[124:127], v[52:55]
	v_mfma_f32_16x16x32_bf16 v[56:59], v[144:147], v[132:135], v[56:59]
	v_mfma_f32_16x16x32_bf16 v[60:63], v[148:151], v[116:119], v[60:63]
	v_mfma_f32_16x16x32_bf16 v[64:67], v[148:151], v[120:123], v[64:67]
	v_mfma_f32_16x16x32_bf16 v[72:75], v[148:151], v[124:127], v[72:75]
	v_mfma_f32_16x16x32_bf16 v[76:79], v[148:151], v[132:135], v[76:79]
	global_load_dwordx4 v[116:119], v[14:15], off offset:1088
	global_load_dwordx4 v[120:123], v[26:27], off offset:1088
	global_load_dwordx4 v[124:127], v[30:31], off offset:1088
	global_load_dwordx4 v[132:135], v[70:71], off offset:1088
	global_load_dwordx4 v[136:139], v[98:99], off offset:1088
	global_load_dwordx4 v[140:143], v[130:131], off offset:1088
	global_load_dwordx4 v[144:147], v[152:153], off offset:1088
	global_load_dwordx4 v[148:151], v[154:155], off offset:1088
	s_waitcnt vmcnt(8)
	v_mfma_f32_16x16x32_bf16 v[0:3], v[100:103], v[80:83], v[0:3]
	v_mfma_f32_16x16x32_bf16 v[4:7], v[100:103], v[84:87], v[4:7]
	v_mfma_f32_16x16x32_bf16 v[8:11], v[100:103], v[88:91], v[8:11]
	v_mfma_f32_16x16x32_bf16 v[16:19], v[100:103], v[92:95], v[16:19]
	v_mfma_f32_16x16x32_bf16 v[20:23], v[104:107], v[80:83], v[20:23]
	v_mfma_f32_16x16x32_bf16 v[32:35], v[104:107], v[84:87], v[32:35]
	v_mfma_f32_16x16x32_bf16 v[36:39], v[104:107], v[88:91], v[36:39]
	v_mfma_f32_16x16x32_bf16 v[40:43], v[104:107], v[92:95], v[40:43]
	v_mfma_f32_16x16x32_bf16 v[44:47], v[108:111], v[80:83], v[44:47]
	v_mfma_f32_16x16x32_bf16 v[48:51], v[108:111], v[84:87], v[48:51]
	v_mfma_f32_16x16x32_bf16 v[52:55], v[108:111], v[88:91], v[52:55]
	v_mfma_f32_16x16x32_bf16 v[56:59], v[108:111], v[92:95], v[56:59]
	v_mfma_f32_16x16x32_bf16 v[60:63], v[112:115], v[80:83], v[60:63]
	v_mfma_f32_16x16x32_bf16 v[64:67], v[112:115], v[84:87], v[64:67]
	v_mfma_f32_16x16x32_bf16 v[72:75], v[112:115], v[88:91], v[72:75]
	v_mfma_f32_16x16x32_bf16 v[76:79], v[112:115], v[92:95], v[76:79]
	global_load_dwordx4 v[80:83], v[14:15], off offset:1152
	global_load_dwordx4 v[84:87], v[26:27], off offset:1152
	global_load_dwordx4 v[88:91], v[30:31], off offset:1152
	global_load_dwordx4 v[92:95], v[70:71], off offset:1152
	global_load_dwordx4 v[100:103], v[98:99], off offset:1152
	global_load_dwordx4 v[104:107], v[130:131], off offset:1152
	global_load_dwordx4 v[108:111], v[152:153], off offset:1152
	global_load_dwordx4 v[112:115], v[154:155], off offset:1152
	s_waitcnt vmcnt(8)
	v_mfma_f32_16x16x32_bf16 v[0:3], v[136:139], v[116:119], v[0:3]
	v_mfma_f32_16x16x32_bf16 v[4:7], v[136:139], v[120:123], v[4:7]
	v_mfma_f32_16x16x32_bf16 v[8:11], v[136:139], v[124:127], v[8:11]
	v_mfma_f32_16x16x32_bf16 v[16:19], v[136:139], v[132:135], v[16:19]
	v_mfma_f32_16x16x32_bf16 v[20:23], v[140:143], v[116:119], v[20:23]
	v_mfma_f32_16x16x32_bf16 v[32:35], v[140:143], v[120:123], v[32:35]
	v_mfma_f32_16x16x32_bf16 v[36:39], v[140:143], v[124:127], v[36:39]
	v_mfma_f32_16x16x32_bf16 v[40:43], v[140:143], v[132:135], v[40:43]
	v_mfma_f32_16x16x32_bf16 v[44:47], v[144:147], v[116:119], v[44:47]
	v_mfma_f32_16x16x32_bf16 v[48:51], v[144:147], v[120:123], v[48:51]
	v_mfma_f32_16x16x32_bf16 v[52:55], v[144:147], v[124:127], v[52:55]
	v_mfma_f32_16x16x32_bf16 v[56:59], v[144:147], v[132:135], v[56:59]
	v_mfma_f32_16x16x32_bf16 v[60:63], v[148:151], v[116:119], v[60:63]
	v_mfma_f32_16x16x32_bf16 v[64:67], v[148:151], v[120:123], v[64:67]
	v_mfma_f32_16x16x32_bf16 v[72:75], v[148:151], v[124:127], v[72:75]
	v_mfma_f32_16x16x32_bf16 v[76:79], v[148:151], v[132:135], v[76:79]
	global_load_dwordx4 v[116:119], v[14:15], off offset:1216
	global_load_dwordx4 v[120:123], v[26:27], off offset:1216
	global_load_dwordx4 v[124:127], v[30:31], off offset:1216
	global_load_dwordx4 v[132:135], v[70:71], off offset:1216
	global_load_dwordx4 v[136:139], v[98:99], off offset:1216
	global_load_dwordx4 v[140:143], v[130:131], off offset:1216
	global_load_dwordx4 v[144:147], v[152:153], off offset:1216
	global_load_dwordx4 v[148:151], v[154:155], off offset:1216
	s_waitcnt vmcnt(8)
	v_mfma_f32_16x16x32_bf16 v[0:3], v[100:103], v[80:83], v[0:3]
	v_mfma_f32_16x16x32_bf16 v[4:7], v[100:103], v[84:87], v[4:7]
	v_mfma_f32_16x16x32_bf16 v[8:11], v[100:103], v[88:91], v[8:11]
	v_mfma_f32_16x16x32_bf16 v[16:19], v[100:103], v[92:95], v[16:19]
	v_mfma_f32_16x16x32_bf16 v[20:23], v[104:107], v[80:83], v[20:23]
	v_mfma_f32_16x16x32_bf16 v[32:35], v[104:107], v[84:87], v[32:35]
	v_mfma_f32_16x16x32_bf16 v[36:39], v[104:107], v[88:91], v[36:39]
	v_mfma_f32_16x16x32_bf16 v[40:43], v[104:107], v[92:95], v[40:43]
	v_mfma_f32_16x16x32_bf16 v[44:47], v[108:111], v[80:83], v[44:47]
	v_mfma_f32_16x16x32_bf16 v[48:51], v[108:111], v[84:87], v[48:51]
	v_mfma_f32_16x16x32_bf16 v[52:55], v[108:111], v[88:91], v[52:55]
	v_mfma_f32_16x16x32_bf16 v[56:59], v[108:111], v[92:95], v[56:59]
	v_mfma_f32_16x16x32_bf16 v[60:63], v[112:115], v[80:83], v[60:63]
	v_mfma_f32_16x16x32_bf16 v[64:67], v[112:115], v[84:87], v[64:67]
	v_mfma_f32_16x16x32_bf16 v[72:75], v[112:115], v[88:91], v[72:75]
	v_mfma_f32_16x16x32_bf16 v[76:79], v[112:115], v[92:95], v[76:79]
	global_load_dwordx4 v[80:83], v[14:15], off offset:1280
	global_load_dwordx4 v[84:87], v[26:27], off offset:1280
	global_load_dwordx4 v[88:91], v[30:31], off offset:1280
	global_load_dwordx4 v[92:95], v[70:71], off offset:1280
	global_load_dwordx4 v[100:103], v[98:99], off offset:1280
	global_load_dwordx4 v[104:107], v[130:131], off offset:1280
	global_load_dwordx4 v[108:111], v[152:153], off offset:1280
	global_load_dwordx4 v[112:115], v[154:155], off offset:1280
	s_waitcnt vmcnt(8)
	v_mfma_f32_16x16x32_bf16 v[0:3], v[136:139], v[116:119], v[0:3]
	v_mfma_f32_16x16x32_bf16 v[4:7], v[136:139], v[120:123], v[4:7]
	v_mfma_f32_16x16x32_bf16 v[8:11], v[136:139], v[124:127], v[8:11]
	v_mfma_f32_16x16x32_bf16 v[16:19], v[136:139], v[132:135], v[16:19]
	v_mfma_f32_16x16x32_bf16 v[20:23], v[140:143], v[116:119], v[20:23]
	v_mfma_f32_16x16x32_bf16 v[32:35], v[140:143], v[120:123], v[32:35]
	v_mfma_f32_16x16x32_bf16 v[36:39], v[140:143], v[124:127], v[36:39]
	v_mfma_f32_16x16x32_bf16 v[40:43], v[140:143], v[132:135], v[40:43]
	v_mfma_f32_16x16x32_bf16 v[44:47], v[144:147], v[116:119], v[44:47]
	v_mfma_f32_16x16x32_bf16 v[48:51], v[144:147], v[120:123], v[48:51]
	v_mfma_f32_16x16x32_bf16 v[52:55], v[144:147], v[124:127], v[52:55]
	v_mfma_f32_16x16x32_bf16 v[56:59], v[144:147], v[132:135], v[56:59]
	v_mfma_f32_16x16x32_bf16 v[60:63], v[148:151], v[116:119], v[60:63]
	v_mfma_f32_16x16x32_bf16 v[64:67], v[148:151], v[120:123], v[64:67]
	v_mfma_f32_16x16x32_bf16 v[72:75], v[148:151], v[124:127], v[72:75]
	v_mfma_f32_16x16x32_bf16 v[76:79], v[148:151], v[132:135], v[76:79]
	global_load_dwordx4 v[116:119], v[14:15], off offset:1344
	global_load_dwordx4 v[120:123], v[26:27], off offset:1344
	global_load_dwordx4 v[124:127], v[30:31], off offset:1344
	global_load_dwordx4 v[132:135], v[70:71], off offset:1344
	global_load_dwordx4 v[136:139], v[98:99], off offset:1344
	global_load_dwordx4 v[140:143], v[130:131], off offset:1344
	global_load_dwordx4 v[144:147], v[152:153], off offset:1344
	global_load_dwordx4 v[148:151], v[154:155], off offset:1344
	s_waitcnt vmcnt(8)
	v_mfma_f32_16x16x32_bf16 v[0:3], v[100:103], v[80:83], v[0:3]
	v_mfma_f32_16x16x32_bf16 v[4:7], v[100:103], v[84:87], v[4:7]
	v_mfma_f32_16x16x32_bf16 v[8:11], v[100:103], v[88:91], v[8:11]
	v_mfma_f32_16x16x32_bf16 v[16:19], v[100:103], v[92:95], v[16:19]
	v_mfma_f32_16x16x32_bf16 v[20:23], v[104:107], v[80:83], v[20:23]
	v_mfma_f32_16x16x32_bf16 v[32:35], v[104:107], v[84:87], v[32:35]
	v_mfma_f32_16x16x32_bf16 v[36:39], v[104:107], v[88:91], v[36:39]
	v_mfma_f32_16x16x32_bf16 v[40:43], v[104:107], v[92:95], v[40:43]
	v_mfma_f32_16x16x32_bf16 v[44:47], v[108:111], v[80:83], v[44:47]
	v_mfma_f32_16x16x32_bf16 v[48:51], v[108:111], v[84:87], v[48:51]
	v_mfma_f32_16x16x32_bf16 v[52:55], v[108:111], v[88:91], v[52:55]
	v_mfma_f32_16x16x32_bf16 v[56:59], v[108:111], v[92:95], v[56:59]
	v_mfma_f32_16x16x32_bf16 v[60:63], v[112:115], v[80:83], v[60:63]
	v_mfma_f32_16x16x32_bf16 v[64:67], v[112:115], v[84:87], v[64:67]
	v_mfma_f32_16x16x32_bf16 v[72:75], v[112:115], v[88:91], v[72:75]
	v_mfma_f32_16x16x32_bf16 v[76:79], v[112:115], v[92:95], v[76:79]
	s_waitcnt vmcnt(0)
	v_mfma_f32_16x16x32_bf16 v[0:3], v[136:139], v[116:119], v[0:3]
	v_mfma_f32_16x16x32_bf16 v[4:7], v[136:139], v[120:123], v[4:7]
	v_mfma_f32_16x16x32_bf16 v[8:11], v[136:139], v[124:127], v[8:11]
	v_mfma_f32_16x16x32_bf16 v[16:19], v[136:139], v[132:135], v[16:19]
	v_mfma_f32_16x16x32_bf16 v[20:23], v[140:143], v[116:119], v[20:23]
	v_mfma_f32_16x16x32_bf16 v[32:35], v[140:143], v[120:123], v[32:35]
	v_mfma_f32_16x16x32_bf16 v[36:39], v[140:143], v[124:127], v[36:39]
	v_mfma_f32_16x16x32_bf16 v[40:43], v[140:143], v[132:135], v[40:43]
	v_mfma_f32_16x16x32_bf16 v[44:47], v[144:147], v[116:119], v[44:47]
	v_mfma_f32_16x16x32_bf16 v[48:51], v[144:147], v[120:123], v[48:51]
	v_mfma_f32_16x16x32_bf16 v[52:55], v[144:147], v[124:127], v[52:55]
	v_mfma_f32_16x16x32_bf16 v[56:59], v[144:147], v[132:135], v[56:59]
	v_mfma_f32_16x16x32_bf16 v[60:63], v[148:151], v[116:119], v[60:63]
	v_mfma_f32_16x16x32_bf16 v[64:67], v[148:151], v[120:123], v[64:67]
	v_mfma_f32_16x16x32_bf16 v[72:75], v[148:151], v[124:127], v[72:75]
	v_mfma_f32_16x16x32_bf16 v[76:79], v[148:151], v[132:135], v[76:79]
	s_nop 7
	s_nop 3
	v_and_b32_e32 v68, 63, v96
	v_lshl_add_u32 v68, v68, 4, 0
	v_lshl_add_u32 v69, s3, 14, v68
	ds_write_b128 v69, v[0:3]
	ds_write_b128 v69, v[4:7] offset:1024
	ds_write_b128 v69, v[8:11] offset:2048
	ds_write_b128 v69, v[16:19] offset:3072
	ds_write_b128 v69, v[20:23] offset:4096
	ds_write_b128 v69, v[32:35] offset:5120
	ds_write_b128 v69, v[36:39] offset:6144
	ds_write_b128 v69, v[40:43] offset:7168
	ds_write_b128 v69, v[44:47] offset:8192
	ds_write_b128 v69, v[48:51] offset:9216
	ds_write_b128 v69, v[52:55] offset:10240
	ds_write_b128 v69, v[56:59] offset:11264
	ds_write_b128 v69, v[60:63] offset:12288
	ds_write_b128 v69, v[64:67] offset:13312
	ds_write_b128 v69, v[72:75] offset:14336
	ds_write_b128 v69, v[76:79] offset:15360
	s_lshl_b32 s3, s1, 4
	s_addk_i32 s3, 0x4000
	s_waitcnt vmcnt(0) lgkmcnt(0)
	s_nop 2
	s_nop 2
	s_nop 5
	s_nop 5
	s_nop 5
	s_nop 2
	v_or_b32_e32 v12, s3, v97
	v_ashrrev_i32_e32 v13, 31, v12
	s_nop 2
	v_lshrrev_b32_e32 v0, 2, v96
	v_and_b32_e32 v0, 12, v0
	v_lshl_or_b32 v0, s4, 4, v0
	v_or_b32_e32 v26, s0, v0
	v_lshlrev_b64 v[0:1], 12, v[12:13]
	s_ashr_i32 s3, s2, 31
	v_lshl_add_u64 v[0:1], s[8:9], 0, v[0:1]
	v_lshl_add_u64 v[0:1], s[2:3], 1, v[0:1]
	v_lshlrev_b32_e32 v128, 1, v26
	v_lshl_add_u64 v[0:1], v[0:1], 0, v[128:129]
	s_waitcnt lgkmcnt(0)
	s_barrier
	global_load_dwordx2 v[14:15], v[0:1], off
	global_load_dwordx2 v[16:17], v[0:1], off offset:256
	s_lshl_b32 s0, s4, 2
	s_add_i32 s0, s0, s1
	v_lshl_add_u32 v13, s0, 10, v68
	ds_read_b128 v[0:3], v13
	ds_read_b128 v[4:7], v13 offset:8192
	ds_read_b128 v[8:11], v13 offset:16384
	v_lshlrev_b32_e32 v128, 2, v26
	s_waitcnt lgkmcnt(0)
	v_pk_add_f32 v[18:19], v[2:3], 0 op_sel_hi:[1,0]
	v_pk_add_f32 v[20:21], v[0:1], 0 op_sel_hi:[1,0]
	ds_read_b128 v[0:3], v13 offset:24576
	v_pk_add_f32 v[18:19], v[18:19], v[10:11]
	v_pk_add_f32 v[20:21], v[20:21], v[8:9]
	ds_read_b128 v[8:11], v13 offset:40960
	v_pk_add_f32 v[22:23], v[6:7], 0 op_sel_hi:[1,0]
	v_pk_add_f32 v[24:25], v[4:5], 0 op_sel_hi:[1,0]
	ds_read_b128 v[4:7], v13 offset:32768
	s_waitcnt lgkmcnt(0)
	v_pk_add_f32 v[22:23], v[22:23], v[2:3]
	v_pk_add_f32 v[24:25], v[24:25], v[0:1]
	ds_read_b128 v[0:3], v13 offset:49152
	v_pk_add_f32 v[24:25], v[24:25], v[8:9]
	v_add_u32_e32 v8, 0x12000, v13
	v_pk_add_f32 v[22:23], v[22:23], v[10:11]
	ds_read_b128 v[8:11], v8
	v_pk_add_f32 v[18:19], v[18:19], v[6:7]
	v_pk_add_f32 v[20:21], v[20:21], v[4:5]
	ds_read_b128 v[4:7], v13 offset:57344
	s_waitcnt lgkmcnt(0)
	v_pk_add_f32 v[20:21], v[20:21], v[0:1]
	v_add_u32_e32 v0, 0x10000, v13
	v_pk_add_f32 v[18:19], v[18:19], v[2:3]
	ds_read_b128 v[0:3], v0
	v_pk_add_f32 v[4:5], v[24:25], v[4:5]
	v_pk_add_f32 v[6:7], v[22:23], v[6:7]
	v_pk_add_f32 v[24:25], v[4:5], v[8:9]
	v_add_u32_e32 v4, 0x16000, v13
	v_pk_add_f32 v[22:23], v[6:7], v[10:11]
	ds_read_b128 v[4:7], v4
	s_waitcnt lgkmcnt(0)
	v_pk_add_f32 v[20:21], v[20:21], v[0:1]
	v_add_u32_e32 v0, 0x14000, v13
	v_pk_add_f32 v[18:19], v[18:19], v[2:3]
	ds_read_b128 v[0:3], v0
	v_add_u32_e32 v8, 0x18000, v13
	ds_read_b128 v[8:11], v8
	v_pk_add_f32 v[24:25], v[24:25], v[4:5]
	v_add_u32_e32 v4, 0x1c000, v13
	v_pk_add_f32 v[22:23], v[22:23], v[6:7]
	ds_read_b128 v[4:7], v4
	s_waitcnt lgkmcnt(0)
	v_pk_add_f32 v[20:21], v[20:21], v[0:1]
	v_add_u32_e32 v0, 0x1a000, v13
	v_pk_add_f32 v[18:19], v[18:19], v[2:3]
	ds_read_b128 v[0:3], v0
	v_pk_add_f32 v[20:21], v[20:21], v[8:9]
	v_add_u32_e32 v8, 0x1e000, v13
	v_pk_add_f32 v[18:19], v[18:19], v[10:11]
	ds_read_b128 v[8:11], v8
	s_waitcnt lgkmcnt(0)
	v_pk_add_f32 v[0:1], v[24:25], v[0:1]
	v_pk_add_f32 v[4:5], v[20:21], v[4:5]
	v_pk_add_f32 v[2:3], v[22:23], v[2:3]
	v_pk_add_f32 v[6:7], v[18:19], v[6:7]
	v_pk_add_f32 v[8:9], v[0:1], v[8:9]
	v_pk_add_f32 v[10:11], v[2:3], v[10:11]
	s_waitcnt vmcnt(0)
	v_lshlrev_b32_e32 v0, 16, v14
	v_and_b32_e32 v1, 0xffff0000, v14
	v_pk_add_f32 v[0:1], v[4:5], v[0:1]
	v_lshlrev_b32_e32 v4, 16, v16
	v_and_b32_e32 v5, 0xffff0000, v16
	v_pk_add_f32 v[4:5], v[8:9], v[4:5]
	v_mul_hi_i32 v8, v12, s97
	v_lshlrev_b32_e32 v2, 16, v15
	v_and_b32_e32 v3, 0xffff0000, v15
	v_lshrrev_b32_e32 v9, 31, v8
	v_ashrrev_i32_e32 v8, 11, v8
	v_pk_add_f32 v[2:3], v[6:7], v[2:3]
	v_lshlrev_b32_e32 v6, 16, v17
	v_and_b32_e32 v7, 0xffff0000, v17
	v_add_u32_e32 v8, v8, v9
	v_pk_add_f32 v[6:7], v[10:11], v[6:7]
	v_mul_i32_i24_e32 v10, 0xffffeff0, v8
	v_ashrrev_i32_e32 v9, 31, v8
	v_add3_u32 v10, v12, v10, -16
	v_ashrrev_i32_e32 v11, 31, v10
	v_lshlrev_b64 v[8:9], 25, v[8:9]
	v_lshl_add_u64 v[8:9], s[6:7], 0, v[8:9]
	v_lshlrev_b64 v[10:11], 13, v[10:11]
	v_lshl_add_u64 v[8:9], v[8:9], 0, v[10:11]
	v_lshl_add_u64 v[8:9], s[2:3], 2, v[8:9]
	v_lshl_add_u64 v[8:9], v[8:9], 0, v[128:129]
	global_store_dwordx4 v[8:9], v[0:3], off
	global_store_dwordx4 v[8:9], v[4:7], off offset:512
	s_waitcnt lgkmcnt(0)
	s_barrier
